# GEMM K-loops: first iteration peeled with C=0 accumulator input, the 127-instruction accumulator zeroing block per unit removed
# speedup vs baseline: 1.0221x; 1.0029x over previous
; #define PG8_STAGE(bufoff, gbase, voff) do { _Pragma("unroll") for (int _i = 0; _i < 2; ++_i) \
;         __builtin_amdgcn_global_load_lds((const unsigned*)((const char*)(gbase) + (voff)[_i]), (PG8_LAS unsigned*)(lds + (bufoff) + ldsw + _i * 8192), 16, 0, 0); } while (0)
; #define PG8_LDA(dst, b, h) do { _Pragma("unroll") for (int m = 0; m < 4; ++m) _Pragma("unroll") for (int k = 0; k < 2; ++k) dst[m][k] = *(const PG8_LAS bf16x8*)(lds + PG8_SA(b, h) + aoff + m * 2048 + k * 1024); } while (0)
; #define PG8_LDB(dst, b, h) do { _Pragma("unroll") for (int n = 0; n < 2; ++n) _Pragma("unroll") for (int k = 0; k < 2; ++k) dst[n][k] = *(const PG8_LAS bf16x8*)(lds + PG8_SB(b, h) + boff + n * 2048 + k * 1024); } while (0)
; #define PG8_WAIT_V(n) asm volatile("s_waitcnt vmcnt(" #n ")" ::: "memory")
; #define PG8_WAIT_L(n) asm volatile("s_waitcnt lgkmcnt(" #n ")" ::: "memory")
; template <class Epi, class Sched, bool ALIGN_EPI = false, bool SP2 = false>
; __device__ __forceinline__ void gemm_phase(PG8_LAS unsigned char* lds, const Gemm g, const Sched& S, const Epi& E, const int tid_in) {
;     ...
;     for (;;) {
;         const bool has_next = S.next(ui + 1, nxt);
;         const char* nA = has_next ? (const char*)g.A + (size_t)nxt.pm * tstep : cA; const char* nB = has_next ? (const char*)g.Bt + (size_t)nxt.pn * tstep : cB;
;         for (int t = 0; t < nt; t += 2) {
;             if constexpr (Epi::KSPLIT > 0) { if (t == Epi::KSPLIT / BK) E.midk(acc, cur, wr, wc, fr, fq); }
;             const bool last = (t == nt - 2);
;             const char* a1 = cA + (size_t)(t + 1) * kstep;
;             const char* a2 = last ? nA : cA + (size_t)(t + 2) * kstep; const char* b2 = last ? nB : cB + (size_t)(t + 2) * kstep;
;             const char* a3 = a2 + kstep; const char* b3 = b2 + kstep;
;             if (last && has_next) S.a_ready(nxt);
;             if constexpr (SP2) {
;             PG8_LDB(B0, 0, 0); PG8_LDB(B1, 0, 1); PG8_SCHED; PG8_LDA(At, 0, 0); PG8_STAGE(PG8_SA(1, 1), a1 + hstep, voffA);
;             PG8_WAIT_V(8); PG8_WAIT_L(0); PG8_BAR; PG8_MMA(0, 0, At, B0); PG8_MMA(0, 1, At, B1); PG8_BAR; PG8_SCHED;
;             PG8_LDA(At, 0, 1); PG8_STAGE(PG8_SB(0, 0), b2, voffB); PG8_STAGE(PG8_SB(0, 1), b2 + hstep, voffB); PG8_STAGE(PG8_SA(0, 0), a2, voffA);
;             PG8_WAIT_V(8); PG8_WAIT_L(0); PG8_BAR; PG8_MMA(1, 0, At, B0); PG8_MMA(1, 1, At, B1); PG8_BAR; PG8_SCHED;
.LBB0_351:
	s_ashr_i32 s27, s26, 31
	s_lshl_b64 s[28:29], s[26:27], 20
	s_add_u32 s28, s1, s28
	s_addc_u32 s29, s5, s29
	s_and_b64 s[30:31], s[36:37], exec
	s_cselect_b32 s27, s29, s35
	s_cselect_b32 s53, s28, s34
	s_ashr_i32 s25, s24, 31
	s_lshl_b64 s[30:31], s[24:25], 20
	s_add_u32 s30, s8, s30
	s_addc_u32 s31, s10, s31
	s_and_b64 s[42:43], s[36:37], exec
	s_cselect_b32 s25, s31, s39
	s_cselect_b32 s54, s30, s38
	s_add_u32 s34, s34, 0x80080
	s_addc_u32 s35, s35, 0
	s_add_u32 s55, s38, 0x100
	v_mov_b32_e32 v0, 0
	s_addc_u32 s56, s39, 0
	s_mov_b32 s57, -2
	s_mov_b32 m0, s49
	s_nop 0
	global_load_lds_dwordx4 v132, s[100:101]
	s_add_u32 s38, s34, 0xfff80080
	s_addc_u32 s39, s35, -1
	s_add_i32 s58, 0, 0x10000
	s_cmp_eq_u32 s57, 28
	s_cselect_b32 s43, s27, s39
	s_cselect_b32 s42, s53, s38
	v_add_u32_e32 v145, s58, v142
	s_cselect_b32 s39, s25, s56
	s_cselect_b32 s38, s54, s55
	s_add_i32 s60, 0, 0x14000
	ds_read_b128 v[146:149], v145
	ds_read_b128 v[150:153], v145 offset:1024
	ds_read_b128 v[154:157], v145 offset:2048
	ds_read_b128 v[158:161], v145 offset:3072
	v_add_u32_e32 v145, s60, v142
	ds_read_b128 v[162:165], v145
	ds_read_b128 v[166:169], v145 offset:1024
	ds_read_b128 v[170:173], v145 offset:2048
	ds_read_b128 v[174:177], v145 offset:3072
	s_add_i32 m0, s44, 0xc000
	ds_read_b128 v[178:181], v144
	ds_read_b128 v[182:185], v144 offset:1024
	ds_read_b128 v[186:189], v144 offset:2048
	ds_read_b128 v[190:193], v144 offset:3072
	ds_read_b128 v[194:197], v144 offset:4096
	ds_read_b128 v[198:201], v144 offset:5120
	ds_read_b128 v[202:205], v144 offset:6144
	ds_read_b128 v[208:211], v144 offset:7168
	global_load_lds_dwordx4 v138, s[34:35]
	s_add_i32 m0, s44, 0xe000
	s_nop 0
	global_load_lds_dwordx4 v140, s[34:35]
	s_waitcnt vmcnt(8)
	s_waitcnt lgkmcnt(0)
	s_barrier
	s_setprio 1
	v_mfma_f32_16x16x32_bf16 v[126:129], v[146:149], v[178:181], 0
	v_mfma_f32_16x16x32_bf16 v[122:125], v[154:157], v[178:181], 0
	v_mfma_f32_16x16x32_bf16 v[114:117], v[146:149], v[186:189], 0
	v_mfma_f32_16x16x32_bf16 v[106:109], v[154:157], v[186:189], 0
	v_mfma_f32_16x16x32_bf16 v[98:101], v[146:149], v[194:197], 0
	v_mfma_f32_16x16x32_bf16 v[90:93], v[154:157], v[194:197], 0
	v_mfma_f32_16x16x32_bf16 v[82:85], v[146:149], v[202:205], 0
	v_mfma_f32_16x16x32_bf16 v[74:77], v[154:157], v[202:205], 0
	v_mfma_f32_16x16x32_bf16 v[126:129], v[150:153], v[182:185], v[126:129]
	v_mfma_f32_16x16x32_bf16 v[122:125], v[158:161], v[182:185], v[122:125]
	v_mfma_f32_16x16x32_bf16 v[114:117], v[150:153], v[190:193], v[114:117]
	v_mfma_f32_16x16x32_bf16 v[106:109], v[158:161], v[190:193], v[106:109]
	v_mfma_f32_16x16x32_bf16 v[98:101], v[150:153], v[198:201], v[98:101]
	v_mfma_f32_16x16x32_bf16 v[90:93], v[158:161], v[198:201], v[90:93]
	v_mfma_f32_16x16x32_bf16 v[82:85], v[150:153], v[208:211], v[82:85]
	v_mfma_f32_16x16x32_bf16 v[74:77], v[158:161], v[208:211], v[74:77]
	s_setprio 0
	s_setprio 1
	v_mfma_f32_16x16x32_bf16 v[118:121], v[162:165], v[178:181], 0
	v_mfma_f32_16x16x32_bf16 v[110:113], v[170:173], v[178:181], 0
	v_mfma_f32_16x16x32_bf16 v[102:105], v[162:165], v[186:189], 0
	v_mfma_f32_16x16x32_bf16 v[94:97], v[170:173], v[186:189], 0
	v_mfma_f32_16x16x32_bf16 v[86:89], v[162:165], v[194:197], 0
	v_mfma_f32_16x16x32_bf16 v[78:81], v[170:173], v[194:197], 0
	v_mfma_f32_16x16x32_bf16 v[70:73], v[162:165], v[202:205], 0
	v_mfma_f32_16x16x32_bf16 v[66:69], v[170:173], v[202:205], 0
	v_mfma_f32_16x16x32_bf16 v[118:121], v[166:169], v[182:185], v[118:121]
	v_mfma_f32_16x16x32_bf16 v[110:113], v[174:177], v[182:185], v[110:113]
	v_mfma_f32_16x16x32_bf16 v[102:105], v[166:169], v[190:193], v[102:105]
	v_mfma_f32_16x16x32_bf16 v[94:97], v[174:177], v[190:193], v[94:97]
	v_mfma_f32_16x16x32_bf16 v[86:89], v[166:169], v[198:201], v[86:89]
	v_mfma_f32_16x16x32_bf16 v[78:81], v[174:177], v[198:201], v[78:81]
	v_mfma_f32_16x16x32_bf16 v[70:73], v[166:169], v[208:211], v[70:73]
	v_mfma_f32_16x16x32_bf16 v[66:69], v[174:177], v[208:211], v[66:69]
	s_setprio 0
	s_barrier
	s_add_i32 s58, s58, s19
	s_add_u32 s98, s38, 0x80
	s_addc_u32 s99, s39, 0
	s_mov_b32 m0, s58
	ds_read_b128 v[178:181], v144 offset:16384
	ds_read_b128 v[182:185], v144 offset:17408
	ds_read_b128 v[186:189], v144 offset:18432
	ds_read_b128 v[190:193], v144 offset:19456
	ds_read_b128 v[194:197], v144 offset:20480
	ds_read_b128 v[198:201], v144 offset:21504
	ds_read_b128 v[202:205], v144 offset:22528
	ds_read_b128 v[208:211], v144 offset:23552
	global_load_lds_dwordx4 v134, s[38:39]
	s_add_i32 m0, s58, 0x2000
	s_add_u32 s58, s38, 0x80000
	s_addc_u32 s59, s39, 0
	s_add_i32 s60, s60, s19
	global_load_lds_dwordx4 v130, s[38:39]
	s_mov_b32 m0, s60
	s_add_u32 s100, s42, 0x80
	s_addc_u32 s101, s43, 0
	global_load_lds_dwordx4 v134, s[58:59]
	s_add_i32 m0, s60, 0x2000
	s_nop 0
	global_load_lds_dwordx4 v130, s[58:59]
	s_mov_b32 m0, s44
	s_nop 0
	global_load_lds_dwordx4 v136, s[42:43]
	s_waitcnt vmcnt(7)
	s_waitcnt lgkmcnt(0)
	s_barrier
; #define PG8_STAGE(bufoff, gbase, voff) do { _Pragma("unroll") for (int _i = 0; _i < 2; ++_i) \
;         __builtin_amdgcn_global_load_lds((const unsigned*)((const char*)(gbase) + (voff)[_i]), (PG8_LAS unsigned*)(lds + (bufoff) + ldsw + _i * 8192), 16, 0, 0); } while (0)
; #define PG8_LDA(dst, b, h) do { _Pragma("unroll") for (int m = 0; m < 4; ++m) _Pragma("unroll") for (int k = 0; k < 2; ++k) dst[m][k] = *(const PG8_LAS bf16x8*)(lds + PG8_SA(b, h) + aoff + m * 2048 + k * 1024); } while (0)
; #define PG8_LDB(dst, b, h) do { _Pragma("unroll") for (int n = 0; n < 2; ++n) _Pragma("unroll") for (int k = 0; k < 2; ++k) dst[n][k] = *(const PG8_LAS bf16x8*)(lds + PG8_SB(b, h) + boff + n * 2048 + k * 1024); } while (0)
; #define PG8_MMA(ai, bj, At, Bt) do { __builtin_amdgcn_s_setprio(1); _Pragma("unroll") for (int m = 0; m < 4; ++m) _Pragma("unroll") for (int n = 0; n < 2; ++n) _Pragma("unroll") for (int k = 0; k < 2; ++k) \
;         acc[ai][bj][m][n] = __builtin_amdgcn_mfma_f32_16x16x32_bf16(Bt[n][k], At[m][k], acc[ai][bj][m][n], 0, 0, 0); __builtin_amdgcn_s_setprio(0); } while (0)
; #define PG8_WAIT_V(n) asm volatile("s_waitcnt vmcnt(" #n ")" ::: "memory")
; #define PG8_WAIT_L(n) asm volatile("s_waitcnt lgkmcnt(" #n ")" ::: "memory")
; #define PG8_BAR __builtin_amdgcn_s_barrier()
; #define PG8_SCHED __builtin_amdgcn_sched_barrier(0)
; template <class Epi, class Sched, bool ALIGN_EPI = false, bool SP2 = false>
; __device__ __forceinline__ void gemm_phase(PG8_LAS unsigned char* lds, const Gemm g, const Sched& S, const Epi& E, const int tid_in) {
;     ...
;             PG8_WAIT_V(8); PG8_WAIT_L(0); PG8_BAR; PG8_MMA(0, 0, At, B0); PG8_MMA(0, 1, At, B1); PG8_BAR; PG8_SCHED;
;             PG8_LDA(At, 0, 1); PG8_STAGE(PG8_SB(0, 0), b2, voffB); PG8_STAGE(PG8_SB(0, 1), b2 + hstep, voffB); PG8_STAGE(PG8_SA(0, 0), a2, voffA);
;             PG8_WAIT_V(8); PG8_WAIT_L(0); PG8_BAR; PG8_MMA(1, 0, At, B0); PG8_MMA(1, 1, At, B1); PG8_BAR; PG8_SCHED;
;             PG8_LDB(B0, 1, 0); PG8_LDB(B1, 1, 1); PG8_SCHED; PG8_LDA(At, 1, 0); PG8_STAGE(PG8_SA(0, 1), a2 + hstep, voffA);
;             PG8_WAIT_V(8); PG8_WAIT_L(0); PG8_BAR; PG8_MMA(0, 0, At, B0); PG8_MMA(0, 1, At, B1); PG8_BAR; PG8_SCHED;
	s_setprio 1
	v_mfma_f32_16x16x32_bf16 v[62:65], v[146:149], v[178:181], 0
	v_mfma_f32_16x16x32_bf16 v[58:61], v[154:157], v[178:181], 0
	v_mfma_f32_16x16x32_bf16 v[50:53], v[146:149], v[186:189], 0
	v_mfma_f32_16x16x32_bf16 v[42:45], v[154:157], v[186:189], 0
	v_mfma_f32_16x16x32_bf16 v[34:37], v[146:149], v[194:197], 0
	v_mfma_f32_16x16x32_bf16 v[26:29], v[154:157], v[194:197], 0
	v_mfma_f32_16x16x32_bf16 v[16:19], v[146:149], v[202:205], 0
	v_mfma_f32_16x16x32_bf16 v[8:11], v[154:157], v[202:205], 0
	v_mfma_f32_16x16x32_bf16 v[62:65], v[150:153], v[182:185], v[62:65]
	v_mfma_f32_16x16x32_bf16 v[58:61], v[158:161], v[182:185], v[58:61]
	v_mfma_f32_16x16x32_bf16 v[50:53], v[150:153], v[190:193], v[50:53]
	v_mfma_f32_16x16x32_bf16 v[42:45], v[158:161], v[190:193], v[42:45]
	v_mfma_f32_16x16x32_bf16 v[34:37], v[150:153], v[198:201], v[34:37]
	v_mfma_f32_16x16x32_bf16 v[26:29], v[158:161], v[198:201], v[26:29]
	v_mfma_f32_16x16x32_bf16 v[16:19], v[150:153], v[208:211], v[16:19]
	v_mfma_f32_16x16x32_bf16 v[8:11], v[158:161], v[208:211], v[8:11]
	s_setprio 0
	s_setprio 1
	v_mfma_f32_16x16x32_bf16 v[54:57], v[162:165], v[178:181], 0
	v_mfma_f32_16x16x32_bf16 v[46:49], v[170:173], v[178:181], 0
	v_mfma_f32_16x16x32_bf16 v[38:41], v[162:165], v[186:189], 0
	v_mfma_f32_16x16x32_bf16 v[30:33], v[170:173], v[186:189], 0
	v_mfma_f32_16x16x32_bf16 v[22:25], v[162:165], v[194:197], 0
	v_mfma_f32_16x16x32_bf16 v[12:15], v[170:173], v[194:197], 0
	v_mfma_f32_16x16x32_bf16 v[4:7], v[162:165], v[202:205], 0
	v_mfma_f32_16x16x32_bf16 v[0:3], v[170:173], v[202:205], 0
	v_mfma_f32_16x16x32_bf16 v[54:57], v[166:169], v[182:185], v[54:57]
	v_mfma_f32_16x16x32_bf16 v[46:49], v[174:177], v[182:185], v[46:49]
	v_mfma_f32_16x16x32_bf16 v[38:41], v[166:169], v[190:193], v[38:41]
	v_mfma_f32_16x16x32_bf16 v[30:33], v[174:177], v[190:193], v[30:33]
	v_mfma_f32_16x16x32_bf16 v[22:25], v[166:169], v[198:201], v[22:25]
	v_mfma_f32_16x16x32_bf16 v[12:15], v[174:177], v[198:201], v[12:15]
	v_mfma_f32_16x16x32_bf16 v[4:7], v[166:169], v[208:211], v[4:7]
	v_mfma_f32_16x16x32_bf16 v[0:3], v[174:177], v[208:211], v[0:3]
	s_setprio 0
	s_barrier
	s_add_i32 s58, 0, 0x18000
	v_add_u32_e32 v145, s58, v142
	s_add_i32 s59, 0, 0x1c000
	ds_read_b128 v[146:149], v145
	ds_read_b128 v[150:153], v145 offset:1024
	ds_read_b128 v[154:157], v145 offset:2048
	ds_read_b128 v[158:161], v145 offset:3072
	v_add_u32_e32 v145, s59, v142
	ds_read_b128 v[162:165], v145
	ds_read_b128 v[166:169], v145 offset:1024
	ds_read_b128 v[170:173], v145 offset:2048
	ds_read_b128 v[174:177], v145 offset:3072
	s_mov_b32 m0, s45
	s_nop 0
	global_load_lds_dwordx4 v132, s[42:43]
	s_add_u32 s42, s42, 0x80000
	s_addc_u32 s43, s43, 0
	s_mov_b32 m0, s46
	ds_read_b128 v[178:181], v144 offset:32768
	ds_read_b128 v[182:185], v144 offset:33792
	ds_read_b128 v[186:189], v144 offset:34816
	ds_read_b128 v[190:193], v144 offset:35840
	ds_read_b128 v[194:197], v144 offset:36864
	ds_read_b128 v[198:201], v144 offset:37888
	ds_read_b128 v[202:205], v144 offset:38912
	ds_read_b128 v[208:211], v144 offset:39936
	global_load_lds_dwordx4 v136, s[42:43]
	s_mov_b32 m0, s47
	s_nop 0
	global_load_lds_dwordx4 v132, s[42:43]
	s_waitcnt vmcnt(8)
	s_waitcnt lgkmcnt(0)
	s_barrier
	s_setprio 1
	v_mfma_f32_16x16x32_bf16 v[126:129], v[146:149], v[178:181], v[126:129]
	v_mfma_f32_16x16x32_bf16 v[122:125], v[154:157], v[178:181], v[122:125]
	v_mfma_f32_16x16x32_bf16 v[114:117], v[146:149], v[186:189], v[114:117]
	v_mfma_f32_16x16x32_bf16 v[106:109], v[154:157], v[186:189], v[106:109]
	v_mfma_f32_16x16x32_bf16 v[98:101], v[146:149], v[194:197], v[98:101]
	v_mfma_f32_16x16x32_bf16 v[90:93], v[154:157], v[194:197], v[90:93]
	v_mfma_f32_16x16x32_bf16 v[82:85], v[146:149], v[202:205], v[82:85]
	v_mfma_f32_16x16x32_bf16 v[74:77], v[154:157], v[202:205], v[74:77]
	v_mfma_f32_16x16x32_bf16 v[126:129], v[150:153], v[182:185], v[126:129]
	v_mfma_f32_16x16x32_bf16 v[122:125], v[158:161], v[182:185], v[122:125]
	v_mfma_f32_16x16x32_bf16 v[114:117], v[150:153], v[190:193], v[114:117]
	v_mfma_f32_16x16x32_bf16 v[106:109], v[158:161], v[190:193], v[106:109]
	v_mfma_f32_16x16x32_bf16 v[98:101], v[150:153], v[198:201], v[98:101]
	v_mfma_f32_16x16x32_bf16 v[90:93], v[158:161], v[198:201], v[90:93]
	v_mfma_f32_16x16x32_bf16 v[82:85], v[150:153], v[208:211], v[82:85]
	v_mfma_f32_16x16x32_bf16 v[74:77], v[158:161], v[208:211], v[74:77]
	s_setprio 0
	s_setprio 1
	v_mfma_f32_16x16x32_bf16 v[118:121], v[162:165], v[178:181], v[118:121]
	v_mfma_f32_16x16x32_bf16 v[110:113], v[170:173], v[178:181], v[110:113]
	v_mfma_f32_16x16x32_bf16 v[102:105], v[162:165], v[186:189], v[102:105]
	v_mfma_f32_16x16x32_bf16 v[94:97], v[170:173], v[186:189], v[94:97]
	v_mfma_f32_16x16x32_bf16 v[86:89], v[162:165], v[194:197], v[86:89]
	v_mfma_f32_16x16x32_bf16 v[78:81], v[170:173], v[194:197], v[78:81]
	v_mfma_f32_16x16x32_bf16 v[70:73], v[162:165], v[202:205], v[70:73]
	v_mfma_f32_16x16x32_bf16 v[66:69], v[170:173], v[202:205], v[66:69]
	v_mfma_f32_16x16x32_bf16 v[118:121], v[166:169], v[182:185], v[118:121]
	v_mfma_f32_16x16x32_bf16 v[110:113], v[174:177], v[182:185], v[110:113]
	v_mfma_f32_16x16x32_bf16 v[102:105], v[166:169], v[190:193], v[102:105]
	v_mfma_f32_16x16x32_bf16 v[94:97], v[174:177], v[190:193], v[94:97]
	v_mfma_f32_16x16x32_bf16 v[86:89], v[166:169], v[198:201], v[86:89]
	v_mfma_f32_16x16x32_bf16 v[78:81], v[174:177], v[198:201], v[78:81]
	v_mfma_f32_16x16x32_bf16 v[70:73], v[166:169], v[208:211], v[70:73]
	v_mfma_f32_16x16x32_bf16 v[66:69], v[174:177], v[208:211], v[66:69]
	s_setprio 0
	s_barrier
; #define PG8_STAGE(bufoff, gbase, voff) do { _Pragma("unroll") for (int _i = 0; _i < 2; ++_i) \
;         __builtin_amdgcn_global_load_lds((const unsigned*)((const char*)(gbase) + (voff)[_i]), (PG8_LAS unsigned*)(lds + (bufoff) + ldsw + _i * 8192), 16, 0, 0); } while (0)
; #define PG8_LDA(dst, b, h) do { _Pragma("unroll") for (int m = 0; m < 4; ++m) _Pragma("unroll") for (int k = 0; k < 2; ++k) dst[m][k] = *(const PG8_LAS bf16x8*)(lds + PG8_SA(b, h) + aoff + m * 2048 + k * 1024); } while (0)
; #define PG8_LDB(dst, b, h) do { _Pragma("unroll") for (int n = 0; n < 2; ++n) _Pragma("unroll") for (int k = 0; k < 2; ++k) dst[n][k] = *(const PG8_LAS bf16x8*)(lds + PG8_SB(b, h) + boff + n * 2048 + k * 1024); } while (0)
; #define PG8_MMA(ai, bj, At, Bt) do { __builtin_amdgcn_s_setprio(1); _Pragma("unroll") for (int m = 0; m < 4; ++m) _Pragma("unroll") for (int n = 0; n < 2; ++n) _Pragma("unroll") for (int k = 0; k < 2; ++k) \
;         acc[ai][bj][m][n] = __builtin_amdgcn_mfma_f32_16x16x32_bf16(Bt[n][k], At[m][k], acc[ai][bj][m][n], 0, 0, 0); __builtin_amdgcn_s_setprio(0); } while (0)
; #define PG8_WAIT_V(n) asm volatile("s_waitcnt vmcnt(" #n ")" ::: "memory")
; #define PG8_WAIT_L(n) asm volatile("s_waitcnt lgkmcnt(" #n ")" ::: "memory")
; #define PG8_BAR __builtin_amdgcn_s_barrier()
; #define PG8_SCHED __builtin_amdgcn_sched_barrier(0)
; template <class Epi, class Sched, bool ALIGN_EPI = false, bool SP2 = false>
; __device__ __forceinline__ void gemm_phase(PG8_LAS unsigned char* lds, const Gemm g, const Sched& S, const Epi& E, const int tid_in) {
;     ...
;         for (int t = 0; t < nt; t += 2) {
;     ...
;             PG8_LDB(B0, 1, 0); PG8_LDB(B1, 1, 1); PG8_SCHED; PG8_LDA(At, 1, 0); PG8_STAGE(PG8_SA(0, 1), a2 + hstep, voffA);
;             PG8_WAIT_V(8); PG8_WAIT_L(0); PG8_BAR; PG8_MMA(0, 0, At, B0); PG8_MMA(0, 1, At, B1); PG8_BAR; PG8_SCHED;
;             PG8_LDA(At, 1, 1); PG8_STAGE(PG8_SB(1, 0), b3, voffB); PG8_STAGE(PG8_SB(1, 1), b3 + hstep, voffB); PG8_STAGE(PG8_SA(1, 0), a3, voffA);
;             PG8_WAIT_V(8); PG8_WAIT_L(0); PG8_BAR; PG8_MMA(1, 0, At, B0); PG8_MMA(1, 1, At, B1); PG8_BAR; PG8_SCHED;
	s_add_i32 s42, s58, s19
	s_mov_b32 m0, s42
	ds_read_b128 v[178:181], v144 offset:49152
	ds_read_b128 v[182:185], v144 offset:50176
	ds_read_b128 v[186:189], v144 offset:51200
	ds_read_b128 v[190:193], v144 offset:52224
	ds_read_b128 v[194:197], v144 offset:53248
	ds_read_b128 v[198:201], v144 offset:54272
	ds_read_b128 v[202:205], v144 offset:55296
	ds_read_b128 v[208:211], v144 offset:56320
	global_load_lds_dwordx4 v134, s[98:99]
	s_add_i32 m0, s42, 0x2000
	s_add_u32 s38, s38, 0x80080
	s_addc_u32 s39, s39, 0
	s_add_i32 s42, s59, s19
	global_load_lds_dwordx4 v130, s[98:99]
	s_mov_b32 m0, s42
	s_nop 0
	global_load_lds_dwordx4 v134, s[38:39]
	s_add_i32 m0, s42, 0x2000
	s_nop 0
	global_load_lds_dwordx4 v130, s[38:39]
	s_mov_b32 m0, s48
	s_nop 0
	global_load_lds_dwordx4 v136, s[100:101]
	s_waitcnt vmcnt(7)
	s_waitcnt lgkmcnt(0)
	s_barrier
	s_setprio 1
	v_mfma_f32_16x16x32_bf16 v[62:65], v[146:149], v[178:181], v[62:65]
	v_mfma_f32_16x16x32_bf16 v[58:61], v[154:157], v[178:181], v[58:61]
	v_mfma_f32_16x16x32_bf16 v[50:53], v[146:149], v[186:189], v[50:53]
	v_mfma_f32_16x16x32_bf16 v[42:45], v[154:157], v[186:189], v[42:45]
	v_mfma_f32_16x16x32_bf16 v[34:37], v[146:149], v[194:197], v[34:37]
	v_mfma_f32_16x16x32_bf16 v[26:29], v[154:157], v[194:197], v[26:29]
	v_mfma_f32_16x16x32_bf16 v[16:19], v[146:149], v[202:205], v[16:19]
	v_mfma_f32_16x16x32_bf16 v[8:11], v[154:157], v[202:205], v[8:11]
	v_mfma_f32_16x16x32_bf16 v[62:65], v[150:153], v[182:185], v[62:65]
	v_mfma_f32_16x16x32_bf16 v[58:61], v[158:161], v[182:185], v[58:61]
	v_mfma_f32_16x16x32_bf16 v[50:53], v[150:153], v[190:193], v[50:53]
	v_mfma_f32_16x16x32_bf16 v[42:45], v[158:161], v[190:193], v[42:45]
	v_mfma_f32_16x16x32_bf16 v[34:37], v[150:153], v[198:201], v[34:37]
	v_mfma_f32_16x16x32_bf16 v[26:29], v[158:161], v[198:201], v[26:29]
	v_mfma_f32_16x16x32_bf16 v[16:19], v[150:153], v[208:211], v[16:19]
	v_mfma_f32_16x16x32_bf16 v[8:11], v[158:161], v[208:211], v[8:11]
	s_setprio 0
	s_setprio 1
	v_mfma_f32_16x16x32_bf16 v[54:57], v[162:165], v[178:181], v[54:57]
	v_mfma_f32_16x16x32_bf16 v[46:49], v[170:173], v[178:181], v[46:49]
	v_mfma_f32_16x16x32_bf16 v[38:41], v[162:165], v[186:189], v[38:41]
	v_mfma_f32_16x16x32_bf16 v[30:33], v[170:173], v[186:189], v[30:33]
	v_mfma_f32_16x16x32_bf16 v[22:25], v[162:165], v[194:197], v[22:25]
	v_mfma_f32_16x16x32_bf16 v[12:15], v[170:173], v[194:197], v[12:15]
	v_mfma_f32_16x16x32_bf16 v[4:7], v[162:165], v[202:205], v[4:7]
	v_mfma_f32_16x16x32_bf16 v[0:3], v[170:173], v[202:205], v[0:3]
	v_mfma_f32_16x16x32_bf16 v[54:57], v[166:169], v[182:185], v[54:57]
	v_mfma_f32_16x16x32_bf16 v[46:49], v[174:177], v[182:185], v[46:49]
	v_mfma_f32_16x16x32_bf16 v[38:41], v[166:169], v[190:193], v[38:41]
	v_mfma_f32_16x16x32_bf16 v[30:33], v[174:177], v[190:193], v[30:33]
	v_mfma_f32_16x16x32_bf16 v[22:25], v[166:169], v[198:201], v[22:25]
	v_mfma_f32_16x16x32_bf16 v[12:15], v[174:177], v[198:201], v[12:15]
	v_mfma_f32_16x16x32_bf16 v[4:7], v[166:169], v[208:211], v[4:7]
	v_mfma_f32_16x16x32_bf16 v[0:3], v[174:177], v[208:211], v[0:3]
	s_setprio 0
	s_barrier
	s_add_i32 s57, s57, 2
	s_add_u32 s34, s34, 0x100
	s_addc_u32 s35, s35, 0
	s_add_u32 s55, s55, 0x100
	s_addc_u32 s56, s56, 0
	s_cmp_gt_u32 s57, 29

; #define PG8_STAGE(bufoff, gbase, voff) do { _Pragma("unroll") for (int _i = 0; _i < 2; ++_i) \
;         __builtin_amdgcn_global_load_lds((const unsigned*)((const char*)(gbase) + (voff)[_i]), (PG8_LAS unsigned*)(lds + (bufoff) + ldsw + _i * 8192), 16, 0, 0); } while (0)
; #define PG8_LDA(dst, b, h) do { _Pragma("unroll") for (int m = 0; m < 4; ++m) _Pragma("unroll") for (int k = 0; k < 2; ++k) dst[m][k] = *(const PG8_LAS bf16x8*)(lds + PG8_SA(b, h) + aoff + m * 2048 + k * 1024); } while (0)
; #define PG8_LDB(dst, b, h) do { _Pragma("unroll") for (int n = 0; n < 2; ++n) _Pragma("unroll") for (int k = 0; k < 2; ++k) dst[n][k] = *(const PG8_LAS bf16x8*)(lds + PG8_SB(b, h) + boff + n * 2048 + k * 1024); } while (0)
; #define PG8_WAIT_V(n) asm volatile("s_waitcnt vmcnt(" #n ")" ::: "memory")
; #define PG8_WAIT_L(n) asm volatile("s_waitcnt lgkmcnt(" #n ")" ::: "memory")
; template <class Epi, class Sched, bool ALIGN_EPI = false, bool SP2 = false>
; __device__ __forceinline__ void gemm_phase(PG8_LAS unsigned char* lds, const Gemm g, const Sched& S, const Epi& E, const int tid_in) {
;     ...
;     for (;;) {
;         const bool has_next = S.next(ui + 1, nxt);
;         const char* nA = has_next ? (const char*)g.A + (size_t)nxt.pm * tstep : cA; const char* nB = has_next ? (const char*)g.Bt + (size_t)nxt.pn * tstep : cB;
;         for (int t = 0; t < nt; t += 2) {
;             if constexpr (Epi::KSPLIT > 0) { if (t == Epi::KSPLIT / BK) E.midk(acc, cur, wr, wc, fr, fq); }
;             const bool last = (t == nt - 2);
;             const char* a1 = cA + (size_t)(t + 1) * kstep;
;             const char* a2 = last ? nA : cA + (size_t)(t + 2) * kstep; const char* b2 = last ? nB : cB + (size_t)(t + 2) * kstep;
;             const char* a3 = a2 + kstep; const char* b3 = b2 + kstep;
;             if (last && has_next) S.a_ready(nxt);
;             if constexpr (SP2) {
;             PG8_LDB(B0, 0, 0); PG8_LDB(B1, 0, 1); PG8_SCHED; PG8_LDA(At, 0, 0); PG8_STAGE(PG8_SA(1, 1), a1 + hstep, voffA);
;             PG8_WAIT_V(8); PG8_WAIT_L(0); PG8_BAR; PG8_MMA(0, 0, At, B0); PG8_MMA(0, 1, At, B1); PG8_BAR; PG8_SCHED;
;             PG8_LDA(At, 0, 1); PG8_STAGE(PG8_SB(0, 0), b2, voffB); PG8_STAGE(PG8_SB(0, 1), b2 + hstep, voffB); PG8_STAGE(PG8_SA(0, 0), a2, voffA);
;             PG8_WAIT_V(8); PG8_WAIT_L(0); PG8_BAR; PG8_MMA(1, 0, At, B0); PG8_MMA(1, 1, At, B1); PG8_BAR; PG8_SCHED;
.LBB0_373:
	s_ashr_i32 s25, s24, 31
	s_lshl_b64 s[26:27], s[24:25], 20
	s_add_u32 s26, s1, s26
	s_addc_u32 s27, s5, s27
	s_and_b64 s[28:29], s[36:37], exec
	s_cselect_b32 s21, s27, s35
	s_cselect_b32 s25, s26, s34
	s_ashr_i32 s23, s22, 31
	s_lshl_b64 s[28:29], s[22:23], 20
	s_add_u32 s28, s8, s28
	s_addc_u32 s29, s10, s29
	s_and_b64 s[42:43], s[36:37], exec
	s_cselect_b32 s23, s29, s39
	s_cselect_b32 s51, s28, s38
	s_add_u32 s34, s34, 0x80080
	s_addc_u32 s35, s35, 0
	s_add_u32 s52, s38, 0x100
	v_mov_b32_e32 v0, 0
	s_addc_u32 s53, s39, 0
	s_mov_b32 s54, -2
	s_mov_b32 m0, s49
	s_nop 0
	global_load_lds_dwordx4 v134, s[100:101]
	s_add_u32 s38, s34, 0xfff80080
	s_addc_u32 s39, s35, -1
	s_add_i32 s55, 0, 0x10000
	s_cmp_eq_u32 s54, 28
	s_cselect_b32 s43, s21, s39
	s_cselect_b32 s42, s25, s38
	v_add_u32_e32 v144, s55, v21
	s_cselect_b32 s39, s23, s53
	s_cselect_b32 s38, s51, s52
	s_add_i32 s58, 0, 0x14000
	ds_read_b128 v[148:151], v144
	ds_read_b128 v[152:155], v144 offset:1024
	ds_read_b128 v[156:159], v144 offset:2048
	ds_read_b128 v[160:163], v144 offset:3072
	v_add_u32_e32 v144, s58, v21
	ds_read_b128 v[164:167], v144
	ds_read_b128 v[168:171], v144 offset:1024
	ds_read_b128 v[172:175], v144 offset:2048
	ds_read_b128 v[176:179], v144 offset:3072
	s_add_i32 m0, s44, 0xc000
	ds_read_b128 v[180:183], v147
	ds_read_b128 v[184:187], v147 offset:1024
	ds_read_b128 v[188:191], v147 offset:2048
	ds_read_b128 v[192:195], v147 offset:3072
	ds_read_b128 v[196:199], v147 offset:4096
	ds_read_b128 v[200:203], v147 offset:5120
	ds_read_b128 v[208:211], v147 offset:6144
	ds_read_b128 v[212:215], v147 offset:7168
	global_load_lds_dwordx4 v140, s[34:35]
	s_add_i32 m0, s44, 0xe000
	s_nop 0
	global_load_lds_dwordx4 v142, s[34:35]
	s_waitcnt vmcnt(8)
	s_waitcnt lgkmcnt(0)
	s_barrier
	s_setprio 1
	v_mfma_f32_16x16x32_bf16 v[126:129], v[148:151], v[180:183], 0
	v_mfma_f32_16x16x32_bf16 v[122:125], v[156:159], v[180:183], 0
	v_mfma_f32_16x16x32_bf16 v[118:121], v[148:151], v[188:191], 0
	v_mfma_f32_16x16x32_bf16 v[110:113], v[156:159], v[188:191], 0
	v_mfma_f32_16x16x32_bf16 v[102:105], v[148:151], v[196:199], 0
	v_mfma_f32_16x16x32_bf16 v[94:97], v[156:159], v[196:199], 0
	v_mfma_f32_16x16x32_bf16 v[86:89], v[148:151], v[208:211], 0
	v_mfma_f32_16x16x32_bf16 v[78:81], v[156:159], v[208:211], 0
	v_mfma_f32_16x16x32_bf16 v[126:129], v[152:155], v[184:187], v[126:129]
	v_mfma_f32_16x16x32_bf16 v[122:125], v[160:163], v[184:187], v[122:125]
	v_mfma_f32_16x16x32_bf16 v[118:121], v[152:155], v[192:195], v[118:121]
	v_mfma_f32_16x16x32_bf16 v[110:113], v[160:163], v[192:195], v[110:113]
	v_mfma_f32_16x16x32_bf16 v[102:105], v[152:155], v[200:203], v[102:105]
	v_mfma_f32_16x16x32_bf16 v[94:97], v[160:163], v[200:203], v[94:97]
	v_mfma_f32_16x16x32_bf16 v[86:89], v[152:155], v[212:215], v[86:89]
	v_mfma_f32_16x16x32_bf16 v[78:81], v[160:163], v[212:215], v[78:81]
	s_setprio 0
	s_setprio 1
	v_mfma_f32_16x16x32_bf16 v[114:117], v[164:167], v[180:183], 0
	v_mfma_f32_16x16x32_bf16 v[106:109], v[172:175], v[180:183], 0
	v_mfma_f32_16x16x32_bf16 v[98:101], v[164:167], v[188:191], 0
	v_mfma_f32_16x16x32_bf16 v[90:93], v[172:175], v[188:191], 0
	v_mfma_f32_16x16x32_bf16 v[82:85], v[164:167], v[196:199], 0
	v_mfma_f32_16x16x32_bf16 v[74:77], v[172:175], v[196:199], 0
	v_mfma_f32_16x16x32_bf16 v[70:73], v[164:167], v[208:211], 0
	v_mfma_f32_16x16x32_bf16 v[66:69], v[172:175], v[208:211], 0
	v_mfma_f32_16x16x32_bf16 v[114:117], v[168:171], v[184:187], v[114:117]
	v_mfma_f32_16x16x32_bf16 v[106:109], v[176:179], v[184:187], v[106:109]
	v_mfma_f32_16x16x32_bf16 v[98:101], v[168:171], v[192:195], v[98:101]
	v_mfma_f32_16x16x32_bf16 v[90:93], v[176:179], v[192:195], v[90:93]
	v_mfma_f32_16x16x32_bf16 v[82:85], v[168:171], v[200:203], v[82:85]
	v_mfma_f32_16x16x32_bf16 v[74:77], v[176:179], v[200:203], v[74:77]
	v_mfma_f32_16x16x32_bf16 v[70:73], v[168:171], v[212:215], v[70:73]
	v_mfma_f32_16x16x32_bf16 v[66:69], v[176:179], v[212:215], v[66:69]
	s_setprio 0
	s_barrier
	s_add_i32 s55, s55, s19
	s_add_u32 s98, s38, 0x80
	s_addc_u32 s99, s39, 0
	s_mov_b32 m0, s55
	ds_read_b128 v[180:183], v147 offset:16384
	ds_read_b128 v[184:187], v147 offset:17408
	ds_read_b128 v[188:191], v147 offset:18432
	ds_read_b128 v[192:195], v147 offset:19456
	ds_read_b128 v[196:199], v147 offset:20480
	ds_read_b128 v[200:203], v147 offset:21504
	ds_read_b128 v[208:211], v147 offset:22528
	ds_read_b128 v[212:215], v147 offset:23552
	global_load_lds_dwordx4 v132, s[38:39]
	s_add_i32 m0, s55, 0x2000
	s_add_u32 s56, s38, 0x80000
	s_addc_u32 s57, s39, 0
	s_add_i32 s55, s58, s19
	global_load_lds_dwordx4 v136, s[38:39]
	s_mov_b32 m0, s55
	s_add_u32 s100, s42, 0x80
	s_addc_u32 s101, s43, 0
	global_load_lds_dwordx4 v132, s[56:57]
	s_add_i32 m0, s55, 0x2000
	s_nop 0
	global_load_lds_dwordx4 v136, s[56:57]
	s_mov_b32 m0, s44
	s_nop 0
	global_load_lds_dwordx4 v130, s[42:43]
	s_waitcnt vmcnt(7)
	s_waitcnt lgkmcnt(0)
	s_barrier
; #define PG8_STAGE(bufoff, gbase, voff) do { _Pragma("unroll") for (int _i = 0; _i < 2; ++_i) \
;         __builtin_amdgcn_global_load_lds((const unsigned*)((const char*)(gbase) + (voff)[_i]), (PG8_LAS unsigned*)(lds + (bufoff) + ldsw + _i * 8192), 16, 0, 0); } while (0)
; #define PG8_LDA(dst, b, h) do { _Pragma("unroll") for (int m = 0; m < 4; ++m) _Pragma("unroll") for (int k = 0; k < 2; ++k) dst[m][k] = *(const PG8_LAS bf16x8*)(lds + PG8_SA(b, h) + aoff + m * 2048 + k * 1024); } while (0)
; #define PG8_LDB(dst, b, h) do { _Pragma("unroll") for (int n = 0; n < 2; ++n) _Pragma("unroll") for (int k = 0; k < 2; ++k) dst[n][k] = *(const PG8_LAS bf16x8*)(lds + PG8_SB(b, h) + boff + n * 2048 + k * 1024); } while (0)
; #define PG8_MMA(ai, bj, At, Bt) do { __builtin_amdgcn_s_setprio(1); _Pragma("unroll") for (int m = 0; m < 4; ++m) _Pragma("unroll") for (int n = 0; n < 2; ++n) _Pragma("unroll") for (int k = 0; k < 2; ++k) \
;         acc[ai][bj][m][n] = __builtin_amdgcn_mfma_f32_16x16x32_bf16(Bt[n][k], At[m][k], acc[ai][bj][m][n], 0, 0, 0); __builtin_amdgcn_s_setprio(0); } while (0)
; #define PG8_WAIT_V(n) asm volatile("s_waitcnt vmcnt(" #n ")" ::: "memory")
; #define PG8_WAIT_L(n) asm volatile("s_waitcnt lgkmcnt(" #n ")" ::: "memory")
; #define PG8_BAR __builtin_amdgcn_s_barrier()
; #define PG8_SCHED __builtin_amdgcn_sched_barrier(0)
; template <class Epi, class Sched, bool ALIGN_EPI = false, bool SP2 = false>
; __device__ __forceinline__ void gemm_phase(PG8_LAS unsigned char* lds, const Gemm g, const Sched& S, const Epi& E, const int tid_in) {
;     ...
;             PG8_WAIT_V(8); PG8_WAIT_L(0); PG8_BAR; PG8_MMA(0, 0, At, B0); PG8_MMA(0, 1, At, B1); PG8_BAR; PG8_SCHED;
;             PG8_LDA(At, 0, 1); PG8_STAGE(PG8_SB(0, 0), b2, voffB); PG8_STAGE(PG8_SB(0, 1), b2 + hstep, voffB); PG8_STAGE(PG8_SA(0, 0), a2, voffA);
;             PG8_WAIT_V(8); PG8_WAIT_L(0); PG8_BAR; PG8_MMA(1, 0, At, B0); PG8_MMA(1, 1, At, B1); PG8_BAR; PG8_SCHED;
;             PG8_LDB(B0, 1, 0); PG8_LDB(B1, 1, 1); PG8_SCHED; PG8_LDA(At, 1, 0); PG8_STAGE(PG8_SA(0, 1), a2 + hstep, voffA);
;             PG8_WAIT_V(8); PG8_WAIT_L(0); PG8_BAR; PG8_MMA(0, 0, At, B0); PG8_MMA(0, 1, At, B1); PG8_BAR; PG8_SCHED;
	s_setprio 1
	v_mfma_f32_16x16x32_bf16 v[62:65], v[148:151], v[180:183], 0
	v_mfma_f32_16x16x32_bf16 v[58:61], v[156:159], v[180:183], 0
	v_mfma_f32_16x16x32_bf16 v[54:57], v[148:151], v[188:191], 0
	v_mfma_f32_16x16x32_bf16 v[46:49], v[156:159], v[188:191], 0
	v_mfma_f32_16x16x32_bf16 v[38:41], v[148:151], v[196:199], 0
	v_mfma_f32_16x16x32_bf16 v[30:33], v[156:159], v[196:199], 0
	v_mfma_f32_16x16x32_bf16 v[22:25], v[148:151], v[208:211], 0
	v_mfma_f32_16x16x32_bf16 v[12:15], v[156:159], v[208:211], 0
	v_mfma_f32_16x16x32_bf16 v[62:65], v[152:155], v[184:187], v[62:65]
	v_mfma_f32_16x16x32_bf16 v[58:61], v[160:163], v[184:187], v[58:61]
	v_mfma_f32_16x16x32_bf16 v[54:57], v[152:155], v[192:195], v[54:57]
	v_mfma_f32_16x16x32_bf16 v[46:49], v[160:163], v[192:195], v[46:49]
	v_mfma_f32_16x16x32_bf16 v[38:41], v[152:155], v[200:203], v[38:41]
	v_mfma_f32_16x16x32_bf16 v[30:33], v[160:163], v[200:203], v[30:33]
	v_mfma_f32_16x16x32_bf16 v[22:25], v[152:155], v[212:215], v[22:25]
	v_mfma_f32_16x16x32_bf16 v[12:15], v[160:163], v[212:215], v[12:15]
	s_setprio 0
	s_setprio 1
	v_mfma_f32_16x16x32_bf16 v[50:53], v[164:167], v[180:183], 0
	v_mfma_f32_16x16x32_bf16 v[42:45], v[172:175], v[180:183], 0
	v_mfma_f32_16x16x32_bf16 v[34:37], v[164:167], v[188:191], 0
	v_mfma_f32_16x16x32_bf16 v[26:29], v[172:175], v[188:191], 0
	v_mfma_f32_16x16x32_bf16 v[16:19], v[164:167], v[196:199], 0
	v_mfma_f32_16x16x32_bf16 v[8:11], v[172:175], v[196:199], 0
	v_mfma_f32_16x16x32_bf16 v[4:7], v[164:167], v[208:211], 0
	v_mfma_f32_16x16x32_bf16 v[0:3], v[172:175], v[208:211], 0
	v_mfma_f32_16x16x32_bf16 v[50:53], v[168:171], v[184:187], v[50:53]
	v_mfma_f32_16x16x32_bf16 v[42:45], v[176:179], v[184:187], v[42:45]
	v_mfma_f32_16x16x32_bf16 v[34:37], v[168:171], v[192:195], v[34:37]
	v_mfma_f32_16x16x32_bf16 v[26:29], v[176:179], v[192:195], v[26:29]
	v_mfma_f32_16x16x32_bf16 v[16:19], v[168:171], v[200:203], v[16:19]
	v_mfma_f32_16x16x32_bf16 v[8:11], v[176:179], v[200:203], v[8:11]
	v_mfma_f32_16x16x32_bf16 v[4:7], v[168:171], v[212:215], v[4:7]
	v_mfma_f32_16x16x32_bf16 v[0:3], v[176:179], v[212:215], v[0:3]
	s_setprio 0
	s_barrier
	s_add_i32 s55, 0, 0x18000
	s_add_i32 s56, 0, 0x1c000
	v_add_u32_e32 v160, s55, v21
	v_add_u32_e32 v176, s56, v21
	ds_read_b128 v[148:151], v160
	ds_read_b128 v[152:155], v160 offset:1024
	ds_read_b128 v[156:159], v160 offset:2048
	ds_read_b128 v[160:163], v160 offset:3072
	ds_read_b128 v[164:167], v176
	ds_read_b128 v[168:171], v176 offset:1024
	ds_read_b128 v[172:175], v176 offset:2048
	ds_read_b128 v[176:179], v176 offset:3072
	s_mov_b32 m0, s45
	s_nop 0
	global_load_lds_dwordx4 v134, s[42:43]
	s_add_u32 s42, s42, 0x80000
	s_addc_u32 s43, s43, 0
	s_mov_b32 m0, s46
	ds_read_b128 v[180:183], v147 offset:32768
	ds_read_b128 v[184:187], v147 offset:33792
	ds_read_b128 v[188:191], v147 offset:34816
	ds_read_b128 v[192:195], v147 offset:35840
	ds_read_b128 v[196:199], v147 offset:36864
	ds_read_b128 v[200:203], v147 offset:37888
	ds_read_b128 v[208:211], v147 offset:38912
	ds_read_b128 v[212:215], v147 offset:39936
	global_load_lds_dwordx4 v130, s[42:43]
	s_mov_b32 m0, s47
	s_nop 0
	global_load_lds_dwordx4 v134, s[42:43]
	s_waitcnt vmcnt(8)
	s_waitcnt lgkmcnt(0)
	s_barrier
	s_setprio 1
	v_mfma_f32_16x16x32_bf16 v[126:129], v[148:151], v[180:183], v[126:129]
	v_mfma_f32_16x16x32_bf16 v[122:125], v[156:159], v[180:183], v[122:125]
	v_mfma_f32_16x16x32_bf16 v[118:121], v[148:151], v[188:191], v[118:121]
	v_mfma_f32_16x16x32_bf16 v[110:113], v[156:159], v[188:191], v[110:113]
	v_mfma_f32_16x16x32_bf16 v[102:105], v[148:151], v[196:199], v[102:105]
	v_mfma_f32_16x16x32_bf16 v[94:97], v[156:159], v[196:199], v[94:97]
	v_mfma_f32_16x16x32_bf16 v[86:89], v[148:151], v[208:211], v[86:89]
	v_mfma_f32_16x16x32_bf16 v[78:81], v[156:159], v[208:211], v[78:81]
	v_mfma_f32_16x16x32_bf16 v[126:129], v[152:155], v[184:187], v[126:129]
	v_mfma_f32_16x16x32_bf16 v[122:125], v[160:163], v[184:187], v[122:125]
	v_mfma_f32_16x16x32_bf16 v[118:121], v[152:155], v[192:195], v[118:121]
	v_mfma_f32_16x16x32_bf16 v[110:113], v[160:163], v[192:195], v[110:113]
	v_mfma_f32_16x16x32_bf16 v[102:105], v[152:155], v[200:203], v[102:105]
	v_mfma_f32_16x16x32_bf16 v[94:97], v[160:163], v[200:203], v[94:97]
	v_mfma_f32_16x16x32_bf16 v[86:89], v[152:155], v[212:215], v[86:89]
	v_mfma_f32_16x16x32_bf16 v[78:81], v[160:163], v[212:215], v[78:81]
	s_setprio 0
	s_setprio 1
	v_mfma_f32_16x16x32_bf16 v[114:117], v[164:167], v[180:183], v[114:117]
	v_mfma_f32_16x16x32_bf16 v[106:109], v[172:175], v[180:183], v[106:109]
	v_mfma_f32_16x16x32_bf16 v[98:101], v[164:167], v[188:191], v[98:101]
	v_mfma_f32_16x16x32_bf16 v[90:93], v[172:175], v[188:191], v[90:93]
	v_mfma_f32_16x16x32_bf16 v[82:85], v[164:167], v[196:199], v[82:85]
	v_mfma_f32_16x16x32_bf16 v[74:77], v[172:175], v[196:199], v[74:77]
	v_mfma_f32_16x16x32_bf16 v[70:73], v[164:167], v[208:211], v[70:73]
	v_mfma_f32_16x16x32_bf16 v[66:69], v[172:175], v[208:211], v[66:69]
	v_mfma_f32_16x16x32_bf16 v[114:117], v[168:171], v[184:187], v[114:117]
	v_mfma_f32_16x16x32_bf16 v[106:109], v[176:179], v[184:187], v[106:109]
	v_mfma_f32_16x16x32_bf16 v[98:101], v[168:171], v[192:195], v[98:101]
	v_mfma_f32_16x16x32_bf16 v[90:93], v[176:179], v[192:195], v[90:93]
	v_mfma_f32_16x16x32_bf16 v[82:85], v[168:171], v[200:203], v[82:85]
	v_mfma_f32_16x16x32_bf16 v[74:77], v[176:179], v[200:203], v[74:77]
	v_mfma_f32_16x16x32_bf16 v[70:73], v[168:171], v[212:215], v[70:73]
	v_mfma_f32_16x16x32_bf16 v[66:69], v[176:179], v[212:215], v[66:69]
	s_setprio 0
	s_barrier
; #define PG8_STAGE(bufoff, gbase, voff) do { _Pragma("unroll") for (int _i = 0; _i < 2; ++_i) \
;         __builtin_amdgcn_global_load_lds((const unsigned*)((const char*)(gbase) + (voff)[_i]), (PG8_LAS unsigned*)(lds + (bufoff) + ldsw + _i * 8192), 16, 0, 0); } while (0)
; #define PG8_LDA(dst, b, h) do { _Pragma("unroll") for (int m = 0; m < 4; ++m) _Pragma("unroll") for (int k = 0; k < 2; ++k) dst[m][k] = *(const PG8_LAS bf16x8*)(lds + PG8_SA(b, h) + aoff + m * 2048 + k * 1024); } while (0)
; #define PG8_MMA(ai, bj, At, Bt) do { __builtin_amdgcn_s_setprio(1); _Pragma("unroll") for (int m = 0; m < 4; ++m) _Pragma("unroll") for (int n = 0; n < 2; ++n) _Pragma("unroll") for (int k = 0; k < 2; ++k) \
;         acc[ai][bj][m][n] = __builtin_amdgcn_mfma_f32_16x16x32_bf16(Bt[n][k], At[m][k], acc[ai][bj][m][n], 0, 0, 0); __builtin_amdgcn_s_setprio(0); } while (0)
; #define PG8_WAIT_V(n) asm volatile("s_waitcnt vmcnt(" #n ")" ::: "memory")
; #define PG8_WAIT_L(n) asm volatile("s_waitcnt lgkmcnt(" #n ")" ::: "memory")
; #define PG8_BAR __builtin_amdgcn_s_barrier()
; #define PG8_SCHED __builtin_amdgcn_sched_barrier(0)
; template <class Epi, class Sched, bool ALIGN_EPI = false, bool SP2 = false>
; __device__ __forceinline__ void gemm_phase(PG8_LAS unsigned char* lds, const Gemm g, const Sched& S, const Epi& E, const int tid_in) {
;     ...
;             PG8_LDA(At, 1, 1); PG8_STAGE(PG8_SB(1, 0), b3, voffB); PG8_STAGE(PG8_SB(1, 1), b3 + hstep, voffB); PG8_STAGE(PG8_SA(1, 0), a3, voffA);
;             PG8_WAIT_V(8); PG8_WAIT_L(0); PG8_BAR; PG8_MMA(1, 0, At, B0); PG8_MMA(1, 1, At, B1); PG8_BAR; PG8_SCHED;
	s_add_i32 s42, s55, s19
	s_mov_b32 m0, s42
	ds_read_b128 v[180:183], v147 offset:49152
	ds_read_b128 v[184:187], v147 offset:50176
	ds_read_b128 v[188:191], v147 offset:51200
	ds_read_b128 v[192:195], v147 offset:52224
	ds_read_b128 v[196:199], v147 offset:53248
	ds_read_b128 v[200:203], v147 offset:54272
	ds_read_b128 v[208:211], v147 offset:55296
	ds_read_b128 v[212:215], v147 offset:56320
	global_load_lds_dwordx4 v132, s[98:99]
	s_add_i32 m0, s42, 0x2000
	s_add_u32 s38, s38, 0x80080
	s_addc_u32 s39, s39, 0
	s_add_i32 s42, s56, s19
	global_load_lds_dwordx4 v136, s[98:99]
	s_mov_b32 m0, s42
	s_nop 0
	global_load_lds_dwordx4 v132, s[38:39]
	s_add_i32 m0, s42, 0x2000
	s_nop 0
	global_load_lds_dwordx4 v136, s[38:39]
	s_mov_b32 m0, s48
	s_nop 0
	global_load_lds_dwordx4 v130, s[100:101]
	s_waitcnt vmcnt(7)
	s_waitcnt lgkmcnt(0)
	s_barrier
	s_setprio 1
	v_mfma_f32_16x16x32_bf16 v[62:65], v[148:151], v[180:183], v[62:65]
	v_mfma_f32_16x16x32_bf16 v[58:61], v[156:159], v[180:183], v[58:61]
	v_mfma_f32_16x16x32_bf16 v[54:57], v[148:151], v[188:191], v[54:57]
	v_mfma_f32_16x16x32_bf16 v[46:49], v[156:159], v[188:191], v[46:49]
	v_mfma_f32_16x16x32_bf16 v[38:41], v[148:151], v[196:199], v[38:41]
	v_mfma_f32_16x16x32_bf16 v[30:33], v[156:159], v[196:199], v[30:33]
	v_mfma_f32_16x16x32_bf16 v[22:25], v[148:151], v[208:211], v[22:25]
	v_mfma_f32_16x16x32_bf16 v[12:15], v[156:159], v[208:211], v[12:15]
	v_mfma_f32_16x16x32_bf16 v[62:65], v[152:155], v[184:187], v[62:65]
	v_mfma_f32_16x16x32_bf16 v[58:61], v[160:163], v[184:187], v[58:61]
	v_mfma_f32_16x16x32_bf16 v[54:57], v[152:155], v[192:195], v[54:57]
	v_mfma_f32_16x16x32_bf16 v[46:49], v[160:163], v[192:195], v[46:49]
	v_mfma_f32_16x16x32_bf16 v[38:41], v[152:155], v[200:203], v[38:41]
	v_mfma_f32_16x16x32_bf16 v[30:33], v[160:163], v[200:203], v[30:33]
	v_mfma_f32_16x16x32_bf16 v[22:25], v[152:155], v[212:215], v[22:25]
	v_mfma_f32_16x16x32_bf16 v[12:15], v[160:163], v[212:215], v[12:15]
	s_setprio 0
	s_setprio 1
	v_mfma_f32_16x16x32_bf16 v[50:53], v[164:167], v[180:183], v[50:53]
	v_mfma_f32_16x16x32_bf16 v[42:45], v[172:175], v[180:183], v[42:45]
	v_mfma_f32_16x16x32_bf16 v[34:37], v[164:167], v[188:191], v[34:37]
	v_mfma_f32_16x16x32_bf16 v[26:29], v[172:175], v[188:191], v[26:29]
	v_mfma_f32_16x16x32_bf16 v[16:19], v[164:167], v[196:199], v[16:19]
	v_mfma_f32_16x16x32_bf16 v[8:11], v[172:175], v[196:199], v[8:11]
	v_mfma_f32_16x16x32_bf16 v[4:7], v[164:167], v[208:211], v[4:7]
	v_mfma_f32_16x16x32_bf16 v[0:3], v[172:175], v[208:211], v[0:3]
	v_mfma_f32_16x16x32_bf16 v[50:53], v[168:171], v[184:187], v[50:53]
	v_mfma_f32_16x16x32_bf16 v[42:45], v[176:179], v[184:187], v[42:45]
	v_mfma_f32_16x16x32_bf16 v[34:37], v[168:171], v[192:195], v[34:37]
	v_mfma_f32_16x16x32_bf16 v[26:29], v[176:179], v[192:195], v[26:29]
	v_mfma_f32_16x16x32_bf16 v[16:19], v[168:171], v[200:203], v[16:19]
	v_mfma_f32_16x16x32_bf16 v[8:11], v[176:179], v[200:203], v[8:11]
	v_mfma_f32_16x16x32_bf16 v[4:7], v[168:171], v[212:215], v[4:7]
	v_mfma_f32_16x16x32_bf16 v[0:3], v[176:179], v[212:215], v[0:3]
	s_setprio 0
	s_barrier
	s_add_i32 s54, s54, 2
	s_add_u32 s34, s34, 0x100
	s_addc_u32 s35, s35, 0
	s_add_u32 s52, s52, 0x100
	s_addc_u32 s53, s53, 0
	s_cmp_gt_u32 s54, 29

; #define PG8_STAGE(bufoff, gbase, voff) do { _Pragma("unroll") for (int _i = 0; _i < 2; ++_i) \
;         __builtin_amdgcn_global_load_lds((const unsigned*)((const char*)(gbase) + (voff)[_i]), (PG8_LAS unsigned*)(lds + (bufoff) + ldsw + _i * 8192), 16, 0, 0); } while (0)
; #define PG8_LDA(dst, b, h) do { _Pragma("unroll") for (int m = 0; m < 4; ++m) _Pragma("unroll") for (int k = 0; k < 2; ++k) dst[m][k] = *(const PG8_LAS bf16x8*)(lds + PG8_SA(b, h) + aoff + m * 2048 + k * 1024); } while (0)
; #define PG8_LDB(dst, b, h) do { _Pragma("unroll") for (int n = 0; n < 2; ++n) _Pragma("unroll") for (int k = 0; k < 2; ++k) dst[n][k] = *(const PG8_LAS bf16x8*)(lds + PG8_SB(b, h) + boff + n * 2048 + k * 1024); } while (0)
; #define PG8_WAIT_V(n) asm volatile("s_waitcnt vmcnt(" #n ")" ::: "memory")
; #define PG8_WAIT_L(n) asm volatile("s_waitcnt lgkmcnt(" #n ")" ::: "memory")
; #define PG8_BAR __builtin_amdgcn_s_barrier()
; #define PG8_SCHED __builtin_amdgcn_sched_barrier(0)
; template <class Epi, class Sched, bool ALIGN_EPI = false, bool SP2 = false>
; __device__ __forceinline__ void gemm_phase(PG8_LAS unsigned char* lds, const Gemm g, const Sched& S, const Epi& E, const int tid_in) {
;     ...
;             const bool last = (t == nt - 2);
;             const char* a1 = cA + (size_t)(t + 1) * kstep;
;             const char* a2 = last ? nA : cA + (size_t)(t + 2) * kstep; const char* b2 = last ? nB : cB + (size_t)(t + 2) * kstep;
;             const char* a3 = a2 + kstep; const char* b3 = b2 + kstep;
;             if (last && has_next) S.a_ready(nxt);
;             if constexpr (SP2) {
;             PG8_LDB(B0, 0, 0); PG8_LDB(B1, 0, 1); PG8_SCHED; PG8_LDA(At, 0, 0); PG8_STAGE(PG8_SA(1, 1), a1 + hstep, voffA);
;             PG8_WAIT_V(8); PG8_WAIT_L(0); PG8_BAR; PG8_MMA(0, 0, At, B0); PG8_MMA(0, 1, At, B1); PG8_BAR; PG8_SCHED;
;             PG8_LDA(At, 0, 1); PG8_STAGE(PG8_SB(0, 0), b2, voffB); PG8_STAGE(PG8_SB(0, 1), b2 + hstep, voffB); PG8_STAGE(PG8_SA(0, 0), a2, voffA);
;             PG8_WAIT_V(8); PG8_WAIT_L(0); PG8_BAR; PG8_MMA(1, 0, At, B0); PG8_MMA(1, 1, At, B1); PG8_BAR; PG8_SCHED;
;     ...
;         for (int a = 0; a < 2; ++a)
; #pragma unroll
;             for (int b = 0; b < 2; ++b)
; #pragma unroll
;                 for (int m = 0; m < 4; ++m)
; #pragma unroll
;                     for (int n = 0; n < 2; ++n) acc[a][b][m][n] = (f32x4){0.f, 0.f, 0.f, 0.f};
.LBB0_393:
	s_ashr_i32 s23, s22, 31
	s_lshl_b64 s[24:25], s[22:23], 20
	s_add_u32 s24, s1, s24
	s_addc_u32 s25, s5, s25
	s_and_b64 s[26:27], s[36:37], exec
	s_cselect_b32 s23, s25, s29
	s_cselect_b32 s49, s24, s28
	s_ashr_i32 s21, s20, 31
	s_lshl_b64 s[26:27], s[20:21], 20
	s_add_u32 s26, s8, s26
	s_addc_u32 s27, s10, s27
	s_and_b64 s[34:35], s[36:37], exec
	s_cselect_b32 s21, s27, s31
	s_cselect_b32 s50, s26, s30
	s_add_u32 s28, s28, 0x80080
	s_addc_u32 s29, s29, 0
	s_add_u32 s51, s30, 0x100
	v_mov_b32_e32 v0, 0
	s_addc_u32 s52, s31, 0
	s_mov_b32 s53, -2
	s_mov_b32 m0, s45
	s_nop 0
	global_load_lds_dwordx4 v132, s[100:101]
	s_add_u32 s30, s28, 0xfff80080
	s_addc_u32 s31, s29, -1
	s_add_i32 s54, 0, 0x10000
	s_cmp_eq_u32 s53, 28
	s_cselect_b32 s35, s23, s31
	s_cselect_b32 s34, s49, s30
	v_add_u32_e32 v144, s54, v21
	s_cselect_b32 s31, s21, s52
	s_cselect_b32 s30, s50, s51
	s_add_i32 s56, 0, 0x14000
	ds_read_b128 v[148:151], v144
	ds_read_b128 v[152:155], v144 offset:1024
	ds_read_b128 v[156:159], v144 offset:2048
	ds_read_b128 v[160:163], v144 offset:3072
	v_add_u32_e32 v144, s56, v21
	ds_read_b128 v[164:167], v144
	ds_read_b128 v[168:171], v144 offset:1024
	ds_read_b128 v[172:175], v144 offset:2048
	ds_read_b128 v[176:179], v144 offset:3072
	s_add_i32 m0, s38, 0xc000
	ds_read_b128 v[180:183], v147
	ds_read_b128 v[184:187], v147 offset:1024
	ds_read_b128 v[188:191], v147 offset:2048
	ds_read_b128 v[192:195], v147 offset:3072
	ds_read_b128 v[196:199], v147 offset:4096
	ds_read_b128 v[200:203], v147 offset:5120
	ds_read_b128 v[208:211], v147 offset:6144
	ds_read_b128 v[212:215], v147 offset:7168
	global_load_lds_dwordx4 v140, s[28:29]
	s_add_i32 m0, s38, 0xe000
	s_nop 0
	global_load_lds_dwordx4 v142, s[28:29]
	s_waitcnt vmcnt(8)
	s_waitcnt lgkmcnt(0)
	s_barrier
	s_setprio 1
	v_mfma_f32_16x16x32_bf16 v[126:129], v[148:151], v[180:183], 0
	v_mfma_f32_16x16x32_bf16 v[122:125], v[156:159], v[180:183], 0
	v_mfma_f32_16x16x32_bf16 v[118:121], v[148:151], v[188:191], 0
	v_mfma_f32_16x16x32_bf16 v[110:113], v[156:159], v[188:191], 0
	v_mfma_f32_16x16x32_bf16 v[102:105], v[148:151], v[196:199], 0
	v_mfma_f32_16x16x32_bf16 v[94:97], v[156:159], v[196:199], 0
	v_mfma_f32_16x16x32_bf16 v[86:89], v[148:151], v[208:211], 0
	v_mfma_f32_16x16x32_bf16 v[78:81], v[156:159], v[208:211], 0
	v_mfma_f32_16x16x32_bf16 v[126:129], v[152:155], v[184:187], v[126:129]
	v_mfma_f32_16x16x32_bf16 v[122:125], v[160:163], v[184:187], v[122:125]
	v_mfma_f32_16x16x32_bf16 v[118:121], v[152:155], v[192:195], v[118:121]
	v_mfma_f32_16x16x32_bf16 v[110:113], v[160:163], v[192:195], v[110:113]
	v_mfma_f32_16x16x32_bf16 v[102:105], v[152:155], v[200:203], v[102:105]
	v_mfma_f32_16x16x32_bf16 v[94:97], v[160:163], v[200:203], v[94:97]
	v_mfma_f32_16x16x32_bf16 v[86:89], v[152:155], v[212:215], v[86:89]
	v_mfma_f32_16x16x32_bf16 v[78:81], v[160:163], v[212:215], v[78:81]
	s_setprio 0
	s_setprio 1
	v_mfma_f32_16x16x32_bf16 v[114:117], v[164:167], v[180:183], 0
	v_mfma_f32_16x16x32_bf16 v[106:109], v[172:175], v[180:183], 0
	v_mfma_f32_16x16x32_bf16 v[98:101], v[164:167], v[188:191], 0
	v_mfma_f32_16x16x32_bf16 v[90:93], v[172:175], v[188:191], 0
	v_mfma_f32_16x16x32_bf16 v[82:85], v[164:167], v[196:199], 0
	v_mfma_f32_16x16x32_bf16 v[74:77], v[172:175], v[196:199], 0
	v_mfma_f32_16x16x32_bf16 v[70:73], v[164:167], v[208:211], 0
	v_mfma_f32_16x16x32_bf16 v[66:69], v[172:175], v[208:211], 0
	v_mfma_f32_16x16x32_bf16 v[114:117], v[168:171], v[184:187], v[114:117]
	v_mfma_f32_16x16x32_bf16 v[106:109], v[176:179], v[184:187], v[106:109]
	v_mfma_f32_16x16x32_bf16 v[98:101], v[168:171], v[192:195], v[98:101]
	v_mfma_f32_16x16x32_bf16 v[90:93], v[176:179], v[192:195], v[90:93]
	v_mfma_f32_16x16x32_bf16 v[82:85], v[168:171], v[200:203], v[82:85]
	v_mfma_f32_16x16x32_bf16 v[74:77], v[176:179], v[200:203], v[74:77]
	v_mfma_f32_16x16x32_bf16 v[70:73], v[168:171], v[212:215], v[70:73]
	v_mfma_f32_16x16x32_bf16 v[66:69], v[176:179], v[212:215], v[66:69]
	s_setprio 0
	s_barrier
	s_add_i32 s54, s54, s19
	s_add_u32 s98, s30, 0x80
	s_addc_u32 s99, s31, 0
	s_mov_b32 m0, s54
	ds_read_b128 v[180:183], v147 offset:16384
	ds_read_b128 v[184:187], v147 offset:17408
	ds_read_b128 v[188:191], v147 offset:18432
	ds_read_b128 v[192:195], v147 offset:19456
	ds_read_b128 v[196:199], v147 offset:20480
	ds_read_b128 v[200:203], v147 offset:21504
	ds_read_b128 v[208:211], v147 offset:22528
	ds_read_b128 v[212:215], v147 offset:23552
	global_load_lds_dwordx4 v134, s[30:31]
	s_add_i32 m0, s54, 0x2000
	s_add_u32 s54, s30, 0x80000
	s_addc_u32 s55, s31, 0
	s_add_i32 s56, s56, s19
	global_load_lds_dwordx4 v130, s[30:31]
	s_mov_b32 m0, s56
	s_add_u32 s100, s34, 0x80
	s_addc_u32 s101, s35, 0
	global_load_lds_dwordx4 v134, s[54:55]
	s_add_i32 m0, s56, 0x2000
	s_nop 0
	global_load_lds_dwordx4 v130, s[54:55]
	s_mov_b32 m0, s38
	s_nop 0
	global_load_lds_dwordx4 v136, s[34:35]
	s_waitcnt vmcnt(7)
	s_waitcnt lgkmcnt(0)
	s_barrier
; #define PG8_STAGE(bufoff, gbase, voff) do { _Pragma("unroll") for (int _i = 0; _i < 2; ++_i) \
;         __builtin_amdgcn_global_load_lds((const unsigned*)((const char*)(gbase) + (voff)[_i]), (PG8_LAS unsigned*)(lds + (bufoff) + ldsw + _i * 8192), 16, 0, 0); } while (0)
; #define PG8_LDA(dst, b, h) do { _Pragma("unroll") for (int m = 0; m < 4; ++m) _Pragma("unroll") for (int k = 0; k < 2; ++k) dst[m][k] = *(const PG8_LAS bf16x8*)(lds + PG8_SA(b, h) + aoff + m * 2048 + k * 1024); } while (0)
; #define PG8_LDB(dst, b, h) do { _Pragma("unroll") for (int n = 0; n < 2; ++n) _Pragma("unroll") for (int k = 0; k < 2; ++k) dst[n][k] = *(const PG8_LAS bf16x8*)(lds + PG8_SB(b, h) + boff + n * 2048 + k * 1024); } while (0)
; #define PG8_MMA(ai, bj, At, Bt) do { __builtin_amdgcn_s_setprio(1); _Pragma("unroll") for (int m = 0; m < 4; ++m) _Pragma("unroll") for (int n = 0; n < 2; ++n) _Pragma("unroll") for (int k = 0; k < 2; ++k) \
;         acc[ai][bj][m][n] = __builtin_amdgcn_mfma_f32_16x16x32_bf16(Bt[n][k], At[m][k], acc[ai][bj][m][n], 0, 0, 0); __builtin_amdgcn_s_setprio(0); } while (0)
; #define PG8_WAIT_V(n) asm volatile("s_waitcnt vmcnt(" #n ")" ::: "memory")
; #define PG8_WAIT_L(n) asm volatile("s_waitcnt lgkmcnt(" #n ")" ::: "memory")
; #define PG8_BAR __builtin_amdgcn_s_barrier()
; #define PG8_SCHED __builtin_amdgcn_sched_barrier(0)
; template <class Epi, class Sched, bool ALIGN_EPI = false, bool SP2 = false>
; __device__ __forceinline__ void gemm_phase(PG8_LAS unsigned char* lds, const Gemm g, const Sched& S, const Epi& E, const int tid_in) {
;     ...
;             PG8_WAIT_V(8); PG8_WAIT_L(0); PG8_BAR; PG8_MMA(1, 0, At, B0); PG8_MMA(1, 1, At, B1); PG8_BAR; PG8_SCHED;
;             PG8_LDB(B0, 1, 0); PG8_LDB(B1, 1, 1); PG8_SCHED; PG8_LDA(At, 1, 0); PG8_STAGE(PG8_SA(0, 1), a2 + hstep, voffA);
;             PG8_WAIT_V(8); PG8_WAIT_L(0); PG8_BAR; PG8_MMA(0, 0, At, B0); PG8_MMA(0, 1, At, B1); PG8_BAR; PG8_SCHED;
	s_setprio 1
	v_mfma_f32_16x16x32_bf16 v[62:65], v[148:151], v[180:183], 0
	v_mfma_f32_16x16x32_bf16 v[58:61], v[156:159], v[180:183], 0
	v_mfma_f32_16x16x32_bf16 v[54:57], v[148:151], v[188:191], 0
	v_mfma_f32_16x16x32_bf16 v[46:49], v[156:159], v[188:191], 0
	v_mfma_f32_16x16x32_bf16 v[38:41], v[148:151], v[196:199], 0
	v_mfma_f32_16x16x32_bf16 v[30:33], v[156:159], v[196:199], 0
	v_mfma_f32_16x16x32_bf16 v[22:25], v[148:151], v[208:211], 0
	v_mfma_f32_16x16x32_bf16 v[12:15], v[156:159], v[208:211], 0
	v_mfma_f32_16x16x32_bf16 v[62:65], v[152:155], v[184:187], v[62:65]
	v_mfma_f32_16x16x32_bf16 v[58:61], v[160:163], v[184:187], v[58:61]
	v_mfma_f32_16x16x32_bf16 v[54:57], v[152:155], v[192:195], v[54:57]
	v_mfma_f32_16x16x32_bf16 v[46:49], v[160:163], v[192:195], v[46:49]
	v_mfma_f32_16x16x32_bf16 v[38:41], v[152:155], v[200:203], v[38:41]
	v_mfma_f32_16x16x32_bf16 v[30:33], v[160:163], v[200:203], v[30:33]
	v_mfma_f32_16x16x32_bf16 v[22:25], v[152:155], v[212:215], v[22:25]
	v_mfma_f32_16x16x32_bf16 v[12:15], v[160:163], v[212:215], v[12:15]
	s_setprio 0
	s_setprio 1
	v_mfma_f32_16x16x32_bf16 v[50:53], v[164:167], v[180:183], 0
	v_mfma_f32_16x16x32_bf16 v[42:45], v[172:175], v[180:183], 0
	v_mfma_f32_16x16x32_bf16 v[34:37], v[164:167], v[188:191], 0
	v_mfma_f32_16x16x32_bf16 v[26:29], v[172:175], v[188:191], 0
	v_mfma_f32_16x16x32_bf16 v[16:19], v[164:167], v[196:199], 0
	v_mfma_f32_16x16x32_bf16 v[8:11], v[172:175], v[196:199], 0
	v_mfma_f32_16x16x32_bf16 v[4:7], v[164:167], v[208:211], 0
	v_mfma_f32_16x16x32_bf16 v[0:3], v[172:175], v[208:211], 0
	v_mfma_f32_16x16x32_bf16 v[50:53], v[168:171], v[184:187], v[50:53]
	v_mfma_f32_16x16x32_bf16 v[42:45], v[176:179], v[184:187], v[42:45]
	v_mfma_f32_16x16x32_bf16 v[34:37], v[168:171], v[192:195], v[34:37]
	v_mfma_f32_16x16x32_bf16 v[26:29], v[176:179], v[192:195], v[26:29]
	v_mfma_f32_16x16x32_bf16 v[16:19], v[168:171], v[200:203], v[16:19]
	v_mfma_f32_16x16x32_bf16 v[8:11], v[176:179], v[200:203], v[8:11]
	v_mfma_f32_16x16x32_bf16 v[4:7], v[168:171], v[212:215], v[4:7]
	v_mfma_f32_16x16x32_bf16 v[0:3], v[176:179], v[212:215], v[0:3]
	s_setprio 0
	s_barrier
	s_add_i32 s54, 0, 0x18000
	s_add_i32 s55, 0, 0x1c000
	v_add_u32_e32 v160, s54, v21
	v_add_u32_e32 v176, s55, v21
	ds_read_b128 v[148:151], v160
	ds_read_b128 v[152:155], v160 offset:1024
	ds_read_b128 v[156:159], v160 offset:2048
	ds_read_b128 v[160:163], v160 offset:3072
	ds_read_b128 v[164:167], v176
	ds_read_b128 v[168:171], v176 offset:1024
	ds_read_b128 v[172:175], v176 offset:2048
	ds_read_b128 v[176:179], v176 offset:3072
	s_mov_b32 m0, s39
	s_nop 0
	global_load_lds_dwordx4 v132, s[34:35]
	s_add_u32 s34, s34, 0x80000
	s_addc_u32 s35, s35, 0
	s_mov_b32 m0, s42
	ds_read_b128 v[180:183], v147 offset:32768
	ds_read_b128 v[184:187], v147 offset:33792
	ds_read_b128 v[188:191], v147 offset:34816
	ds_read_b128 v[192:195], v147 offset:35840
	ds_read_b128 v[196:199], v147 offset:36864
	ds_read_b128 v[200:203], v147 offset:37888
	ds_read_b128 v[208:211], v147 offset:38912
	ds_read_b128 v[212:215], v147 offset:39936
	global_load_lds_dwordx4 v136, s[34:35]
	s_mov_b32 m0, s43
	s_nop 0
	global_load_lds_dwordx4 v132, s[34:35]
	s_waitcnt vmcnt(8)
	s_waitcnt lgkmcnt(0)
	s_barrier
	s_setprio 1
	v_mfma_f32_16x16x32_bf16 v[126:129], v[148:151], v[180:183], v[126:129]
	v_mfma_f32_16x16x32_bf16 v[122:125], v[156:159], v[180:183], v[122:125]
	v_mfma_f32_16x16x32_bf16 v[118:121], v[148:151], v[188:191], v[118:121]
	v_mfma_f32_16x16x32_bf16 v[110:113], v[156:159], v[188:191], v[110:113]
	v_mfma_f32_16x16x32_bf16 v[102:105], v[148:151], v[196:199], v[102:105]
	v_mfma_f32_16x16x32_bf16 v[94:97], v[156:159], v[196:199], v[94:97]
	v_mfma_f32_16x16x32_bf16 v[86:89], v[148:151], v[208:211], v[86:89]
	v_mfma_f32_16x16x32_bf16 v[78:81], v[156:159], v[208:211], v[78:81]
	v_mfma_f32_16x16x32_bf16 v[126:129], v[152:155], v[184:187], v[126:129]
	v_mfma_f32_16x16x32_bf16 v[122:125], v[160:163], v[184:187], v[122:125]
	v_mfma_f32_16x16x32_bf16 v[118:121], v[152:155], v[192:195], v[118:121]
	v_mfma_f32_16x16x32_bf16 v[110:113], v[160:163], v[192:195], v[110:113]
	v_mfma_f32_16x16x32_bf16 v[102:105], v[152:155], v[200:203], v[102:105]
	v_mfma_f32_16x16x32_bf16 v[94:97], v[160:163], v[200:203], v[94:97]
	v_mfma_f32_16x16x32_bf16 v[86:89], v[152:155], v[212:215], v[86:89]
	v_mfma_f32_16x16x32_bf16 v[78:81], v[160:163], v[212:215], v[78:81]
	s_setprio 0
	s_setprio 1
	v_mfma_f32_16x16x32_bf16 v[114:117], v[164:167], v[180:183], v[114:117]
	v_mfma_f32_16x16x32_bf16 v[106:109], v[172:175], v[180:183], v[106:109]
	v_mfma_f32_16x16x32_bf16 v[98:101], v[164:167], v[188:191], v[98:101]
	v_mfma_f32_16x16x32_bf16 v[90:93], v[172:175], v[188:191], v[90:93]
	v_mfma_f32_16x16x32_bf16 v[82:85], v[164:167], v[196:199], v[82:85]
	v_mfma_f32_16x16x32_bf16 v[74:77], v[172:175], v[196:199], v[74:77]
	v_mfma_f32_16x16x32_bf16 v[70:73], v[164:167], v[208:211], v[70:73]
	v_mfma_f32_16x16x32_bf16 v[66:69], v[172:175], v[208:211], v[66:69]
	v_mfma_f32_16x16x32_bf16 v[114:117], v[168:171], v[184:187], v[114:117]
	v_mfma_f32_16x16x32_bf16 v[106:109], v[176:179], v[184:187], v[106:109]
	v_mfma_f32_16x16x32_bf16 v[98:101], v[168:171], v[192:195], v[98:101]
	v_mfma_f32_16x16x32_bf16 v[90:93], v[176:179], v[192:195], v[90:93]
	v_mfma_f32_16x16x32_bf16 v[82:85], v[168:171], v[200:203], v[82:85]
	v_mfma_f32_16x16x32_bf16 v[74:77], v[176:179], v[200:203], v[74:77]
	v_mfma_f32_16x16x32_bf16 v[70:73], v[168:171], v[212:215], v[70:73]
	v_mfma_f32_16x16x32_bf16 v[66:69], v[176:179], v[212:215], v[66:69]
	s_setprio 0
	s_barrier
; #define PG8_STAGE(bufoff, gbase, voff) do { _Pragma("unroll") for (int _i = 0; _i < 2; ++_i) \
;         __builtin_amdgcn_global_load_lds((const unsigned*)((const char*)(gbase) + (voff)[_i]), (PG8_LAS unsigned*)(lds + (bufoff) + ldsw + _i * 8192), 16, 0, 0); } while (0)
; #define PG8_LDA(dst, b, h) do { _Pragma("unroll") for (int m = 0; m < 4; ++m) _Pragma("unroll") for (int k = 0; k < 2; ++k) dst[m][k] = *(const PG8_LAS bf16x8*)(lds + PG8_SA(b, h) + aoff + m * 2048 + k * 1024); } while (0)
; #define PG8_MMA(ai, bj, At, Bt) do { __builtin_amdgcn_s_setprio(1); _Pragma("unroll") for (int m = 0; m < 4; ++m) _Pragma("unroll") for (int n = 0; n < 2; ++n) _Pragma("unroll") for (int k = 0; k < 2; ++k) \
;         acc[ai][bj][m][n] = __builtin_amdgcn_mfma_f32_16x16x32_bf16(Bt[n][k], At[m][k], acc[ai][bj][m][n], 0, 0, 0); __builtin_amdgcn_s_setprio(0); } while (0)
; #define PG8_WAIT_V(n) asm volatile("s_waitcnt vmcnt(" #n ")" ::: "memory")
; #define PG8_WAIT_L(n) asm volatile("s_waitcnt lgkmcnt(" #n ")" ::: "memory")
; #define PG8_BAR __builtin_amdgcn_s_barrier()
; #define PG8_SCHED __builtin_amdgcn_sched_barrier(0)
; template <class Epi, class Sched, bool ALIGN_EPI = false, bool SP2 = false>
; __device__ __forceinline__ void gemm_phase(PG8_LAS unsigned char* lds, const Gemm g, const Sched& S, const Epi& E, const int tid_in) {
;     ...
;             PG8_LDA(At, 1, 1); PG8_STAGE(PG8_SB(1, 0), b3, voffB); PG8_STAGE(PG8_SB(1, 1), b3 + hstep, voffB); PG8_STAGE(PG8_SA(1, 0), a3, voffA);
;             PG8_WAIT_V(8); PG8_WAIT_L(0); PG8_BAR; PG8_MMA(1, 0, At, B0); PG8_MMA(1, 1, At, B1); PG8_BAR; PG8_SCHED;
	s_add_i32 s34, s54, s19
	s_mov_b32 m0, s34
	ds_read_b128 v[180:183], v147 offset:49152
	ds_read_b128 v[184:187], v147 offset:50176
	ds_read_b128 v[188:191], v147 offset:51200
	ds_read_b128 v[192:195], v147 offset:52224
	ds_read_b128 v[196:199], v147 offset:53248
	ds_read_b128 v[200:203], v147 offset:54272
	ds_read_b128 v[208:211], v147 offset:55296
	ds_read_b128 v[212:215], v147 offset:56320
	global_load_lds_dwordx4 v134, s[98:99]
	s_add_i32 m0, s34, 0x2000
	s_add_u32 s30, s30, 0x80080
	s_addc_u32 s31, s31, 0
	s_add_i32 s34, s55, s19
	global_load_lds_dwordx4 v130, s[98:99]
	s_mov_b32 m0, s34
	s_nop 0
	global_load_lds_dwordx4 v134, s[30:31]
	s_add_i32 m0, s34, 0x2000
	s_nop 0
	global_load_lds_dwordx4 v130, s[30:31]
	s_mov_b32 m0, s44
	s_nop 0
	global_load_lds_dwordx4 v136, s[100:101]
	s_waitcnt vmcnt(7)
	s_waitcnt lgkmcnt(0)
	s_barrier
	s_setprio 1
	v_mfma_f32_16x16x32_bf16 v[62:65], v[148:151], v[180:183], v[62:65]
	v_mfma_f32_16x16x32_bf16 v[58:61], v[156:159], v[180:183], v[58:61]
	v_mfma_f32_16x16x32_bf16 v[54:57], v[148:151], v[188:191], v[54:57]
	v_mfma_f32_16x16x32_bf16 v[46:49], v[156:159], v[188:191], v[46:49]
	v_mfma_f32_16x16x32_bf16 v[38:41], v[148:151], v[196:199], v[38:41]
	v_mfma_f32_16x16x32_bf16 v[30:33], v[156:159], v[196:199], v[30:33]
	v_mfma_f32_16x16x32_bf16 v[22:25], v[148:151], v[208:211], v[22:25]
	v_mfma_f32_16x16x32_bf16 v[12:15], v[156:159], v[208:211], v[12:15]
	v_mfma_f32_16x16x32_bf16 v[62:65], v[152:155], v[184:187], v[62:65]
	v_mfma_f32_16x16x32_bf16 v[58:61], v[160:163], v[184:187], v[58:61]
	v_mfma_f32_16x16x32_bf16 v[54:57], v[152:155], v[192:195], v[54:57]
	v_mfma_f32_16x16x32_bf16 v[46:49], v[160:163], v[192:195], v[46:49]
	v_mfma_f32_16x16x32_bf16 v[38:41], v[152:155], v[200:203], v[38:41]
	v_mfma_f32_16x16x32_bf16 v[30:33], v[160:163], v[200:203], v[30:33]
	v_mfma_f32_16x16x32_bf16 v[22:25], v[152:155], v[212:215], v[22:25]
	v_mfma_f32_16x16x32_bf16 v[12:15], v[160:163], v[212:215], v[12:15]
	s_setprio 0
	s_setprio 1
	v_mfma_f32_16x16x32_bf16 v[50:53], v[164:167], v[180:183], v[50:53]
	v_mfma_f32_16x16x32_bf16 v[42:45], v[172:175], v[180:183], v[42:45]
	v_mfma_f32_16x16x32_bf16 v[34:37], v[164:167], v[188:191], v[34:37]
	v_mfma_f32_16x16x32_bf16 v[26:29], v[172:175], v[188:191], v[26:29]
	v_mfma_f32_16x16x32_bf16 v[16:19], v[164:167], v[196:199], v[16:19]
	v_mfma_f32_16x16x32_bf16 v[8:11], v[172:175], v[196:199], v[8:11]
	v_mfma_f32_16x16x32_bf16 v[4:7], v[164:167], v[208:211], v[4:7]
	v_mfma_f32_16x16x32_bf16 v[0:3], v[172:175], v[208:211], v[0:3]
	v_mfma_f32_16x16x32_bf16 v[50:53], v[168:171], v[184:187], v[50:53]
	v_mfma_f32_16x16x32_bf16 v[42:45], v[176:179], v[184:187], v[42:45]
	v_mfma_f32_16x16x32_bf16 v[34:37], v[168:171], v[192:195], v[34:37]
	v_mfma_f32_16x16x32_bf16 v[26:29], v[176:179], v[192:195], v[26:29]
	v_mfma_f32_16x16x32_bf16 v[16:19], v[168:171], v[200:203], v[16:19]
	v_mfma_f32_16x16x32_bf16 v[8:11], v[176:179], v[200:203], v[8:11]
	v_mfma_f32_16x16x32_bf16 v[4:7], v[168:171], v[212:215], v[4:7]
	v_mfma_f32_16x16x32_bf16 v[0:3], v[176:179], v[212:215], v[0:3]
	s_setprio 0
	s_barrier
	s_add_i32 s53, s53, 2
	s_add_u32 s28, s28, 0x100
	s_addc_u32 s29, s29, 0
	s_add_u32 s51, s51, 0x100
	s_addc_u32 s52, s52, 0
	s_cmp_gt_u32 s53, 29

; #define PG8_STAGE(bufoff, gbase, voff) do { _Pragma("unroll") for (int _i = 0; _i < 2; ++_i) \
;         __builtin_amdgcn_global_load_lds((const unsigned*)((const char*)(gbase) + (voff)[_i]), (PG8_LAS unsigned*)(lds + (bufoff) + ldsw + _i * 8192), 16, 0, 0); } while (0)
; #define PG8_LDA(dst, b, h) do { _Pragma("unroll") for (int m = 0; m < 4; ++m) _Pragma("unroll") for (int k = 0; k < 2; ++k) dst[m][k] = *(const PG8_LAS bf16x8*)(lds + PG8_SA(b, h) + aoff + m * 2048 + k * 1024); } while (0)
; #define PG8_LDB(dst, b, h) do { _Pragma("unroll") for (int n = 0; n < 2; ++n) _Pragma("unroll") for (int k = 0; k < 2; ++k) dst[n][k] = *(const PG8_LAS bf16x8*)(lds + PG8_SB(b, h) + boff + n * 2048 + k * 1024); } while (0)
; #define PG8_WAIT_V(n) asm volatile("s_waitcnt vmcnt(" #n ")" ::: "memory")
; #define PG8_WAIT_L(n) asm volatile("s_waitcnt lgkmcnt(" #n ")" ::: "memory")
; #define PG8_BAR __builtin_amdgcn_s_barrier()
; #define PG8_SCHED __builtin_amdgcn_sched_barrier(0)
; template <class Epi, class Sched, bool ALIGN_EPI = false, bool SP2 = false>
; __device__ __forceinline__ void gemm_phase(PG8_LAS unsigned char* lds, const Gemm g, const Sched& S, const Epi& E, const int tid_in) {
;     ...
;             const bool last = (t == nt - 2);
;             const char* a1 = cA + (size_t)(t + 1) * kstep;
;             const char* a2 = last ? nA : cA + (size_t)(t + 2) * kstep; const char* b2 = last ? nB : cB + (size_t)(t + 2) * kstep;
;             const char* a3 = a2 + kstep; const char* b3 = b2 + kstep;
;             if (last && has_next) S.a_ready(nxt);
;             if constexpr (SP2) {
;             PG8_LDB(B0, 0, 0); PG8_LDB(B1, 0, 1); PG8_SCHED; PG8_LDA(At, 0, 0); PG8_STAGE(PG8_SA(1, 1), a1 + hstep, voffA);
;             PG8_WAIT_V(8); PG8_WAIT_L(0); PG8_BAR; PG8_MMA(0, 0, At, B0); PG8_MMA(0, 1, At, B1); PG8_BAR; PG8_SCHED;
;             PG8_LDA(At, 0, 1); PG8_STAGE(PG8_SB(0, 0), b2, voffB); PG8_STAGE(PG8_SB(0, 1), b2 + hstep, voffB); PG8_STAGE(PG8_SA(0, 0), a2, voffA);
;             PG8_WAIT_V(8); PG8_WAIT_L(0); PG8_BAR; PG8_MMA(1, 0, At, B0); PG8_MMA(1, 1, At, B1); PG8_BAR; PG8_SCHED;
;     ...
;         for (int a = 0; a < 2; ++a)
; #pragma unroll
;             for (int b = 0; b < 2; ++b)
; #pragma unroll
;                 for (int m = 0; m < 4; ++m)
; #pragma unroll
;                     for (int n = 0; n < 2; ++n) acc[a][b][m][n] = (f32x4){0.f, 0.f, 0.f, 0.f};
.LBB0_411:
	s_ashr_i32 s27, s26, 31
	s_lshl_b64 s[28:29], s[26:27], 20
	s_add_u32 s28, s1, s28
	s_addc_u32 s29, s5, s29
	s_and_b64 s[30:31], s[36:37], exec
	s_cselect_b32 s27, s29, s35
	s_cselect_b32 s54, s28, s34
	s_ashr_i32 s7, s6, 31
	s_lshl_b64 s[30:31], s[6:7], 20
	s_add_u32 s30, s8, s30
	s_addc_u32 s31, s10, s31
	s_and_b64 s[42:43], s[36:37], exec
	s_cselect_b32 s7, s31, s39
	s_cselect_b32 s55, s30, s38
	s_add_u32 s34, s34, 0x80080
	s_addc_u32 s35, s35, 0
	s_add_u32 s56, s38, 0x100
	v_mov_b32_e32 v0, 0
	s_addc_u32 s57, s39, 0
	s_mov_b32 s58, -2
	s_mov_b32 m0, s49
	s_nop 0
	global_load_lds_dwordx4 v150, s[100:101]
	s_add_u32 s38, s34, 0xfff80080
	s_addc_u32 s39, s35, -1
	s_add_i32 s59, 0, 0x10000
	s_cmp_eq_u32 s58, 28
	s_cselect_b32 s43, s27, s39
	s_cselect_b32 s42, s54, s38
	s_cselect_b32 s39, s7, s57
	s_cselect_b32 s38, s55, s56
	s_add_i32 s62, 0, 0x14000
	v_add_u32_e32 v78, s59, v162
	v_add_u32_e32 v160, s62, v162
	ds_read_b128 v[66:69], v78
	ds_read_b128 v[70:73], v78 offset:1024
	ds_read_b128 v[74:77], v78 offset:2048
	ds_read_b128 v[78:81], v78 offset:3072
	ds_read_b128 v[166:169], v160
	ds_read_b128 v[170:173], v160 offset:1024
	ds_read_b128 v[174:177], v160 offset:2048
	ds_read_b128 v[178:181], v160 offset:3072
	s_add_i32 m0, s44, 0xc000
	ds_read_b128 v[182:185], v165
	ds_read_b128 v[186:189], v165 offset:1024
	ds_read_b128 v[190:193], v165 offset:2048
	ds_read_b128 v[194:197], v165 offset:3072
	ds_read_b128 v[198:201], v165 offset:4096
	ds_read_b128 v[202:205], v165 offset:5120
	ds_read_b128 v[208:211], v165 offset:6144
	ds_read_b128 v[212:215], v165 offset:7168
	global_load_lds_dwordx4 v156, s[34:35]
	s_add_i32 m0, s44, 0xe000
	s_nop 0
	global_load_lds_dwordx4 v158, s[34:35]
	s_waitcnt vmcnt(8)
	s_waitcnt lgkmcnt(0)
	s_barrier
	s_setprio 1
	v_mfma_f32_16x16x32_bf16 v[142:145], v[66:69], v[182:185], 0
	v_mfma_f32_16x16x32_bf16 v[138:141], v[74:77], v[182:185], 0
	v_mfma_f32_16x16x32_bf16 v[126:129], v[66:69], v[190:193], 0
	v_mfma_f32_16x16x32_bf16 v[122:125], v[74:77], v[190:193], 0
	v_mfma_f32_16x16x32_bf16 v[110:113], v[66:69], v[198:201], 0
	v_mfma_f32_16x16x32_bf16 v[106:109], v[74:77], v[198:201], 0
	v_mfma_f32_16x16x32_bf16 v[94:97], v[66:69], v[208:211], 0
	v_mfma_f32_16x16x32_bf16 v[90:93], v[74:77], v[208:211], 0
	v_mfma_f32_16x16x32_bf16 v[142:145], v[70:73], v[186:189], v[142:145]
	v_mfma_f32_16x16x32_bf16 v[138:141], v[78:81], v[186:189], v[138:141]
	v_mfma_f32_16x16x32_bf16 v[126:129], v[70:73], v[194:197], v[126:129]
	v_mfma_f32_16x16x32_bf16 v[122:125], v[78:81], v[194:197], v[122:125]
	v_mfma_f32_16x16x32_bf16 v[110:113], v[70:73], v[202:205], v[110:113]
	v_mfma_f32_16x16x32_bf16 v[106:109], v[78:81], v[202:205], v[106:109]
	v_mfma_f32_16x16x32_bf16 v[94:97], v[70:73], v[212:215], v[94:97]
	v_mfma_f32_16x16x32_bf16 v[90:93], v[78:81], v[212:215], v[90:93]
	s_setprio 0
	s_setprio 1
	v_mfma_f32_16x16x32_bf16 v[134:137], v[166:169], v[182:185], 0
	v_mfma_f32_16x16x32_bf16 v[130:133], v[174:177], v[182:185], 0
	v_mfma_f32_16x16x32_bf16 v[118:121], v[166:169], v[190:193], 0
	v_mfma_f32_16x16x32_bf16 v[114:117], v[174:177], v[190:193], 0
	v_mfma_f32_16x16x32_bf16 v[102:105], v[166:169], v[198:201], 0
	v_mfma_f32_16x16x32_bf16 v[98:101], v[174:177], v[198:201], 0
	v_mfma_f32_16x16x32_bf16 v[86:89], v[166:169], v[208:211], 0
	v_mfma_f32_16x16x32_bf16 v[82:85], v[174:177], v[208:211], 0
	v_mfma_f32_16x16x32_bf16 v[134:137], v[170:173], v[186:189], v[134:137]
	v_mfma_f32_16x16x32_bf16 v[130:133], v[178:181], v[186:189], v[130:133]
	v_mfma_f32_16x16x32_bf16 v[118:121], v[170:173], v[194:197], v[118:121]
	v_mfma_f32_16x16x32_bf16 v[114:117], v[178:181], v[194:197], v[114:117]
	v_mfma_f32_16x16x32_bf16 v[102:105], v[170:173], v[202:205], v[102:105]
	v_mfma_f32_16x16x32_bf16 v[98:101], v[178:181], v[202:205], v[98:101]
	v_mfma_f32_16x16x32_bf16 v[86:89], v[170:173], v[212:215], v[86:89]
	v_mfma_f32_16x16x32_bf16 v[82:85], v[178:181], v[212:215], v[82:85]
	s_setprio 0
	s_barrier
	s_add_i32 s59, s59, s19
	s_add_u32 s98, s38, 0x80
	s_addc_u32 s99, s39, 0
	s_mov_b32 m0, s59
	ds_read_b128 v[182:185], v165 offset:16384
	ds_read_b128 v[186:189], v165 offset:17408
	ds_read_b128 v[190:193], v165 offset:18432
	ds_read_b128 v[194:197], v165 offset:19456
	ds_read_b128 v[198:201], v165 offset:20480
	ds_read_b128 v[202:205], v165 offset:21504
	ds_read_b128 v[208:211], v165 offset:22528
	ds_read_b128 v[212:215], v165 offset:23552
	global_load_lds_dwordx4 v148, s[38:39]
	s_add_i32 m0, s59, 0x2000
	s_add_u32 s60, s38, 0x80000
	s_addc_u32 s61, s39, 0
	s_add_i32 s59, s62, s19
	global_load_lds_dwordx4 v152, s[38:39]
	s_mov_b32 m0, s59
	s_add_u32 s100, s42, 0x80
	s_addc_u32 s101, s43, 0
	global_load_lds_dwordx4 v148, s[60:61]
	s_add_i32 m0, s59, 0x2000
	s_nop 0
	global_load_lds_dwordx4 v152, s[60:61]
	s_mov_b32 m0, s44
	s_nop 0
	global_load_lds_dwordx4 v146, s[42:43]
	s_waitcnt vmcnt(7)
	s_waitcnt lgkmcnt(0)
	s_barrier
; #define PG8_STAGE(bufoff, gbase, voff) do { _Pragma("unroll") for (int _i = 0; _i < 2; ++_i) \
;         __builtin_amdgcn_global_load_lds((const unsigned*)((const char*)(gbase) + (voff)[_i]), (PG8_LAS unsigned*)(lds + (bufoff) + ldsw + _i * 8192), 16, 0, 0); } while (0)
; #define PG8_LDA(dst, b, h) do { _Pragma("unroll") for (int m = 0; m < 4; ++m) _Pragma("unroll") for (int k = 0; k < 2; ++k) dst[m][k] = *(const PG8_LAS bf16x8*)(lds + PG8_SA(b, h) + aoff + m * 2048 + k * 1024); } while (0)
; #define PG8_LDB(dst, b, h) do { _Pragma("unroll") for (int n = 0; n < 2; ++n) _Pragma("unroll") for (int k = 0; k < 2; ++k) dst[n][k] = *(const PG8_LAS bf16x8*)(lds + PG8_SB(b, h) + boff + n * 2048 + k * 1024); } while (0)
; #define PG8_MMA(ai, bj, At, Bt) do { __builtin_amdgcn_s_setprio(1); _Pragma("unroll") for (int m = 0; m < 4; ++m) _Pragma("unroll") for (int n = 0; n < 2; ++n) _Pragma("unroll") for (int k = 0; k < 2; ++k) \
;         acc[ai][bj][m][n] = __builtin_amdgcn_mfma_f32_16x16x32_bf16(Bt[n][k], At[m][k], acc[ai][bj][m][n], 0, 0, 0); __builtin_amdgcn_s_setprio(0); } while (0)
; #define PG8_WAIT_V(n) asm volatile("s_waitcnt vmcnt(" #n ")" ::: "memory")
; #define PG8_WAIT_L(n) asm volatile("s_waitcnt lgkmcnt(" #n ")" ::: "memory")
; #define PG8_BAR __builtin_amdgcn_s_barrier()
; #define PG8_SCHED __builtin_amdgcn_sched_barrier(0)
; template <class Epi, class Sched, bool ALIGN_EPI = false, bool SP2 = false>
; __device__ __forceinline__ void gemm_phase(PG8_LAS unsigned char* lds, const Gemm g, const Sched& S, const Epi& E, const int tid_in) {
;     ...
;             PG8_WAIT_V(8); PG8_WAIT_L(0); PG8_BAR; PG8_MMA(1, 0, At, B0); PG8_MMA(1, 1, At, B1); PG8_BAR; PG8_SCHED;
;             PG8_LDB(B0, 1, 0); PG8_LDB(B1, 1, 1); PG8_SCHED; PG8_LDA(At, 1, 0); PG8_STAGE(PG8_SA(0, 1), a2 + hstep, voffA);
;             PG8_WAIT_V(8); PG8_WAIT_L(0); PG8_BAR; PG8_MMA(0, 0, At, B0); PG8_MMA(0, 1, At, B1); PG8_BAR; PG8_SCHED;
	s_setprio 1
	v_mfma_f32_16x16x32_bf16 v[62:65], v[66:69], v[182:185], 0
	v_mfma_f32_16x16x32_bf16 v[58:61], v[74:77], v[182:185], 0
	v_mfma_f32_16x16x32_bf16 v[46:49], v[66:69], v[190:193], 0
	v_mfma_f32_16x16x32_bf16 v[42:45], v[74:77], v[190:193], 0
	v_mfma_f32_16x16x32_bf16 v[30:33], v[66:69], v[198:201], 0
	v_mfma_f32_16x16x32_bf16 v[26:29], v[74:77], v[198:201], 0
	v_mfma_f32_16x16x32_bf16 v[12:15], v[66:69], v[208:211], 0
	v_mfma_f32_16x16x32_bf16 v[8:11], v[74:77], v[208:211], 0
	v_mfma_f32_16x16x32_bf16 v[62:65], v[70:73], v[186:189], v[62:65]
	v_mfma_f32_16x16x32_bf16 v[58:61], v[78:81], v[186:189], v[58:61]
	v_mfma_f32_16x16x32_bf16 v[46:49], v[70:73], v[194:197], v[46:49]
	v_mfma_f32_16x16x32_bf16 v[42:45], v[78:81], v[194:197], v[42:45]
	v_mfma_f32_16x16x32_bf16 v[30:33], v[70:73], v[202:205], v[30:33]
	v_mfma_f32_16x16x32_bf16 v[26:29], v[78:81], v[202:205], v[26:29]
	v_mfma_f32_16x16x32_bf16 v[12:15], v[70:73], v[212:215], v[12:15]
	v_mfma_f32_16x16x32_bf16 v[8:11], v[78:81], v[212:215], v[8:11]
	s_setprio 0
	s_setprio 1
	v_mfma_f32_16x16x32_bf16 v[54:57], v[166:169], v[182:185], 0
	v_mfma_f32_16x16x32_bf16 v[50:53], v[174:177], v[182:185], 0
	v_mfma_f32_16x16x32_bf16 v[38:41], v[166:169], v[190:193], 0
	v_mfma_f32_16x16x32_bf16 v[34:37], v[174:177], v[190:193], 0
	v_mfma_f32_16x16x32_bf16 v[22:25], v[166:169], v[198:201], 0
	v_mfma_f32_16x16x32_bf16 v[16:19], v[174:177], v[198:201], 0
	v_mfma_f32_16x16x32_bf16 v[4:7], v[166:169], v[208:211], 0
	v_mfma_f32_16x16x32_bf16 v[0:3], v[174:177], v[208:211], 0
	v_mfma_f32_16x16x32_bf16 v[54:57], v[170:173], v[186:189], v[54:57]
	v_mfma_f32_16x16x32_bf16 v[50:53], v[178:181], v[186:189], v[50:53]
	v_mfma_f32_16x16x32_bf16 v[38:41], v[170:173], v[194:197], v[38:41]
	v_mfma_f32_16x16x32_bf16 v[34:37], v[178:181], v[194:197], v[34:37]
	v_mfma_f32_16x16x32_bf16 v[22:25], v[170:173], v[202:205], v[22:25]
	v_mfma_f32_16x16x32_bf16 v[16:19], v[178:181], v[202:205], v[16:19]
	v_mfma_f32_16x16x32_bf16 v[4:7], v[170:173], v[212:215], v[4:7]
	v_mfma_f32_16x16x32_bf16 v[0:3], v[178:181], v[212:215], v[0:3]
	s_setprio 0
	s_barrier
	s_add_i32 s59, 0, 0x18000
	s_add_i32 s60, 0, 0x1c000
	v_add_u32_e32 v78, s59, v162
	v_add_u32_e32 v178, s60, v162
	ds_read_b128 v[66:69], v78
	ds_read_b128 v[70:73], v78 offset:1024
	ds_read_b128 v[74:77], v78 offset:2048
	ds_read_b128 v[78:81], v78 offset:3072
	ds_read_b128 v[166:169], v178
	ds_read_b128 v[170:173], v178 offset:1024
	ds_read_b128 v[174:177], v178 offset:2048
	ds_read_b128 v[178:181], v178 offset:3072
	s_mov_b32 m0, s45
	s_nop 0
	global_load_lds_dwordx4 v150, s[42:43]
	s_add_u32 s42, s42, 0x80000
	s_addc_u32 s43, s43, 0
	s_mov_b32 m0, s46
	ds_read_b128 v[182:185], v165 offset:32768
	ds_read_b128 v[186:189], v165 offset:33792
	ds_read_b128 v[190:193], v165 offset:34816
	ds_read_b128 v[194:197], v165 offset:35840
	ds_read_b128 v[198:201], v165 offset:36864
	ds_read_b128 v[202:205], v165 offset:37888
	ds_read_b128 v[208:211], v165 offset:38912
	ds_read_b128 v[212:215], v165 offset:39936
	global_load_lds_dwordx4 v146, s[42:43]
	s_mov_b32 m0, s47
	s_nop 0
	global_load_lds_dwordx4 v150, s[42:43]
	s_waitcnt vmcnt(8)
	s_waitcnt lgkmcnt(0)
	s_barrier
	s_setprio 1
	v_mfma_f32_16x16x32_bf16 v[142:145], v[66:69], v[182:185], v[142:145]
	v_mfma_f32_16x16x32_bf16 v[138:141], v[74:77], v[182:185], v[138:141]
	v_mfma_f32_16x16x32_bf16 v[126:129], v[66:69], v[190:193], v[126:129]
	v_mfma_f32_16x16x32_bf16 v[122:125], v[74:77], v[190:193], v[122:125]
	v_mfma_f32_16x16x32_bf16 v[110:113], v[66:69], v[198:201], v[110:113]
	v_mfma_f32_16x16x32_bf16 v[106:109], v[74:77], v[198:201], v[106:109]
	v_mfma_f32_16x16x32_bf16 v[94:97], v[66:69], v[208:211], v[94:97]
	v_mfma_f32_16x16x32_bf16 v[90:93], v[74:77], v[208:211], v[90:93]
	v_mfma_f32_16x16x32_bf16 v[142:145], v[70:73], v[186:189], v[142:145]
	v_mfma_f32_16x16x32_bf16 v[138:141], v[78:81], v[186:189], v[138:141]
	v_mfma_f32_16x16x32_bf16 v[126:129], v[70:73], v[194:197], v[126:129]
	v_mfma_f32_16x16x32_bf16 v[122:125], v[78:81], v[194:197], v[122:125]
	v_mfma_f32_16x16x32_bf16 v[110:113], v[70:73], v[202:205], v[110:113]
	v_mfma_f32_16x16x32_bf16 v[106:109], v[78:81], v[202:205], v[106:109]
	v_mfma_f32_16x16x32_bf16 v[94:97], v[70:73], v[212:215], v[94:97]
	v_mfma_f32_16x16x32_bf16 v[90:93], v[78:81], v[212:215], v[90:93]
	s_setprio 0
	s_setprio 1
	v_mfma_f32_16x16x32_bf16 v[134:137], v[166:169], v[182:185], v[134:137]
	v_mfma_f32_16x16x32_bf16 v[130:133], v[174:177], v[182:185], v[130:133]
	v_mfma_f32_16x16x32_bf16 v[118:121], v[166:169], v[190:193], v[118:121]
	v_mfma_f32_16x16x32_bf16 v[114:117], v[174:177], v[190:193], v[114:117]
	v_mfma_f32_16x16x32_bf16 v[102:105], v[166:169], v[198:201], v[102:105]
	v_mfma_f32_16x16x32_bf16 v[98:101], v[174:177], v[198:201], v[98:101]
	v_mfma_f32_16x16x32_bf16 v[86:89], v[166:169], v[208:211], v[86:89]
	v_mfma_f32_16x16x32_bf16 v[82:85], v[174:177], v[208:211], v[82:85]
	v_mfma_f32_16x16x32_bf16 v[134:137], v[170:173], v[186:189], v[134:137]
	v_mfma_f32_16x16x32_bf16 v[130:133], v[178:181], v[186:189], v[130:133]
	v_mfma_f32_16x16x32_bf16 v[118:121], v[170:173], v[194:197], v[118:121]
	v_mfma_f32_16x16x32_bf16 v[114:117], v[178:181], v[194:197], v[114:117]
	v_mfma_f32_16x16x32_bf16 v[102:105], v[170:173], v[202:205], v[102:105]
	v_mfma_f32_16x16x32_bf16 v[98:101], v[178:181], v[202:205], v[98:101]
	v_mfma_f32_16x16x32_bf16 v[86:89], v[170:173], v[212:215], v[86:89]
	v_mfma_f32_16x16x32_bf16 v[82:85], v[178:181], v[212:215], v[82:85]
	s_setprio 0
	s_barrier
; #define PG8_STAGE(bufoff, gbase, voff) do { _Pragma("unroll") for (int _i = 0; _i < 2; ++_i) \
;         __builtin_amdgcn_global_load_lds((const unsigned*)((const char*)(gbase) + (voff)[_i]), (PG8_LAS unsigned*)(lds + (bufoff) + ldsw + _i * 8192), 16, 0, 0); } while (0)
; #define PG8_LDA(dst, b, h) do { _Pragma("unroll") for (int m = 0; m < 4; ++m) _Pragma("unroll") for (int k = 0; k < 2; ++k) dst[m][k] = *(const PG8_LAS bf16x8*)(lds + PG8_SA(b, h) + aoff + m * 2048 + k * 1024); } while (0)
; #define PG8_MMA(ai, bj, At, Bt) do { __builtin_amdgcn_s_setprio(1); _Pragma("unroll") for (int m = 0; m < 4; ++m) _Pragma("unroll") for (int n = 0; n < 2; ++n) _Pragma("unroll") for (int k = 0; k < 2; ++k) \
;         acc[ai][bj][m][n] = __builtin_amdgcn_mfma_f32_16x16x32_bf16(Bt[n][k], At[m][k], acc[ai][bj][m][n], 0, 0, 0); __builtin_amdgcn_s_setprio(0); } while (0)
; #define PG8_WAIT_V(n) asm volatile("s_waitcnt vmcnt(" #n ")" ::: "memory")
; #define PG8_WAIT_L(n) asm volatile("s_waitcnt lgkmcnt(" #n ")" ::: "memory")
; #define PG8_BAR __builtin_amdgcn_s_barrier()
; #define PG8_SCHED __builtin_amdgcn_sched_barrier(0)
; template <class Epi, class Sched, bool ALIGN_EPI = false, bool SP2 = false>
; __device__ __forceinline__ void gemm_phase(PG8_LAS unsigned char* lds, const Gemm g, const Sched& S, const Epi& E, const int tid_in) {
;     ...
;             PG8_LDA(At, 1, 1); PG8_STAGE(PG8_SB(1, 0), b3, voffB); PG8_STAGE(PG8_SB(1, 1), b3 + hstep, voffB); PG8_STAGE(PG8_SA(1, 0), a3, voffA);
;             PG8_WAIT_V(8); PG8_WAIT_L(0); PG8_BAR; PG8_MMA(1, 0, At, B0); PG8_MMA(1, 1, At, B1); PG8_BAR; PG8_SCHED;
	s_add_i32 s42, s59, s19
	s_mov_b32 m0, s42
	ds_read_b128 v[182:185], v165 offset:49152
	ds_read_b128 v[186:189], v165 offset:50176
	ds_read_b128 v[190:193], v165 offset:51200
	ds_read_b128 v[194:197], v165 offset:52224
	ds_read_b128 v[198:201], v165 offset:53248
	ds_read_b128 v[202:205], v165 offset:54272
	ds_read_b128 v[208:211], v165 offset:55296
	ds_read_b128 v[212:215], v165 offset:56320
	global_load_lds_dwordx4 v148, s[98:99]
	s_add_i32 m0, s42, 0x2000
	s_add_u32 s38, s38, 0x80080
	s_addc_u32 s39, s39, 0
	s_add_i32 s42, s60, s19
	global_load_lds_dwordx4 v152, s[98:99]
	s_mov_b32 m0, s42
	s_nop 0
	global_load_lds_dwordx4 v148, s[38:39]
	s_add_i32 m0, s42, 0x2000
	s_nop 0
	global_load_lds_dwordx4 v152, s[38:39]
	s_mov_b32 m0, s48
	s_nop 0
	global_load_lds_dwordx4 v146, s[100:101]
	s_waitcnt vmcnt(7)
	s_waitcnt lgkmcnt(0)
	s_barrier
	s_setprio 1
	v_mfma_f32_16x16x32_bf16 v[62:65], v[66:69], v[182:185], v[62:65]
	v_mfma_f32_16x16x32_bf16 v[58:61], v[74:77], v[182:185], v[58:61]
	v_mfma_f32_16x16x32_bf16 v[46:49], v[66:69], v[190:193], v[46:49]
	v_mfma_f32_16x16x32_bf16 v[42:45], v[74:77], v[190:193], v[42:45]
	v_mfma_f32_16x16x32_bf16 v[30:33], v[66:69], v[198:201], v[30:33]
	v_mfma_f32_16x16x32_bf16 v[26:29], v[74:77], v[198:201], v[26:29]
	v_mfma_f32_16x16x32_bf16 v[12:15], v[66:69], v[208:211], v[12:15]
	v_mfma_f32_16x16x32_bf16 v[8:11], v[74:77], v[208:211], v[8:11]
	v_mfma_f32_16x16x32_bf16 v[62:65], v[70:73], v[186:189], v[62:65]
	v_mfma_f32_16x16x32_bf16 v[58:61], v[78:81], v[186:189], v[58:61]
	v_mfma_f32_16x16x32_bf16 v[46:49], v[70:73], v[194:197], v[46:49]
	v_mfma_f32_16x16x32_bf16 v[42:45], v[78:81], v[194:197], v[42:45]
	v_mfma_f32_16x16x32_bf16 v[30:33], v[70:73], v[202:205], v[30:33]
	v_mfma_f32_16x16x32_bf16 v[26:29], v[78:81], v[202:205], v[26:29]
	v_mfma_f32_16x16x32_bf16 v[12:15], v[70:73], v[212:215], v[12:15]
	v_mfma_f32_16x16x32_bf16 v[8:11], v[78:81], v[212:215], v[8:11]
	s_setprio 0
	s_setprio 1
	v_mfma_f32_16x16x32_bf16 v[54:57], v[166:169], v[182:185], v[54:57]
	v_mfma_f32_16x16x32_bf16 v[50:53], v[174:177], v[182:185], v[50:53]
	v_mfma_f32_16x16x32_bf16 v[38:41], v[166:169], v[190:193], v[38:41]
	v_mfma_f32_16x16x32_bf16 v[34:37], v[174:177], v[190:193], v[34:37]
	v_mfma_f32_16x16x32_bf16 v[22:25], v[166:169], v[198:201], v[22:25]
	v_mfma_f32_16x16x32_bf16 v[16:19], v[174:177], v[198:201], v[16:19]
	v_mfma_f32_16x16x32_bf16 v[4:7], v[166:169], v[208:211], v[4:7]
	v_mfma_f32_16x16x32_bf16 v[0:3], v[174:177], v[208:211], v[0:3]
	v_mfma_f32_16x16x32_bf16 v[54:57], v[170:173], v[186:189], v[54:57]
	v_mfma_f32_16x16x32_bf16 v[50:53], v[178:181], v[186:189], v[50:53]
	v_mfma_f32_16x16x32_bf16 v[38:41], v[170:173], v[194:197], v[38:41]
	v_mfma_f32_16x16x32_bf16 v[34:37], v[178:181], v[194:197], v[34:37]
	v_mfma_f32_16x16x32_bf16 v[22:25], v[170:173], v[202:205], v[22:25]
	v_mfma_f32_16x16x32_bf16 v[16:19], v[178:181], v[202:205], v[16:19]
	v_mfma_f32_16x16x32_bf16 v[4:7], v[170:173], v[212:215], v[4:7]
	v_mfma_f32_16x16x32_bf16 v[0:3], v[178:181], v[212:215], v[0:3]
	s_setprio 0
	s_barrier
	s_add_i32 s58, s58, 2
	s_add_u32 s34, s34, 0x100
	s_addc_u32 s35, s35, 0
	s_add_u32 s56, s56, 0x100
	s_addc_u32 s57, s57, 0
	s_cmp_gt_u32 s58, 29

; #define PG8_STAGE(bufoff, gbase, voff) do { _Pragma("unroll") for (int _i = 0; _i < 2; ++_i) \
;         __builtin_amdgcn_global_load_lds((const unsigned*)((const char*)(gbase) + (voff)[_i]), (PG8_LAS unsigned*)(lds + (bufoff) + ldsw + _i * 8192), 16, 0, 0); } while (0)
; #define PG8_LDA(dst, b, h) do { _Pragma("unroll") for (int m = 0; m < 4; ++m) _Pragma("unroll") for (int k = 0; k < 2; ++k) dst[m][k] = *(const PG8_LAS bf16x8*)(lds + PG8_SA(b, h) + aoff + m * 2048 + k * 1024); } while (0)
; #define PG8_LDB(dst, b, h) do { _Pragma("unroll") for (int n = 0; n < 2; ++n) _Pragma("unroll") for (int k = 0; k < 2; ++k) dst[n][k] = *(const PG8_LAS bf16x8*)(lds + PG8_SB(b, h) + boff + n * 2048 + k * 1024); } while (0)
; #define PG8_WAIT_V(n) asm volatile("s_waitcnt vmcnt(" #n ")" ::: "memory")
; #define PG8_WAIT_L(n) asm volatile("s_waitcnt lgkmcnt(" #n ")" ::: "memory")
; #define PG8_BAR __builtin_amdgcn_s_barrier()
; #define PG8_SCHED __builtin_amdgcn_sched_barrier(0)
; template <class Epi, class Sched, bool ALIGN_EPI = false, bool SP2 = false>
; __device__ __forceinline__ void gemm_phase(PG8_LAS unsigned char* lds, const Gemm g, const Sched& S, const Epi& E, const int tid_in) {
;     ...
;             const bool last = (t == nt - 2);
;             const char* a1 = cA + (size_t)(t + 1) * kstep;
;             const char* a2 = last ? nA : cA + (size_t)(t + 2) * kstep; const char* b2 = last ? nB : cB + (size_t)(t + 2) * kstep;
;             const char* a3 = a2 + kstep; const char* b3 = b2 + kstep;
;             if (last && has_next) S.a_ready(nxt);
;             if constexpr (SP2) {
;             PG8_LDB(B0, 0, 0); PG8_LDB(B1, 0, 1); PG8_SCHED; PG8_LDA(At, 0, 0); PG8_STAGE(PG8_SA(1, 1), a1 + hstep, voffA);
;             PG8_WAIT_V(8); PG8_WAIT_L(0); PG8_BAR; PG8_MMA(0, 0, At, B0); PG8_MMA(0, 1, At, B1); PG8_BAR; PG8_SCHED;
;             PG8_LDA(At, 0, 1); PG8_STAGE(PG8_SB(0, 0), b2, voffB); PG8_STAGE(PG8_SB(0, 1), b2 + hstep, voffB); PG8_STAGE(PG8_SA(0, 0), a2, voffA);
;             PG8_WAIT_V(8); PG8_WAIT_L(0); PG8_BAR; PG8_MMA(1, 0, At, B0); PG8_MMA(1, 1, At, B1); PG8_BAR; PG8_SCHED;
;     ...
;         for (int a = 0; a < 2; ++a)
; #pragma unroll
;             for (int b = 0; b < 2; ++b)
; #pragma unroll
;                 for (int m = 0; m < 4; ++m)
; #pragma unroll
;                     for (int n = 0; n < 2; ++n) acc[a][b][m][n] = (f32x4){0.f, 0.f, 0.f, 0.f};
.LBB0_1036:
	s_ashr_i32 s57, s56, 31
	s_lshl_b64 s[34:35], s[56:57], 20
	s_add_u32 s36, s10, s34
	s_addc_u32 s37, s19, s35
	s_and_b64 s[34:35], exec, s[6:7]
	v_readlane_b32 s34, v254, 36
	v_readlane_b32 s35, v254, 37
	s_cselect_b32 s38, s29, s37
	s_cselect_b32 s39, s28, s36
	s_mov_b32 s40, s34
	s_ashr_i32 s41, s34, 31
	v_writelane_b32 v254, s34, 36
	v_mov_b32_e32 v0, 0
	s_mov_b32 vcc_lo, -2
	v_writelane_b32 v254, s35, 37
	s_lshl_b64 s[34:35], s[40:41], 20
	s_add_u32 s60, s62, s34
	s_addc_u32 s61, s63, s35
	s_and_b64 s[34:35], exec, s[6:7]
	s_cselect_b32 s40, s31, s61
	s_cselect_b32 s41, s30, s60
	s_add_u32 s28, s28, 0x80080
	s_addc_u32 s29, s29, 0
	s_add_u32 s57, s30, 0x100
	s_addc_u32 s92, s31, 0
	s_mov_b32 m0, s76
	s_nop 0
	global_load_lds_dwordx4 v214, s[100:101]
	s_add_u32 s30, s28, 0xfff80080
	s_addc_u32 s31, s29, -1
	s_add_i32 s46, 0, 0x10000
	s_cmp_eq_u32 vcc_lo, 28
	s_cselect_b32 s35, s38, s31
	s_cselect_b32 s34, s39, s30
	s_cselect_b32 s31, s40, s92
	s_cselect_b32 s30, s41, s57
	s_add_i32 vcc_hi, 0, 0x14000
	v_add_u32_e32 v142, s46, v21
	v_add_u32_e32 v158, vcc_hi, v21
	ds_read_b128 v[130:133], v142
	ds_read_b128 v[134:137], v142 offset:1024
	ds_read_b128 v[138:141], v142 offset:2048
	ds_read_b128 v[142:145], v142 offset:3072
	ds_read_b128 v[146:149], v158
	ds_read_b128 v[150:153], v158 offset:1024
	ds_read_b128 v[154:157], v158 offset:2048
	ds_read_b128 v[158:161], v158 offset:3072
	s_add_i32 m0, s64, 0xc000
	ds_read_b128 v[162:165], v208
	ds_read_b128 v[166:169], v208 offset:1024
	ds_read_b128 v[170:173], v208 offset:2048
	ds_read_b128 v[174:177], v208 offset:3072
	ds_read_b128 v[178:181], v208 offset:4096
	ds_read_b128 v[182:185], v208 offset:5120
	ds_read_b128 v[186:189], v208 offset:6144
	ds_read_b128 v[190:193], v208 offset:7168
	global_load_lds_dwordx4 v218, s[28:29]
	s_add_i32 m0, s64, 0xe000
	s_nop 0
	global_load_lds_dwordx4 v220, s[28:29]
	s_waitcnt vmcnt(8)
	s_waitcnt lgkmcnt(0)
	s_barrier
	s_setprio 1
	v_mfma_f32_16x16x32_bf16 v[126:129], v[130:133], v[162:165], 0
	v_mfma_f32_16x16x32_bf16 v[122:125], v[138:141], v[162:165], 0
	v_mfma_f32_16x16x32_bf16 v[110:113], v[130:133], v[170:173], 0
	v_mfma_f32_16x16x32_bf16 v[106:109], v[138:141], v[170:173], 0
	v_mfma_f32_16x16x32_bf16 v[94:97], v[130:133], v[178:181], 0
	v_mfma_f32_16x16x32_bf16 v[90:93], v[138:141], v[178:181], 0
	v_mfma_f32_16x16x32_bf16 v[78:81], v[130:133], v[186:189], 0
	v_mfma_f32_16x16x32_bf16 v[74:77], v[138:141], v[186:189], 0
	v_mfma_f32_16x16x32_bf16 v[126:129], v[134:137], v[166:169], v[126:129]
	v_mfma_f32_16x16x32_bf16 v[122:125], v[142:145], v[166:169], v[122:125]
	v_mfma_f32_16x16x32_bf16 v[110:113], v[134:137], v[174:177], v[110:113]
	v_mfma_f32_16x16x32_bf16 v[106:109], v[142:145], v[174:177], v[106:109]
	v_mfma_f32_16x16x32_bf16 v[94:97], v[134:137], v[182:185], v[94:97]
	v_mfma_f32_16x16x32_bf16 v[90:93], v[142:145], v[182:185], v[90:93]
	v_mfma_f32_16x16x32_bf16 v[78:81], v[134:137], v[190:193], v[78:81]
	v_mfma_f32_16x16x32_bf16 v[74:77], v[142:145], v[190:193], v[74:77]
	s_setprio 0
	s_setprio 1
	v_mfma_f32_16x16x32_bf16 v[118:121], v[146:149], v[162:165], 0
	v_mfma_f32_16x16x32_bf16 v[114:117], v[154:157], v[162:165], 0
	v_mfma_f32_16x16x32_bf16 v[102:105], v[146:149], v[170:173], 0
	v_mfma_f32_16x16x32_bf16 v[98:101], v[154:157], v[170:173], 0
	v_mfma_f32_16x16x32_bf16 v[86:89], v[146:149], v[178:181], 0
	v_mfma_f32_16x16x32_bf16 v[82:85], v[154:157], v[178:181], 0
	v_mfma_f32_16x16x32_bf16 v[70:73], v[146:149], v[186:189], 0
	v_mfma_f32_16x16x32_bf16 v[66:69], v[154:157], v[186:189], 0
	v_mfma_f32_16x16x32_bf16 v[118:121], v[150:153], v[166:169], v[118:121]
	v_mfma_f32_16x16x32_bf16 v[114:117], v[158:161], v[166:169], v[114:117]
	v_mfma_f32_16x16x32_bf16 v[102:105], v[150:153], v[174:177], v[102:105]
	v_mfma_f32_16x16x32_bf16 v[98:101], v[158:161], v[174:177], v[98:101]
	v_mfma_f32_16x16x32_bf16 v[86:89], v[150:153], v[182:185], v[86:89]
	v_mfma_f32_16x16x32_bf16 v[82:85], v[158:161], v[182:185], v[82:85]
	v_mfma_f32_16x16x32_bf16 v[70:73], v[150:153], v[190:193], v[70:73]
	v_mfma_f32_16x16x32_bf16 v[66:69], v[158:161], v[190:193], v[66:69]
	s_setprio 0
	s_barrier
	s_add_i32 s46, s46, s8
	s_add_u32 s98, s30, 0x80
	s_addc_u32 s99, s31, 0
	s_mov_b32 m0, s46
	ds_read_b128 v[162:165], v208 offset:16384
	ds_read_b128 v[166:169], v208 offset:17408
	ds_read_b128 v[170:173], v208 offset:18432
	ds_read_b128 v[174:177], v208 offset:19456
	ds_read_b128 v[178:181], v208 offset:20480
	ds_read_b128 v[182:185], v208 offset:21504
	ds_read_b128 v[186:189], v208 offset:22528
	ds_read_b128 v[190:193], v208 offset:23552
	global_load_lds_dwordx4 v204, s[30:31]
	s_add_i32 m0, s46, 0x2000
	s_add_u32 s46, s30, 0x80000
	s_addc_u32 s47, s31, 0
	s_add_i32 vcc_hi, vcc_hi, s8
	global_load_lds_dwordx4 v216, s[30:31]
	s_mov_b32 m0, vcc_hi
	s_add_u32 s100, s34, 0x80
	s_addc_u32 s101, s35, 0
	global_load_lds_dwordx4 v204, s[46:47]
	s_add_i32 m0, vcc_hi, 0x2000
	s_nop 0
	global_load_lds_dwordx4 v216, s[46:47]
	s_mov_b32 m0, s64
	s_nop 0
	global_load_lds_dwordx4 v202, s[34:35]
	s_waitcnt vmcnt(7)
	s_waitcnt lgkmcnt(0)
	s_barrier
; #define PG8_STAGE(bufoff, gbase, voff) do { _Pragma("unroll") for (int _i = 0; _i < 2; ++_i) \
;         __builtin_amdgcn_global_load_lds((const unsigned*)((const char*)(gbase) + (voff)[_i]), (PG8_LAS unsigned*)(lds + (bufoff) + ldsw + _i * 8192), 16, 0, 0); } while (0)
; #define PG8_LDA(dst, b, h) do { _Pragma("unroll") for (int m = 0; m < 4; ++m) _Pragma("unroll") for (int k = 0; k < 2; ++k) dst[m][k] = *(const PG8_LAS bf16x8*)(lds + PG8_SA(b, h) + aoff + m * 2048 + k * 1024); } while (0)
; #define PG8_LDB(dst, b, h) do { _Pragma("unroll") for (int n = 0; n < 2; ++n) _Pragma("unroll") for (int k = 0; k < 2; ++k) dst[n][k] = *(const PG8_LAS bf16x8*)(lds + PG8_SB(b, h) + boff + n * 2048 + k * 1024); } while (0)
; #define PG8_MMA(ai, bj, At, Bt) do { __builtin_amdgcn_s_setprio(1); _Pragma("unroll") for (int m = 0; m < 4; ++m) _Pragma("unroll") for (int n = 0; n < 2; ++n) _Pragma("unroll") for (int k = 0; k < 2; ++k) \
;         acc[ai][bj][m][n] = __builtin_amdgcn_mfma_f32_16x16x32_bf16(Bt[n][k], At[m][k], acc[ai][bj][m][n], 0, 0, 0); __builtin_amdgcn_s_setprio(0); } while (0)
; #define PG8_WAIT_V(n) asm volatile("s_waitcnt vmcnt(" #n ")" ::: "memory")
; #define PG8_WAIT_L(n) asm volatile("s_waitcnt lgkmcnt(" #n ")" ::: "memory")
; #define PG8_BAR __builtin_amdgcn_s_barrier()
; #define PG8_SCHED __builtin_amdgcn_sched_barrier(0)
; template <class Epi, class Sched, bool ALIGN_EPI = false, bool SP2 = false>
; __device__ __forceinline__ void gemm_phase(PG8_LAS unsigned char* lds, const Gemm g, const Sched& S, const Epi& E, const int tid_in) {
;     ...
;             PG8_WAIT_V(8); PG8_WAIT_L(0); PG8_BAR; PG8_MMA(1, 0, At, B0); PG8_MMA(1, 1, At, B1); PG8_BAR; PG8_SCHED;
;             PG8_LDB(B0, 1, 0); PG8_LDB(B1, 1, 1); PG8_SCHED; PG8_LDA(At, 1, 0); PG8_STAGE(PG8_SA(0, 1), a2 + hstep, voffA);
;             PG8_WAIT_V(8); PG8_WAIT_L(0); PG8_BAR; PG8_MMA(0, 0, At, B0); PG8_MMA(0, 1, At, B1); PG8_BAR; PG8_SCHED;
	s_setprio 1
	v_mfma_f32_16x16x32_bf16 v[62:65], v[130:133], v[162:165], 0
	v_mfma_f32_16x16x32_bf16 v[58:61], v[138:141], v[162:165], 0
	v_mfma_f32_16x16x32_bf16 v[46:49], v[130:133], v[170:173], 0
	v_mfma_f32_16x16x32_bf16 v[42:45], v[138:141], v[170:173], 0
	v_mfma_f32_16x16x32_bf16 v[30:33], v[130:133], v[178:181], 0
	v_mfma_f32_16x16x32_bf16 v[26:29], v[138:141], v[178:181], 0
	v_mfma_f32_16x16x32_bf16 v[12:15], v[130:133], v[186:189], 0
	v_mfma_f32_16x16x32_bf16 v[8:11], v[138:141], v[186:189], 0
	v_mfma_f32_16x16x32_bf16 v[62:65], v[134:137], v[166:169], v[62:65]
	v_mfma_f32_16x16x32_bf16 v[58:61], v[142:145], v[166:169], v[58:61]
	v_mfma_f32_16x16x32_bf16 v[46:49], v[134:137], v[174:177], v[46:49]
	v_mfma_f32_16x16x32_bf16 v[42:45], v[142:145], v[174:177], v[42:45]
	v_mfma_f32_16x16x32_bf16 v[30:33], v[134:137], v[182:185], v[30:33]
	v_mfma_f32_16x16x32_bf16 v[26:29], v[142:145], v[182:185], v[26:29]
	v_mfma_f32_16x16x32_bf16 v[12:15], v[134:137], v[190:193], v[12:15]
	v_mfma_f32_16x16x32_bf16 v[8:11], v[142:145], v[190:193], v[8:11]
	s_setprio 0
	s_setprio 1
	v_mfma_f32_16x16x32_bf16 v[54:57], v[146:149], v[162:165], 0
	v_mfma_f32_16x16x32_bf16 v[50:53], v[154:157], v[162:165], 0
	v_mfma_f32_16x16x32_bf16 v[38:41], v[146:149], v[170:173], 0
	v_mfma_f32_16x16x32_bf16 v[34:37], v[154:157], v[170:173], 0
	v_mfma_f32_16x16x32_bf16 v[22:25], v[146:149], v[178:181], 0
	v_mfma_f32_16x16x32_bf16 v[16:19], v[154:157], v[178:181], 0
	v_mfma_f32_16x16x32_bf16 v[4:7], v[146:149], v[186:189], 0
	v_mfma_f32_16x16x32_bf16 v[0:3], v[154:157], v[186:189], 0
	v_mfma_f32_16x16x32_bf16 v[54:57], v[150:153], v[166:169], v[54:57]
	v_mfma_f32_16x16x32_bf16 v[50:53], v[158:161], v[166:169], v[50:53]
	v_mfma_f32_16x16x32_bf16 v[38:41], v[150:153], v[174:177], v[38:41]
	v_mfma_f32_16x16x32_bf16 v[34:37], v[158:161], v[174:177], v[34:37]
	v_mfma_f32_16x16x32_bf16 v[22:25], v[150:153], v[182:185], v[22:25]
	v_mfma_f32_16x16x32_bf16 v[16:19], v[158:161], v[182:185], v[16:19]
	v_mfma_f32_16x16x32_bf16 v[4:7], v[150:153], v[190:193], v[4:7]
	v_mfma_f32_16x16x32_bf16 v[0:3], v[158:161], v[190:193], v[0:3]
	s_setprio 0
	s_barrier
	s_add_i32 s46, 0, 0x18000
	s_add_i32 s47, 0, 0x1c000
	v_add_u32_e32 v142, s46, v21
	v_add_u32_e32 v158, s47, v21
	ds_read_b128 v[130:133], v142
	ds_read_b128 v[134:137], v142 offset:1024
	ds_read_b128 v[138:141], v142 offset:2048
	ds_read_b128 v[142:145], v142 offset:3072
	ds_read_b128 v[146:149], v158
	ds_read_b128 v[150:153], v158 offset:1024
	ds_read_b128 v[154:157], v158 offset:2048
	ds_read_b128 v[158:161], v158 offset:3072
	s_mov_b32 m0, s65
	s_nop 0
	global_load_lds_dwordx4 v214, s[34:35]
	s_add_u32 s34, s34, 0x80000
	s_addc_u32 s35, s35, 0
	s_mov_b32 m0, s66
	ds_read_b128 v[162:165], v208 offset:32768
	ds_read_b128 v[166:169], v208 offset:33792
	ds_read_b128 v[170:173], v208 offset:34816
	ds_read_b128 v[174:177], v208 offset:35840
	ds_read_b128 v[178:181], v208 offset:36864
	ds_read_b128 v[182:185], v208 offset:37888
	ds_read_b128 v[186:189], v208 offset:38912
	ds_read_b128 v[190:193], v208 offset:39936
	global_load_lds_dwordx4 v202, s[34:35]
	s_mov_b32 m0, s67
	s_nop 0
	global_load_lds_dwordx4 v214, s[34:35]
	s_waitcnt vmcnt(8)
	s_waitcnt lgkmcnt(0)
	s_barrier
	s_setprio 1
	v_mfma_f32_16x16x32_bf16 v[126:129], v[130:133], v[162:165], v[126:129]
	v_mfma_f32_16x16x32_bf16 v[122:125], v[138:141], v[162:165], v[122:125]
	v_mfma_f32_16x16x32_bf16 v[110:113], v[130:133], v[170:173], v[110:113]
	v_mfma_f32_16x16x32_bf16 v[106:109], v[138:141], v[170:173], v[106:109]
	v_mfma_f32_16x16x32_bf16 v[94:97], v[130:133], v[178:181], v[94:97]
	v_mfma_f32_16x16x32_bf16 v[90:93], v[138:141], v[178:181], v[90:93]
	v_mfma_f32_16x16x32_bf16 v[78:81], v[130:133], v[186:189], v[78:81]
	v_mfma_f32_16x16x32_bf16 v[74:77], v[138:141], v[186:189], v[74:77]
	v_mfma_f32_16x16x32_bf16 v[126:129], v[134:137], v[166:169], v[126:129]
	v_mfma_f32_16x16x32_bf16 v[122:125], v[142:145], v[166:169], v[122:125]
	v_mfma_f32_16x16x32_bf16 v[110:113], v[134:137], v[174:177], v[110:113]
	v_mfma_f32_16x16x32_bf16 v[106:109], v[142:145], v[174:177], v[106:109]
	v_mfma_f32_16x16x32_bf16 v[94:97], v[134:137], v[182:185], v[94:97]
	v_mfma_f32_16x16x32_bf16 v[90:93], v[142:145], v[182:185], v[90:93]
	v_mfma_f32_16x16x32_bf16 v[78:81], v[134:137], v[190:193], v[78:81]
	v_mfma_f32_16x16x32_bf16 v[74:77], v[142:145], v[190:193], v[74:77]
	s_setprio 0
	s_setprio 1
	v_mfma_f32_16x16x32_bf16 v[118:121], v[146:149], v[162:165], v[118:121]
	v_mfma_f32_16x16x32_bf16 v[114:117], v[154:157], v[162:165], v[114:117]
	v_mfma_f32_16x16x32_bf16 v[102:105], v[146:149], v[170:173], v[102:105]
	v_mfma_f32_16x16x32_bf16 v[98:101], v[154:157], v[170:173], v[98:101]
	v_mfma_f32_16x16x32_bf16 v[86:89], v[146:149], v[178:181], v[86:89]
	v_mfma_f32_16x16x32_bf16 v[82:85], v[154:157], v[178:181], v[82:85]
	v_mfma_f32_16x16x32_bf16 v[70:73], v[146:149], v[186:189], v[70:73]
	v_mfma_f32_16x16x32_bf16 v[66:69], v[154:157], v[186:189], v[66:69]
	v_mfma_f32_16x16x32_bf16 v[118:121], v[150:153], v[166:169], v[118:121]
	v_mfma_f32_16x16x32_bf16 v[114:117], v[158:161], v[166:169], v[114:117]
	v_mfma_f32_16x16x32_bf16 v[102:105], v[150:153], v[174:177], v[102:105]
	v_mfma_f32_16x16x32_bf16 v[98:101], v[158:161], v[174:177], v[98:101]
	v_mfma_f32_16x16x32_bf16 v[86:89], v[150:153], v[182:185], v[86:89]
	v_mfma_f32_16x16x32_bf16 v[82:85], v[158:161], v[182:185], v[82:85]
	v_mfma_f32_16x16x32_bf16 v[70:73], v[150:153], v[190:193], v[70:73]
	v_mfma_f32_16x16x32_bf16 v[66:69], v[158:161], v[190:193], v[66:69]
	s_setprio 0
	s_barrier
; #define PG8_STAGE(bufoff, gbase, voff) do { _Pragma("unroll") for (int _i = 0; _i < 2; ++_i) \
;         __builtin_amdgcn_global_load_lds((const unsigned*)((const char*)(gbase) + (voff)[_i]), (PG8_LAS unsigned*)(lds + (bufoff) + ldsw + _i * 8192), 16, 0, 0); } while (0)
; #define PG8_LDA(dst, b, h) do { _Pragma("unroll") for (int m = 0; m < 4; ++m) _Pragma("unroll") for (int k = 0; k < 2; ++k) dst[m][k] = *(const PG8_LAS bf16x8*)(lds + PG8_SA(b, h) + aoff + m * 2048 + k * 1024); } while (0)
; #define PG8_MMA(ai, bj, At, Bt) do { __builtin_amdgcn_s_setprio(1); _Pragma("unroll") for (int m = 0; m < 4; ++m) _Pragma("unroll") for (int n = 0; n < 2; ++n) _Pragma("unroll") for (int k = 0; k < 2; ++k) \
;         acc[ai][bj][m][n] = __builtin_amdgcn_mfma_f32_16x16x32_bf16(Bt[n][k], At[m][k], acc[ai][bj][m][n], 0, 0, 0); __builtin_amdgcn_s_setprio(0); } while (0)
; #define PG8_WAIT_V(n) asm volatile("s_waitcnt vmcnt(" #n ")" ::: "memory")
; #define PG8_WAIT_L(n) asm volatile("s_waitcnt lgkmcnt(" #n ")" ::: "memory")
; #define PG8_BAR __builtin_amdgcn_s_barrier()
; #define PG8_SCHED __builtin_amdgcn_sched_barrier(0)
; template <class Epi, class Sched, bool ALIGN_EPI = false, bool SP2 = false>
; __device__ __forceinline__ void gemm_phase(PG8_LAS unsigned char* lds, const Gemm g, const Sched& S, const Epi& E, const int tid_in) {
;     ...
;             PG8_LDA(At, 1, 1); PG8_STAGE(PG8_SB(1, 0), b3, voffB); PG8_STAGE(PG8_SB(1, 1), b3 + hstep, voffB); PG8_STAGE(PG8_SA(1, 0), a3, voffA);
;             PG8_WAIT_V(8); PG8_WAIT_L(0); PG8_BAR; PG8_MMA(1, 0, At, B0); PG8_MMA(1, 1, At, B1); PG8_BAR; PG8_SCHED;
	s_add_i32 s34, s46, s8
	s_mov_b32 m0, s34
	ds_read_b128 v[162:165], v208 offset:49152
	ds_read_b128 v[166:169], v208 offset:50176
	ds_read_b128 v[170:173], v208 offset:51200
	ds_read_b128 v[174:177], v208 offset:52224
	ds_read_b128 v[178:181], v208 offset:53248
	ds_read_b128 v[182:185], v208 offset:54272
	ds_read_b128 v[186:189], v208 offset:55296
	ds_read_b128 v[190:193], v208 offset:56320
	global_load_lds_dwordx4 v204, s[98:99]
	s_add_i32 m0, s34, 0x2000
	s_add_u32 s30, s30, 0x80080
	s_addc_u32 s31, s31, 0
	s_add_i32 s34, s47, s8
	global_load_lds_dwordx4 v216, s[98:99]
	s_mov_b32 m0, s34
	s_nop 0
	global_load_lds_dwordx4 v204, s[30:31]
	s_add_i32 m0, s34, 0x2000
	s_nop 0
	global_load_lds_dwordx4 v216, s[30:31]
	s_mov_b32 m0, s75
	s_nop 0
	global_load_lds_dwordx4 v202, s[100:101]
	s_waitcnt vmcnt(7)
	s_waitcnt lgkmcnt(0)
	s_barrier
	s_setprio 1
	v_mfma_f32_16x16x32_bf16 v[62:65], v[130:133], v[162:165], v[62:65]
	v_mfma_f32_16x16x32_bf16 v[58:61], v[138:141], v[162:165], v[58:61]
	v_mfma_f32_16x16x32_bf16 v[46:49], v[130:133], v[170:173], v[46:49]
	v_mfma_f32_16x16x32_bf16 v[42:45], v[138:141], v[170:173], v[42:45]
	v_mfma_f32_16x16x32_bf16 v[30:33], v[130:133], v[178:181], v[30:33]
	v_mfma_f32_16x16x32_bf16 v[26:29], v[138:141], v[178:181], v[26:29]
	v_mfma_f32_16x16x32_bf16 v[12:15], v[130:133], v[186:189], v[12:15]
	v_mfma_f32_16x16x32_bf16 v[8:11], v[138:141], v[186:189], v[8:11]
	v_mfma_f32_16x16x32_bf16 v[62:65], v[134:137], v[166:169], v[62:65]
	v_mfma_f32_16x16x32_bf16 v[58:61], v[142:145], v[166:169], v[58:61]
	v_mfma_f32_16x16x32_bf16 v[46:49], v[134:137], v[174:177], v[46:49]
	v_mfma_f32_16x16x32_bf16 v[42:45], v[142:145], v[174:177], v[42:45]
	v_mfma_f32_16x16x32_bf16 v[30:33], v[134:137], v[182:185], v[30:33]
	v_mfma_f32_16x16x32_bf16 v[26:29], v[142:145], v[182:185], v[26:29]
	v_mfma_f32_16x16x32_bf16 v[12:15], v[134:137], v[190:193], v[12:15]
	v_mfma_f32_16x16x32_bf16 v[8:11], v[142:145], v[190:193], v[8:11]
	s_setprio 0
	s_setprio 1
	v_mfma_f32_16x16x32_bf16 v[54:57], v[146:149], v[162:165], v[54:57]
	v_mfma_f32_16x16x32_bf16 v[50:53], v[154:157], v[162:165], v[50:53]
	v_mfma_f32_16x16x32_bf16 v[38:41], v[146:149], v[170:173], v[38:41]
	v_mfma_f32_16x16x32_bf16 v[34:37], v[154:157], v[170:173], v[34:37]
	v_mfma_f32_16x16x32_bf16 v[22:25], v[146:149], v[178:181], v[22:25]
	v_mfma_f32_16x16x32_bf16 v[16:19], v[154:157], v[178:181], v[16:19]
	v_mfma_f32_16x16x32_bf16 v[4:7], v[146:149], v[186:189], v[4:7]
	v_mfma_f32_16x16x32_bf16 v[0:3], v[154:157], v[186:189], v[0:3]
	v_mfma_f32_16x16x32_bf16 v[54:57], v[150:153], v[166:169], v[54:57]
	v_mfma_f32_16x16x32_bf16 v[50:53], v[158:161], v[166:169], v[50:53]
	v_mfma_f32_16x16x32_bf16 v[38:41], v[150:153], v[174:177], v[38:41]
	v_mfma_f32_16x16x32_bf16 v[34:37], v[158:161], v[174:177], v[34:37]
	v_mfma_f32_16x16x32_bf16 v[22:25], v[150:153], v[182:185], v[22:25]
	v_mfma_f32_16x16x32_bf16 v[16:19], v[158:161], v[182:185], v[16:19]
	v_mfma_f32_16x16x32_bf16 v[4:7], v[150:153], v[190:193], v[4:7]
	v_mfma_f32_16x16x32_bf16 v[0:3], v[158:161], v[190:193], v[0:3]
	s_setprio 0
	s_barrier
	s_add_i32 vcc_lo, vcc_lo, 2
	s_add_u32 s28, s28, 0x100
	s_addc_u32 s29, s29, 0
	s_add_u32 s57, s57, 0x100
	s_addc_u32 s92, s92, 0
	s_cmp_gt_u32 vcc_lo, 29

; #define PG8_STAGE(bufoff, gbase, voff) do { _Pragma("unroll") for (int _i = 0; _i < 2; ++_i) \
;         __builtin_amdgcn_global_load_lds((const unsigned*)((const char*)(gbase) + (voff)[_i]), (PG8_LAS unsigned*)(lds + (bufoff) + ldsw + _i * 8192), 16, 0, 0); } while (0)
; #define PG8_LDA(dst, b, h) do { _Pragma("unroll") for (int m = 0; m < 4; ++m) _Pragma("unroll") for (int k = 0; k < 2; ++k) dst[m][k] = *(const PG8_LAS bf16x8*)(lds + PG8_SA(b, h) + aoff + m * 2048 + k * 1024); } while (0)
; #define PG8_LDB(dst, b, h) do { _Pragma("unroll") for (int n = 0; n < 2; ++n) _Pragma("unroll") for (int k = 0; k < 2; ++k) dst[n][k] = *(const PG8_LAS bf16x8*)(lds + PG8_SB(b, h) + boff + n * 2048 + k * 1024); } while (0)
; #define PG8_WAIT_V(n) asm volatile("s_waitcnt vmcnt(" #n ")" ::: "memory")
; #define PG8_WAIT_L(n) asm volatile("s_waitcnt lgkmcnt(" #n ")" ::: "memory")
; #define PG8_BAR __builtin_amdgcn_s_barrier()
; #define PG8_SCHED __builtin_amdgcn_sched_barrier(0)
; template <class Epi, class Sched, bool ALIGN_EPI = false, bool SP2 = false>
; __device__ __forceinline__ void gemm_phase(PG8_LAS unsigned char* lds, const Gemm g, const Sched& S, const Epi& E, const int tid_in) {
;     ...
;             const bool last = (t == nt - 2);
;             const char* a1 = cA + (size_t)(t + 1) * kstep;
;             const char* a2 = last ? nA : cA + (size_t)(t + 2) * kstep; const char* b2 = last ? nB : cB + (size_t)(t + 2) * kstep;
;             const char* a3 = a2 + kstep; const char* b3 = b2 + kstep;
;             if (last && has_next) S.a_ready(nxt);
;             if constexpr (SP2) {
;             PG8_LDB(B0, 0, 0); PG8_LDB(B1, 0, 1); PG8_SCHED; PG8_LDA(At, 0, 0); PG8_STAGE(PG8_SA(1, 1), a1 + hstep, voffA);
;             PG8_WAIT_V(8); PG8_WAIT_L(0); PG8_BAR; PG8_MMA(0, 0, At, B0); PG8_MMA(0, 1, At, B1); PG8_BAR; PG8_SCHED;
;             PG8_LDA(At, 0, 1); PG8_STAGE(PG8_SB(0, 0), b2, voffB); PG8_STAGE(PG8_SB(0, 1), b2 + hstep, voffB); PG8_STAGE(PG8_SA(0, 0), a2, voffA);
;             PG8_WAIT_V(8); PG8_WAIT_L(0); PG8_BAR; PG8_MMA(1, 0, At, B0); PG8_MMA(1, 1, At, B1); PG8_BAR; PG8_SCHED;
;     ...
;         for (int a = 0; a < 2; ++a)
; #pragma unroll
;             for (int b = 0; b < 2; ++b)
; #pragma unroll
;                 for (int m = 0; m < 4; ++m)
; #pragma unroll
;                     for (int n = 0; n < 2; ++n) acc[a][b][m][n] = (f32x4){0.f, 0.f, 0.f, 0.f};
.LBB0_1156:
	s_ashr_i32 s35, s34, 31
	s_lshl_b64 s[6:7], s[34:35], 20
	s_add_u32 s6, s5, s6
	s_addc_u32 s7, s8, s7
	s_and_b64 s[20:21], exec, s[48:49]
	s_cselect_b32 s35, s51, s7
	s_cselect_b32 s58, s50, s6
	s_ashr_i32 s31, s30, 31
	s_lshl_b64 s[20:21], s[30:31], 20
	s_add_u32 s20, s10, s20
	s_addc_u32 s21, s19, s21
	s_and_b64 s[54:55], exec, s[48:49]
	s_cselect_b32 s31, s53, s21
	s_cselect_b32 s59, s52, s20
	s_add_u32 s50, s50, 0x80080
	s_addc_u32 s51, s51, 0
	s_add_u32 s60, s52, 0x100
	v_mov_b32_e32 v0, 0
	s_addc_u32 s61, s53, 0
	s_mov_b32 s62, -2
	s_mov_b32 m0, s25
	s_nop 0
	global_load_lds_dwordx4 v166, s[100:101]
	s_add_u32 s52, s50, 0xfff80080
	s_addc_u32 s53, s51, -1
	s_add_i32 s63, 0, 0x10000
	s_cmp_eq_u32 s62, 28
	s_cselect_b32 s55, s35, s53
	s_cselect_b32 s54, s58, s52
	s_cselect_b32 s53, s31, s61
	s_cselect_b32 s52, s59, s60
	s_add_i32 s66, 0, 0x14000
	v_add_u32_e32 v78, s63, v177
	v_add_u32_e32 v134, s66, v177
	ds_read_b128 v[66:69], v78
	ds_read_b128 v[70:73], v78 offset:1024
	ds_read_b128 v[74:77], v78 offset:2048
	ds_read_b128 v[78:81], v78 offset:3072
	ds_read_b128 v[122:125], v134
	ds_read_b128 v[126:129], v134 offset:1024
	ds_read_b128 v[130:133], v134 offset:2048
	ds_read_b128 v[134:137], v134 offset:3072
	s_add_i32 m0, s89, 0xc000
	ds_read_b128 v[188:191], v193
	ds_read_b128 v[194:197], v193 offset:1024
	ds_read_b128 v[198:201], v193 offset:2048
	ds_read_b128 v[202:205], v193 offset:3072
	ds_read_b128 v[208:211], v193 offset:4096
	ds_read_b128 v[212:215], v193 offset:5120
	ds_read_b128 v[216:219], v193 offset:6144
	ds_read_b128 v[220:223], v193 offset:7168
	global_load_lds_dwordx4 v184, s[50:51]
	s_add_i32 m0, s89, 0xe000
	s_nop 0
	global_load_lds_dwordx4 v186, s[50:51]
	s_waitcnt vmcnt(8)
	s_waitcnt lgkmcnt(0)
	s_barrier
	s_setprio 1
	v_mfma_f32_16x16x32_bf16 v[150:153], v[66:69], v[188:191], 0
	v_mfma_f32_16x16x32_bf16 v[110:113], v[74:77], v[188:191], 0
	v_mfma_f32_16x16x32_bf16 v[146:149], v[66:69], v[198:201], 0
	v_mfma_f32_16x16x32_bf16 v[106:109], v[74:77], v[198:201], 0
	v_mfma_f32_16x16x32_bf16 v[142:145], v[66:69], v[208:211], 0
	v_mfma_f32_16x16x32_bf16 v[102:105], v[74:77], v[208:211], 0
	v_mfma_f32_16x16x32_bf16 v[138:141], v[66:69], v[216:219], 0
	v_mfma_f32_16x16x32_bf16 v[98:101], v[74:77], v[216:219], 0
	v_mfma_f32_16x16x32_bf16 v[150:153], v[70:73], v[194:197], v[150:153]
	v_mfma_f32_16x16x32_bf16 v[110:113], v[78:81], v[194:197], v[110:113]
	v_mfma_f32_16x16x32_bf16 v[146:149], v[70:73], v[202:205], v[146:149]
	v_mfma_f32_16x16x32_bf16 v[106:109], v[78:81], v[202:205], v[106:109]
	v_mfma_f32_16x16x32_bf16 v[142:145], v[70:73], v[212:215], v[142:145]
	v_mfma_f32_16x16x32_bf16 v[102:105], v[78:81], v[212:215], v[102:105]
	v_mfma_f32_16x16x32_bf16 v[138:141], v[70:73], v[220:223], v[138:141]
	v_mfma_f32_16x16x32_bf16 v[98:101], v[78:81], v[220:223], v[98:101]
	s_setprio 0
	s_setprio 1
	v_mfma_f32_16x16x32_bf16 v[94:97], v[122:125], v[188:191], 0
	v_mfma_f32_16x16x32_bf16 v[90:93], v[130:133], v[188:191], 0
	v_mfma_f32_16x16x32_bf16 v[158:161], v[122:125], v[198:201], 0
	v_mfma_f32_16x16x32_bf16 v[118:121], v[130:133], v[198:201], 0
	v_mfma_f32_16x16x32_bf16 v[154:157], v[122:125], v[208:211], 0
	v_mfma_f32_16x16x32_bf16 v[114:117], v[130:133], v[208:211], 0
	v_mfma_f32_16x16x32_bf16 v[86:89], v[122:125], v[216:219], 0
	v_mfma_f32_16x16x32_bf16 v[82:85], v[130:133], v[216:219], 0
	v_mfma_f32_16x16x32_bf16 v[94:97], v[126:129], v[194:197], v[94:97]
	v_mfma_f32_16x16x32_bf16 v[90:93], v[134:137], v[194:197], v[90:93]
	v_mfma_f32_16x16x32_bf16 v[158:161], v[126:129], v[202:205], v[158:161]
	v_mfma_f32_16x16x32_bf16 v[118:121], v[134:137], v[202:205], v[118:121]
	v_mfma_f32_16x16x32_bf16 v[154:157], v[126:129], v[212:215], v[154:157]
	v_mfma_f32_16x16x32_bf16 v[114:117], v[134:137], v[212:215], v[114:117]
	v_mfma_f32_16x16x32_bf16 v[86:89], v[126:129], v[220:223], v[86:89]
	v_mfma_f32_16x16x32_bf16 v[82:85], v[134:137], v[220:223], v[82:85]
	s_setprio 0
	s_barrier
	s_add_i32 s63, s63, s1
	s_add_u32 s98, s52, 0x80
	s_addc_u32 s99, s53, 0
	s_mov_b32 m0, s63
	ds_read_b128 v[188:191], v193 offset:16384
	ds_read_b128 v[194:197], v193 offset:17408
	ds_read_b128 v[198:201], v193 offset:18432
	ds_read_b128 v[202:205], v193 offset:19456
	ds_read_b128 v[208:211], v193 offset:20480
	ds_read_b128 v[212:215], v193 offset:21504
	ds_read_b128 v[216:219], v193 offset:22528
	ds_read_b128 v[220:223], v193 offset:23552
	global_load_lds_dwordx4 v164, s[52:53]
	s_add_i32 m0, s63, 0x2000
	s_add_u32 s64, s52, 0x80000
	s_addc_u32 s65, s53, 0
	s_add_i32 s63, s66, s1
	global_load_lds_dwordx4 v168, s[52:53]
	s_mov_b32 m0, s63
	s_add_u32 s100, s54, 0x80
	s_addc_u32 s101, s55, 0
	global_load_lds_dwordx4 v164, s[64:65]
	s_add_i32 m0, s63, 0x2000
	s_nop 0
	global_load_lds_dwordx4 v168, s[64:65]
	s_mov_b32 m0, s89
	s_nop 0
	global_load_lds_dwordx4 v162, s[54:55]
	s_waitcnt vmcnt(7)
	s_waitcnt lgkmcnt(0)
	s_barrier
; #define PG8_STAGE(bufoff, gbase, voff) do { _Pragma("unroll") for (int _i = 0; _i < 2; ++_i) \
;         __builtin_amdgcn_global_load_lds((const unsigned*)((const char*)(gbase) + (voff)[_i]), (PG8_LAS unsigned*)(lds + (bufoff) + ldsw + _i * 8192), 16, 0, 0); } while (0)
; #define PG8_LDA(dst, b, h) do { _Pragma("unroll") for (int m = 0; m < 4; ++m) _Pragma("unroll") for (int k = 0; k < 2; ++k) dst[m][k] = *(const PG8_LAS bf16x8*)(lds + PG8_SA(b, h) + aoff + m * 2048 + k * 1024); } while (0)
; #define PG8_LDB(dst, b, h) do { _Pragma("unroll") for (int n = 0; n < 2; ++n) _Pragma("unroll") for (int k = 0; k < 2; ++k) dst[n][k] = *(const PG8_LAS bf16x8*)(lds + PG8_SB(b, h) + boff + n * 2048 + k * 1024); } while (0)
; #define PG8_MMA(ai, bj, At, Bt) do { __builtin_amdgcn_s_setprio(1); _Pragma("unroll") for (int m = 0; m < 4; ++m) _Pragma("unroll") for (int n = 0; n < 2; ++n) _Pragma("unroll") for (int k = 0; k < 2; ++k) \
;         acc[ai][bj][m][n] = __builtin_amdgcn_mfma_f32_16x16x32_bf16(Bt[n][k], At[m][k], acc[ai][bj][m][n], 0, 0, 0); __builtin_amdgcn_s_setprio(0); } while (0)
; #define PG8_WAIT_V(n) asm volatile("s_waitcnt vmcnt(" #n ")" ::: "memory")
; #define PG8_WAIT_L(n) asm volatile("s_waitcnt lgkmcnt(" #n ")" ::: "memory")
; #define PG8_BAR __builtin_amdgcn_s_barrier()
; #define PG8_SCHED __builtin_amdgcn_sched_barrier(0)
; template <class Epi, class Sched, bool ALIGN_EPI = false, bool SP2 = false>
; __device__ __forceinline__ void gemm_phase(PG8_LAS unsigned char* lds, const Gemm g, const Sched& S, const Epi& E, const int tid_in) {
;     ...
;             PG8_WAIT_V(8); PG8_WAIT_L(0); PG8_BAR; PG8_MMA(1, 0, At, B0); PG8_MMA(1, 1, At, B1); PG8_BAR; PG8_SCHED;
;             PG8_LDB(B0, 1, 0); PG8_LDB(B1, 1, 1); PG8_SCHED; PG8_LDA(At, 1, 0); PG8_STAGE(PG8_SA(0, 1), a2 + hstep, voffA);
;             PG8_WAIT_V(8); PG8_WAIT_L(0); PG8_BAR; PG8_MMA(0, 0, At, B0); PG8_MMA(0, 1, At, B1); PG8_BAR; PG8_SCHED;
	s_setprio 1
	v_mfma_f32_16x16x32_bf16 v[54:57], v[66:69], v[188:191], 0
	v_mfma_f32_16x16x32_bf16 v[30:33], v[74:77], v[188:191], 0
	v_mfma_f32_16x16x32_bf16 v[50:53], v[66:69], v[198:201], 0
	v_mfma_f32_16x16x32_bf16 v[26:29], v[74:77], v[198:201], 0
	v_mfma_f32_16x16x32_bf16 v[46:49], v[66:69], v[208:211], 0
	v_mfma_f32_16x16x32_bf16 v[22:25], v[74:77], v[208:211], 0
	v_mfma_f32_16x16x32_bf16 v[42:45], v[66:69], v[216:219], 0
	v_mfma_f32_16x16x32_bf16 v[16:19], v[74:77], v[216:219], 0
	v_mfma_f32_16x16x32_bf16 v[54:57], v[70:73], v[194:197], v[54:57]
	v_mfma_f32_16x16x32_bf16 v[30:33], v[78:81], v[194:197], v[30:33]
	v_mfma_f32_16x16x32_bf16 v[50:53], v[70:73], v[202:205], v[50:53]
	v_mfma_f32_16x16x32_bf16 v[26:29], v[78:81], v[202:205], v[26:29]
	v_mfma_f32_16x16x32_bf16 v[46:49], v[70:73], v[212:215], v[46:49]
	v_mfma_f32_16x16x32_bf16 v[22:25], v[78:81], v[212:215], v[22:25]
	v_mfma_f32_16x16x32_bf16 v[42:45], v[70:73], v[220:223], v[42:45]
	v_mfma_f32_16x16x32_bf16 v[16:19], v[78:81], v[220:223], v[16:19]
	s_setprio 0
	s_setprio 1
	v_mfma_f32_16x16x32_bf16 v[12:15], v[122:125], v[188:191], 0
	v_mfma_f32_16x16x32_bf16 v[8:11], v[130:133], v[188:191], 0
	v_mfma_f32_16x16x32_bf16 v[62:65], v[122:125], v[198:201], 0
	v_mfma_f32_16x16x32_bf16 v[38:41], v[130:133], v[198:201], 0
	v_mfma_f32_16x16x32_bf16 v[58:61], v[122:125], v[208:211], 0
	v_mfma_f32_16x16x32_bf16 v[34:37], v[130:133], v[208:211], 0
	v_mfma_f32_16x16x32_bf16 v[4:7], v[122:125], v[216:219], 0
	v_mfma_f32_16x16x32_bf16 v[0:3], v[130:133], v[216:219], 0
	v_mfma_f32_16x16x32_bf16 v[12:15], v[126:129], v[194:197], v[12:15]
	v_mfma_f32_16x16x32_bf16 v[8:11], v[134:137], v[194:197], v[8:11]
	v_mfma_f32_16x16x32_bf16 v[62:65], v[126:129], v[202:205], v[62:65]
	v_mfma_f32_16x16x32_bf16 v[38:41], v[134:137], v[202:205], v[38:41]
	v_mfma_f32_16x16x32_bf16 v[58:61], v[126:129], v[212:215], v[58:61]
	v_mfma_f32_16x16x32_bf16 v[34:37], v[134:137], v[212:215], v[34:37]
	v_mfma_f32_16x16x32_bf16 v[4:7], v[126:129], v[220:223], v[4:7]
	v_mfma_f32_16x16x32_bf16 v[0:3], v[134:137], v[220:223], v[0:3]
	s_setprio 0
	s_barrier
	s_add_i32 s63, 0, 0x18000
	s_add_i32 s64, 0, 0x1c000
	v_add_u32_e32 v78, s63, v177
	v_add_u32_e32 v134, s64, v177
	ds_read_b128 v[66:69], v78
	ds_read_b128 v[70:73], v78 offset:1024
	ds_read_b128 v[74:77], v78 offset:2048
	ds_read_b128 v[78:81], v78 offset:3072
	ds_read_b128 v[122:125], v134
	ds_read_b128 v[126:129], v134 offset:1024
	ds_read_b128 v[130:133], v134 offset:2048
	ds_read_b128 v[134:137], v134 offset:3072
	s_mov_b32 m0, s92
	s_nop 0
	global_load_lds_dwordx4 v166, s[54:55]
	s_add_u32 s54, s54, 0x80000
	s_addc_u32 s55, s55, 0
	s_mov_b32 m0, s2
	ds_read_b128 v[188:191], v193 offset:32768
	ds_read_b128 v[194:197], v193 offset:33792
	ds_read_b128 v[198:201], v193 offset:34816
	ds_read_b128 v[202:205], v193 offset:35840
	ds_read_b128 v[208:211], v193 offset:36864
	ds_read_b128 v[212:215], v193 offset:37888
	ds_read_b128 v[216:219], v193 offset:38912
	ds_read_b128 v[220:223], v193 offset:39936
	global_load_lds_dwordx4 v162, s[54:55]
	s_mov_b32 m0, s3
	s_nop 0
	global_load_lds_dwordx4 v166, s[54:55]
	s_waitcnt vmcnt(8)
	s_waitcnt lgkmcnt(0)
	s_barrier
	s_setprio 1
	v_mfma_f32_16x16x32_bf16 v[150:153], v[66:69], v[188:191], v[150:153]
	v_mfma_f32_16x16x32_bf16 v[110:113], v[74:77], v[188:191], v[110:113]
	v_mfma_f32_16x16x32_bf16 v[146:149], v[66:69], v[198:201], v[146:149]
	v_mfma_f32_16x16x32_bf16 v[106:109], v[74:77], v[198:201], v[106:109]
	v_mfma_f32_16x16x32_bf16 v[142:145], v[66:69], v[208:211], v[142:145]
	v_mfma_f32_16x16x32_bf16 v[102:105], v[74:77], v[208:211], v[102:105]
	v_mfma_f32_16x16x32_bf16 v[138:141], v[66:69], v[216:219], v[138:141]
	v_mfma_f32_16x16x32_bf16 v[98:101], v[74:77], v[216:219], v[98:101]
	v_mfma_f32_16x16x32_bf16 v[150:153], v[70:73], v[194:197], v[150:153]
	v_mfma_f32_16x16x32_bf16 v[110:113], v[78:81], v[194:197], v[110:113]
	v_mfma_f32_16x16x32_bf16 v[146:149], v[70:73], v[202:205], v[146:149]
	v_mfma_f32_16x16x32_bf16 v[106:109], v[78:81], v[202:205], v[106:109]
	v_mfma_f32_16x16x32_bf16 v[142:145], v[70:73], v[212:215], v[142:145]
	v_mfma_f32_16x16x32_bf16 v[102:105], v[78:81], v[212:215], v[102:105]
	v_mfma_f32_16x16x32_bf16 v[138:141], v[70:73], v[220:223], v[138:141]
	v_mfma_f32_16x16x32_bf16 v[98:101], v[78:81], v[220:223], v[98:101]
	s_setprio 0
	s_setprio 1
	v_mfma_f32_16x16x32_bf16 v[94:97], v[122:125], v[188:191], v[94:97]
	v_mfma_f32_16x16x32_bf16 v[90:93], v[130:133], v[188:191], v[90:93]
	v_mfma_f32_16x16x32_bf16 v[158:161], v[122:125], v[198:201], v[158:161]
	v_mfma_f32_16x16x32_bf16 v[118:121], v[130:133], v[198:201], v[118:121]
	v_mfma_f32_16x16x32_bf16 v[154:157], v[122:125], v[208:211], v[154:157]
	v_mfma_f32_16x16x32_bf16 v[114:117], v[130:133], v[208:211], v[114:117]
	v_mfma_f32_16x16x32_bf16 v[86:89], v[122:125], v[216:219], v[86:89]
	v_mfma_f32_16x16x32_bf16 v[82:85], v[130:133], v[216:219], v[82:85]
	v_mfma_f32_16x16x32_bf16 v[94:97], v[126:129], v[194:197], v[94:97]
	v_mfma_f32_16x16x32_bf16 v[90:93], v[134:137], v[194:197], v[90:93]
	v_mfma_f32_16x16x32_bf16 v[158:161], v[126:129], v[202:205], v[158:161]
	v_mfma_f32_16x16x32_bf16 v[118:121], v[134:137], v[202:205], v[118:121]
	v_mfma_f32_16x16x32_bf16 v[154:157], v[126:129], v[212:215], v[154:157]
	v_mfma_f32_16x16x32_bf16 v[114:117], v[134:137], v[212:215], v[114:117]
	v_mfma_f32_16x16x32_bf16 v[86:89], v[126:129], v[220:223], v[86:89]
	v_mfma_f32_16x16x32_bf16 v[82:85], v[134:137], v[220:223], v[82:85]
	s_setprio 0
	s_barrier
; #define PG8_STAGE(bufoff, gbase, voff) do { _Pragma("unroll") for (int _i = 0; _i < 2; ++_i) \
;         __builtin_amdgcn_global_load_lds((const unsigned*)((const char*)(gbase) + (voff)[_i]), (PG8_LAS unsigned*)(lds + (bufoff) + ldsw + _i * 8192), 16, 0, 0); } while (0)
; #define PG8_LDA(dst, b, h) do { _Pragma("unroll") for (int m = 0; m < 4; ++m) _Pragma("unroll") for (int k = 0; k < 2; ++k) dst[m][k] = *(const PG8_LAS bf16x8*)(lds + PG8_SA(b, h) + aoff + m * 2048 + k * 1024); } while (0)
; #define PG8_MMA(ai, bj, At, Bt) do { __builtin_amdgcn_s_setprio(1); _Pragma("unroll") for (int m = 0; m < 4; ++m) _Pragma("unroll") for (int n = 0; n < 2; ++n) _Pragma("unroll") for (int k = 0; k < 2; ++k) \
;         acc[ai][bj][m][n] = __builtin_amdgcn_mfma_f32_16x16x32_bf16(Bt[n][k], At[m][k], acc[ai][bj][m][n], 0, 0, 0); __builtin_amdgcn_s_setprio(0); } while (0)
; #define PG8_WAIT_V(n) asm volatile("s_waitcnt vmcnt(" #n ")" ::: "memory")
; #define PG8_WAIT_L(n) asm volatile("s_waitcnt lgkmcnt(" #n ")" ::: "memory")
; #define PG8_BAR __builtin_amdgcn_s_barrier()
; #define PG8_SCHED __builtin_amdgcn_sched_barrier(0)
; template <class Epi, class Sched, bool ALIGN_EPI = false, bool SP2 = false>
; __device__ __forceinline__ void gemm_phase(PG8_LAS unsigned char* lds, const Gemm g, const Sched& S, const Epi& E, const int tid_in) {
;     ...
;             PG8_LDA(At, 1, 1); PG8_STAGE(PG8_SB(1, 0), b3, voffB); PG8_STAGE(PG8_SB(1, 1), b3 + hstep, voffB); PG8_STAGE(PG8_SA(1, 0), a3, voffA);
;             PG8_WAIT_V(8); PG8_WAIT_L(0); PG8_BAR; PG8_MMA(1, 0, At, B0); PG8_MMA(1, 1, At, B1); PG8_BAR; PG8_SCHED;
	s_add_i32 s54, s63, s1
	s_mov_b32 m0, s54
	ds_read_b128 v[188:191], v193 offset:49152
	ds_read_b128 v[194:197], v193 offset:50176
	ds_read_b128 v[198:201], v193 offset:51200
	ds_read_b128 v[202:205], v193 offset:52224
	ds_read_b128 v[208:211], v193 offset:53248
	ds_read_b128 v[212:215], v193 offset:54272
	ds_read_b128 v[216:219], v193 offset:55296
	ds_read_b128 v[220:223], v193 offset:56320
	global_load_lds_dwordx4 v164, s[98:99]
	s_add_i32 m0, s54, 0x2000
	s_add_u32 s52, s52, 0x80080
	s_addc_u32 s53, s53, 0
	s_add_i32 s54, s64, s1
	global_load_lds_dwordx4 v168, s[98:99]
	s_mov_b32 m0, s54
	s_nop 0
	global_load_lds_dwordx4 v164, s[52:53]
	s_add_i32 m0, s54, 0x2000
	s_nop 0
	global_load_lds_dwordx4 v168, s[52:53]
	s_mov_b32 m0, s24
	s_nop 0
	global_load_lds_dwordx4 v162, s[100:101]
	s_waitcnt vmcnt(7)
	s_waitcnt lgkmcnt(0)
	s_barrier
	s_setprio 1
	v_mfma_f32_16x16x32_bf16 v[54:57], v[66:69], v[188:191], v[54:57]
	v_mfma_f32_16x16x32_bf16 v[30:33], v[74:77], v[188:191], v[30:33]
	v_mfma_f32_16x16x32_bf16 v[50:53], v[66:69], v[198:201], v[50:53]
	v_mfma_f32_16x16x32_bf16 v[26:29], v[74:77], v[198:201], v[26:29]
	v_mfma_f32_16x16x32_bf16 v[46:49], v[66:69], v[208:211], v[46:49]
	v_mfma_f32_16x16x32_bf16 v[22:25], v[74:77], v[208:211], v[22:25]
	v_mfma_f32_16x16x32_bf16 v[42:45], v[66:69], v[216:219], v[42:45]
	v_mfma_f32_16x16x32_bf16 v[16:19], v[74:77], v[216:219], v[16:19]
	v_mfma_f32_16x16x32_bf16 v[54:57], v[70:73], v[194:197], v[54:57]
	v_mfma_f32_16x16x32_bf16 v[30:33], v[78:81], v[194:197], v[30:33]
	v_mfma_f32_16x16x32_bf16 v[50:53], v[70:73], v[202:205], v[50:53]
	v_mfma_f32_16x16x32_bf16 v[26:29], v[78:81], v[202:205], v[26:29]
	v_mfma_f32_16x16x32_bf16 v[46:49], v[70:73], v[212:215], v[46:49]
	v_mfma_f32_16x16x32_bf16 v[22:25], v[78:81], v[212:215], v[22:25]
	v_mfma_f32_16x16x32_bf16 v[42:45], v[70:73], v[220:223], v[42:45]
	v_mfma_f32_16x16x32_bf16 v[16:19], v[78:81], v[220:223], v[16:19]
	s_setprio 0
	s_setprio 1
	v_mfma_f32_16x16x32_bf16 v[12:15], v[122:125], v[188:191], v[12:15]
	v_mfma_f32_16x16x32_bf16 v[8:11], v[130:133], v[188:191], v[8:11]
	v_mfma_f32_16x16x32_bf16 v[62:65], v[122:125], v[198:201], v[62:65]
	v_mfma_f32_16x16x32_bf16 v[38:41], v[130:133], v[198:201], v[38:41]
	v_mfma_f32_16x16x32_bf16 v[58:61], v[122:125], v[208:211], v[58:61]
	v_mfma_f32_16x16x32_bf16 v[34:37], v[130:133], v[208:211], v[34:37]
	v_mfma_f32_16x16x32_bf16 v[4:7], v[122:125], v[216:219], v[4:7]
	v_mfma_f32_16x16x32_bf16 v[0:3], v[130:133], v[216:219], v[0:3]
	v_mfma_f32_16x16x32_bf16 v[12:15], v[126:129], v[194:197], v[12:15]
	v_mfma_f32_16x16x32_bf16 v[8:11], v[134:137], v[194:197], v[8:11]
	v_mfma_f32_16x16x32_bf16 v[62:65], v[126:129], v[202:205], v[62:65]
	v_mfma_f32_16x16x32_bf16 v[38:41], v[134:137], v[202:205], v[38:41]
	v_mfma_f32_16x16x32_bf16 v[58:61], v[126:129], v[212:215], v[58:61]
	v_mfma_f32_16x16x32_bf16 v[34:37], v[134:137], v[212:215], v[34:37]
	v_mfma_f32_16x16x32_bf16 v[4:7], v[126:129], v[220:223], v[4:7]
	v_mfma_f32_16x16x32_bf16 v[0:3], v[134:137], v[220:223], v[0:3]
	s_setprio 0
	s_barrier
	s_add_i32 s62, s62, 2
	s_add_u32 s50, s50, 0x100
	s_addc_u32 s51, s51, 0
	s_add_u32 s60, s60, 0x100
	s_addc_u32 s61, s61, 0
	s_cmp_gt_u32 s62, 29

; #define PG8_STAGE(bufoff, gbase, voff) do { _Pragma("unroll") for (int _i = 0; _i < 2; ++_i) \
;         __builtin_amdgcn_global_load_lds((const unsigned*)((const char*)(gbase) + (voff)[_i]), (PG8_LAS unsigned*)(lds + (bufoff) + ldsw + _i * 8192), 16, 0, 0); } while (0)
; #define PG8_LDA(dst, b, h) do { _Pragma("unroll") for (int m = 0; m < 4; ++m) _Pragma("unroll") for (int k = 0; k < 2; ++k) dst[m][k] = *(const PG8_LAS bf16x8*)(lds + PG8_SA(b, h) + aoff + m * 2048 + k * 1024); } while (0)
; #define PG8_LDB(dst, b, h) do { _Pragma("unroll") for (int n = 0; n < 2; ++n) _Pragma("unroll") for (int k = 0; k < 2; ++k) dst[n][k] = *(const PG8_LAS bf16x8*)(lds + PG8_SB(b, h) + boff + n * 2048 + k * 1024); } while (0)
; #define PG8_WAIT_V(n) asm volatile("s_waitcnt vmcnt(" #n ")" ::: "memory")
; #define PG8_WAIT_L(n) asm volatile("s_waitcnt lgkmcnt(" #n ")" ::: "memory")
; #define PG8_BAR __builtin_amdgcn_s_barrier()
; #define PG8_SCHED __builtin_amdgcn_sched_barrier(0)
; template <class Epi, class Sched, bool ALIGN_EPI = false, bool SP2 = false>
; __device__ __forceinline__ void gemm_phase(PG8_LAS unsigned char* lds, const Gemm g, const Sched& S, const Epi& E, const int tid_in) {
;     ...
;             const bool last = (t == nt - 2);
;             const char* a1 = cA + (size_t)(t + 1) * kstep;
;             const char* a2 = last ? nA : cA + (size_t)(t + 2) * kstep; const char* b2 = last ? nB : cB + (size_t)(t + 2) * kstep;
;             const char* a3 = a2 + kstep; const char* b3 = b2 + kstep;
;             if (last && has_next) S.a_ready(nxt);
;             if constexpr (SP2) {
;             PG8_LDB(B0, 0, 0); PG8_LDB(B1, 0, 1); PG8_SCHED; PG8_LDA(At, 0, 0); PG8_STAGE(PG8_SA(1, 1), a1 + hstep, voffA);
;             PG8_WAIT_V(8); PG8_WAIT_L(0); PG8_BAR; PG8_MMA(0, 0, At, B0); PG8_MMA(0, 1, At, B1); PG8_BAR; PG8_SCHED;
;             PG8_LDA(At, 0, 1); PG8_STAGE(PG8_SB(0, 0), b2, voffB); PG8_STAGE(PG8_SB(0, 1), b2 + hstep, voffB); PG8_STAGE(PG8_SA(0, 0), a2, voffA);
;             PG8_WAIT_V(8); PG8_WAIT_L(0); PG8_BAR; PG8_MMA(1, 0, At, B0); PG8_MMA(1, 1, At, B1); PG8_BAR; PG8_SCHED;
;     ...
;         for (int a = 0; a < 2; ++a)
; #pragma unroll
;             for (int b = 0; b < 2; ++b)
; #pragma unroll
;                 for (int m = 0; m < 4; ++m)
; #pragma unroll
;                     for (int n = 0; n < 2; ++n) acc[a][b][m][n] = (f32x4){0.f, 0.f, 0.f, 0.f};
.LBB0_1304:
	s_add_u32 s54, s30, 0x100
	v_mov_b32_e32 v0, 0
	s_addc_u32 s55, s31, 0
	s_mov_b32 s56, -2
	s_mov_b32 m0, s47
	s_nop 0
	global_load_lds_dwordx4 v216, s[100:101]
	s_add_u32 s30, s28, 0x100
	s_addc_u32 s31, s29, 0
	s_add_i32 s57, 0, 0x10000
	s_cmpk_eq_i32 s56, 0x54
	s_cselect_b32 s39, s25, s31
	s_cselect_b32 s38, s24, s30
	s_cselect_b32 s35, s27, s55
	s_cselect_b32 s34, s26, s54
	s_add_i32 s58, 0, 0x14000
	v_add_u32_e32 v102, s57, v208
	v_add_u32_e32 v142, s58, v208
	ds_read_b128 v[78:81], v102
	ds_read_b128 v[86:89], v102 offset:1024
	ds_read_b128 v[94:97], v102 offset:2048
	ds_read_b128 v[102:105], v102 offset:3072
	ds_read_b128 v[118:121], v142
	ds_read_b128 v[126:129], v142 offset:1024
	ds_read_b128 v[134:137], v142 offset:2048
	ds_read_b128 v[142:145], v142 offset:3072
	v_lshl_add_u64 v[194:195], s[28:29], 0, v[222:223]
	s_add_i32 m0, s40, 0xc000
	ds_read_b128 v[154:157], v244
	ds_read_b128 v[158:161], v244 offset:1024
	ds_read_b128 v[162:165], v244 offset:2048
	ds_read_b128 v[166:169], v244 offset:3072
	ds_read_b128 v[170:173], v244 offset:4096
	ds_read_b128 v[182:185], v244 offset:5120
	ds_read_b128 v[186:189], v244 offset:6144
	ds_read_b128 v[190:193], v244 offset:7168
	global_load_lds_dwordx4 v[194:195], off
	v_lshl_add_u64 v[194:195], s[28:29], 0, v[224:225]
	s_add_i32 m0, s40, 0xe000
	s_nop 0
	global_load_lds_dwordx4 v[194:195], off
	s_waitcnt vmcnt(8)
	s_waitcnt lgkmcnt(0)
	s_barrier
	s_setprio 1
	v_mfma_f32_16x16x32_bf16 v[178:181], v[78:81], v[154:157], 0
	v_mfma_f32_16x16x32_bf16 v[174:177], v[94:97], v[154:157], 0
	v_mfma_f32_16x16x32_bf16 v[138:141], v[78:81], v[162:165], 0
	v_mfma_f32_16x16x32_bf16 v[130:133], v[94:97], v[162:165], 0
	v_mfma_f32_16x16x32_bf16 v[110:113], v[78:81], v[170:173], 0
	v_mfma_f32_16x16x32_bf16 v[106:109], v[94:97], v[170:173], 0
	v_mfma_f32_16x16x32_bf16 v[82:85], v[78:81], v[186:189], 0
	v_mfma_f32_16x16x32_bf16 v[74:77], v[94:97], v[186:189], 0
	v_mfma_f32_16x16x32_bf16 v[178:181], v[86:89], v[158:161], v[178:181]
	v_mfma_f32_16x16x32_bf16 v[174:177], v[102:105], v[158:161], v[174:177]
	v_mfma_f32_16x16x32_bf16 v[138:141], v[86:89], v[166:169], v[138:141]
	v_mfma_f32_16x16x32_bf16 v[130:133], v[102:105], v[166:169], v[130:133]
	v_mfma_f32_16x16x32_bf16 v[110:113], v[86:89], v[182:185], v[110:113]
	v_mfma_f32_16x16x32_bf16 v[106:109], v[102:105], v[182:185], v[106:109]
	v_mfma_f32_16x16x32_bf16 v[82:85], v[86:89], v[190:193], v[82:85]
	v_mfma_f32_16x16x32_bf16 v[74:77], v[102:105], v[190:193], v[74:77]
	s_setprio 0
	s_setprio 1
	v_mfma_f32_16x16x32_bf16 v[150:153], v[118:121], v[154:157], 0
	v_mfma_f32_16x16x32_bf16 v[146:149], v[134:137], v[154:157], 0
	v_mfma_f32_16x16x32_bf16 v[122:125], v[118:121], v[162:165], 0
	v_mfma_f32_16x16x32_bf16 v[114:117], v[134:137], v[162:165], 0
	v_mfma_f32_16x16x32_bf16 v[98:101], v[118:121], v[170:173], 0
	v_mfma_f32_16x16x32_bf16 v[90:93], v[134:137], v[170:173], 0
	v_mfma_f32_16x16x32_bf16 v[70:73], v[118:121], v[186:189], 0
	v_mfma_f32_16x16x32_bf16 v[66:69], v[134:137], v[186:189], 0
	v_mfma_f32_16x16x32_bf16 v[150:153], v[126:129], v[158:161], v[150:153]
	v_mfma_f32_16x16x32_bf16 v[146:149], v[142:145], v[158:161], v[146:149]
	v_mfma_f32_16x16x32_bf16 v[122:125], v[126:129], v[166:169], v[122:125]
	v_mfma_f32_16x16x32_bf16 v[114:117], v[142:145], v[166:169], v[114:117]
	v_mfma_f32_16x16x32_bf16 v[98:101], v[126:129], v[182:185], v[98:101]
	v_mfma_f32_16x16x32_bf16 v[90:93], v[142:145], v[182:185], v[90:93]
	v_mfma_f32_16x16x32_bf16 v[70:73], v[126:129], v[190:193], v[70:73]
	v_mfma_f32_16x16x32_bf16 v[66:69], v[142:145], v[190:193], v[66:69]
	s_setprio 0
	s_barrier
	s_add_i32 s28, s57, s19
	s_add_u32 s98, s34, 0x80
	s_addc_u32 s99, s35, 0
	s_mov_b32 m0, s28
	ds_read_b128 v[154:157], v244 offset:16384
	ds_read_b128 v[158:161], v244 offset:17408
	ds_read_b128 v[162:165], v244 offset:18432
	ds_read_b128 v[166:169], v244 offset:19456
	ds_read_b128 v[170:173], v244 offset:20480
	ds_read_b128 v[182:185], v244 offset:21504
	ds_read_b128 v[186:189], v244 offset:22528
	ds_read_b128 v[190:193], v244 offset:23552
	global_load_lds_dwordx4 v218, s[34:35]
	s_add_i32 m0, s28, 0x2000
	s_add_u32 s28, s34, 0x160000
	s_addc_u32 s29, s35, 0
	s_add_i32 s57, s58, s19
	global_load_lds_dwordx4 v214, s[34:35]
	s_mov_b32 m0, s57
	s_add_u32 s100, s38, 0x80
	s_addc_u32 s101, s39, 0
	global_load_lds_dwordx4 v218, s[28:29]
	s_add_i32 m0, s57, 0x2000
	s_nop 0
	global_load_lds_dwordx4 v214, s[28:29]
	s_mov_b32 m0, s40
	s_nop 0
	global_load_lds_dwordx4 v220, s[38:39]
	s_waitcnt vmcnt(7)
	s_waitcnt lgkmcnt(0)
	s_barrier
	s_setprio 1
	v_mfma_f32_16x16x32_bf16 v[62:65], v[78:81], v[154:157], 0
	v_mfma_f32_16x16x32_bf16 v[58:61], v[94:97], v[154:157], 0
	v_mfma_f32_16x16x32_bf16 v[46:49], v[78:81], v[162:165], 0
	v_mfma_f32_16x16x32_bf16 v[42:45], v[94:97], v[162:165], 0
	v_mfma_f32_16x16x32_bf16 v[30:33], v[78:81], v[170:173], 0
	v_mfma_f32_16x16x32_bf16 v[26:29], v[94:97], v[170:173], 0
	v_mfma_f32_16x16x32_bf16 v[12:15], v[78:81], v[186:189], 0
	v_mfma_f32_16x16x32_bf16 v[8:11], v[94:97], v[186:189], 0
	v_mfma_f32_16x16x32_bf16 v[62:65], v[86:89], v[158:161], v[62:65]
	v_mfma_f32_16x16x32_bf16 v[58:61], v[102:105], v[158:161], v[58:61]
	v_mfma_f32_16x16x32_bf16 v[46:49], v[86:89], v[166:169], v[46:49]
	v_mfma_f32_16x16x32_bf16 v[42:45], v[102:105], v[166:169], v[42:45]
	v_mfma_f32_16x16x32_bf16 v[30:33], v[86:89], v[182:185], v[30:33]
	v_mfma_f32_16x16x32_bf16 v[26:29], v[102:105], v[182:185], v[26:29]
	v_mfma_f32_16x16x32_bf16 v[12:15], v[86:89], v[190:193], v[12:15]
	v_mfma_f32_16x16x32_bf16 v[8:11], v[102:105], v[190:193], v[8:11]
	s_setprio 0
	s_setprio 1
	v_mfma_f32_16x16x32_bf16 v[54:57], v[118:121], v[154:157], 0
	v_mfma_f32_16x16x32_bf16 v[50:53], v[134:137], v[154:157], 0
	v_mfma_f32_16x16x32_bf16 v[38:41], v[118:121], v[162:165], 0
	v_mfma_f32_16x16x32_bf16 v[34:37], v[134:137], v[162:165], 0
	v_mfma_f32_16x16x32_bf16 v[22:25], v[118:121], v[170:173], 0
	v_mfma_f32_16x16x32_bf16 v[16:19], v[134:137], v[170:173], 0
	v_mfma_f32_16x16x32_bf16 v[4:7], v[118:121], v[186:189], 0
	v_mfma_f32_16x16x32_bf16 v[0:3], v[134:137], v[186:189], 0
	v_mfma_f32_16x16x32_bf16 v[54:57], v[126:129], v[158:161], v[54:57]
	v_mfma_f32_16x16x32_bf16 v[50:53], v[142:145], v[158:161], v[50:53]
	v_mfma_f32_16x16x32_bf16 v[38:41], v[126:129], v[166:169], v[38:41]
	v_mfma_f32_16x16x32_bf16 v[34:37], v[142:145], v[166:169], v[34:37]
	v_mfma_f32_16x16x32_bf16 v[22:25], v[126:129], v[182:185], v[22:25]
	v_mfma_f32_16x16x32_bf16 v[16:19], v[142:145], v[182:185], v[16:19]
	v_mfma_f32_16x16x32_bf16 v[4:7], v[126:129], v[190:193], v[4:7]
	v_mfma_f32_16x16x32_bf16 v[0:3], v[142:145], v[190:193], v[0:3]
	s_setprio 0
	s_barrier
; #define PG8_STAGE(bufoff, gbase, voff) do { _Pragma("unroll") for (int _i = 0; _i < 2; ++_i) \
;         __builtin_amdgcn_global_load_lds((const unsigned*)((const char*)(gbase) + (voff)[_i]), (PG8_LAS unsigned*)(lds + (bufoff) + ldsw + _i * 8192), 16, 0, 0); } while (0)
; #define PG8_LDA(dst, b, h) do { _Pragma("unroll") for (int m = 0; m < 4; ++m) _Pragma("unroll") for (int k = 0; k < 2; ++k) dst[m][k] = *(const PG8_LAS bf16x8*)(lds + PG8_SA(b, h) + aoff + m * 2048 + k * 1024); } while (0)
; #define PG8_LDB(dst, b, h) do { _Pragma("unroll") for (int n = 0; n < 2; ++n) _Pragma("unroll") for (int k = 0; k < 2; ++k) dst[n][k] = *(const PG8_LAS bf16x8*)(lds + PG8_SB(b, h) + boff + n * 2048 + k * 1024); } while (0)
; #define PG8_MMA(ai, bj, At, Bt) do { __builtin_amdgcn_s_setprio(1); _Pragma("unroll") for (int m = 0; m < 4; ++m) _Pragma("unroll") for (int n = 0; n < 2; ++n) _Pragma("unroll") for (int k = 0; k < 2; ++k) \
;         acc[ai][bj][m][n] = __builtin_amdgcn_mfma_f32_16x16x32_bf16(Bt[n][k], At[m][k], acc[ai][bj][m][n], 0, 0, 0); __builtin_amdgcn_s_setprio(0); } while (0)
; #define PG8_WAIT_V(n) asm volatile("s_waitcnt vmcnt(" #n ")" ::: "memory")
; #define PG8_WAIT_L(n) asm volatile("s_waitcnt lgkmcnt(" #n ")" ::: "memory")
; #define PG8_BAR __builtin_amdgcn_s_barrier()
; #define PG8_SCHED __builtin_amdgcn_sched_barrier(0)
; template <class Epi, class Sched, bool ALIGN_EPI = false, bool SP2 = false>
; __device__ __forceinline__ void gemm_phase(PG8_LAS unsigned char* lds, const Gemm g, const Sched& S, const Epi& E, const int tid_in) {
;     ...
;             PG8_LDB(B0, 1, 0); PG8_LDB(B1, 1, 1); PG8_SCHED; PG8_LDA(At, 1, 0); PG8_STAGE(PG8_SA(0, 1), a2 + hstep, voffA);
;             PG8_WAIT_V(8); PG8_WAIT_L(0); PG8_BAR; PG8_MMA(0, 0, At, B0); PG8_MMA(0, 1, At, B1); PG8_BAR; PG8_SCHED;
;             PG8_LDA(At, 1, 1); PG8_STAGE(PG8_SB(1, 0), b3, voffB); PG8_STAGE(PG8_SB(1, 1), b3 + hstep, voffB); PG8_STAGE(PG8_SA(1, 0), a3, voffA);
;             PG8_WAIT_V(8); PG8_WAIT_L(0); PG8_BAR; PG8_MMA(1, 0, At, B0); PG8_MMA(1, 1, At, B1); PG8_BAR; PG8_SCHED;
	s_add_i32 s57, 0, 0x18000
	s_add_i32 s58, 0, 0x1c000
	v_add_u32_e32 v102, s57, v208
	v_add_u32_e32 v142, s58, v208
	ds_read_b128 v[78:81], v102
	ds_read_b128 v[86:89], v102 offset:1024
	ds_read_b128 v[94:97], v102 offset:2048
	ds_read_b128 v[102:105], v102 offset:3072
	ds_read_b128 v[118:121], v142
	ds_read_b128 v[126:129], v142 offset:1024
	ds_read_b128 v[134:137], v142 offset:2048
	ds_read_b128 v[142:145], v142 offset:3072
	s_add_u32 s28, s38, 0x160000
	s_addc_u32 s29, s39, 0
	s_mov_b32 m0, s41
	s_nop 0
	global_load_lds_dwordx4 v216, s[38:39]
	s_mov_b32 m0, s42
	ds_read_b128 v[154:157], v244 offset:32768
	ds_read_b128 v[158:161], v244 offset:33792
	ds_read_b128 v[162:165], v244 offset:34816
	ds_read_b128 v[166:169], v244 offset:35840
	ds_read_b128 v[170:173], v244 offset:36864
	ds_read_b128 v[182:185], v244 offset:37888
	ds_read_b128 v[186:189], v244 offset:38912
	ds_read_b128 v[190:193], v244 offset:39936
	global_load_lds_dwordx4 v220, s[28:29]
	s_mov_b32 m0, s43
	s_nop 0
	global_load_lds_dwordx4 v216, s[28:29]
	s_waitcnt vmcnt(8)
	s_waitcnt lgkmcnt(0)
	s_barrier
	s_setprio 1
	v_mfma_f32_16x16x32_bf16 v[178:181], v[78:81], v[154:157], v[178:181]
	v_mfma_f32_16x16x32_bf16 v[174:177], v[94:97], v[154:157], v[174:177]
	v_mfma_f32_16x16x32_bf16 v[138:141], v[78:81], v[162:165], v[138:141]
	v_mfma_f32_16x16x32_bf16 v[130:133], v[94:97], v[162:165], v[130:133]
	v_mfma_f32_16x16x32_bf16 v[110:113], v[78:81], v[170:173], v[110:113]
	v_mfma_f32_16x16x32_bf16 v[106:109], v[94:97], v[170:173], v[106:109]
	v_mfma_f32_16x16x32_bf16 v[82:85], v[78:81], v[186:189], v[82:85]
	v_mfma_f32_16x16x32_bf16 v[74:77], v[94:97], v[186:189], v[74:77]
	v_mfma_f32_16x16x32_bf16 v[178:181], v[86:89], v[158:161], v[178:181]
	v_mfma_f32_16x16x32_bf16 v[174:177], v[102:105], v[158:161], v[174:177]
	v_mfma_f32_16x16x32_bf16 v[138:141], v[86:89], v[166:169], v[138:141]
	v_mfma_f32_16x16x32_bf16 v[130:133], v[102:105], v[166:169], v[130:133]
	v_mfma_f32_16x16x32_bf16 v[110:113], v[86:89], v[182:185], v[110:113]
	v_mfma_f32_16x16x32_bf16 v[106:109], v[102:105], v[182:185], v[106:109]
	v_mfma_f32_16x16x32_bf16 v[82:85], v[86:89], v[190:193], v[82:85]
	v_mfma_f32_16x16x32_bf16 v[74:77], v[102:105], v[190:193], v[74:77]
	s_setprio 0
	s_setprio 1
	v_mfma_f32_16x16x32_bf16 v[150:153], v[118:121], v[154:157], v[150:153]
	v_mfma_f32_16x16x32_bf16 v[146:149], v[134:137], v[154:157], v[146:149]
	v_mfma_f32_16x16x32_bf16 v[122:125], v[118:121], v[162:165], v[122:125]
	v_mfma_f32_16x16x32_bf16 v[114:117], v[134:137], v[162:165], v[114:117]
	v_mfma_f32_16x16x32_bf16 v[98:101], v[118:121], v[170:173], v[98:101]
	v_mfma_f32_16x16x32_bf16 v[90:93], v[134:137], v[170:173], v[90:93]
	v_mfma_f32_16x16x32_bf16 v[70:73], v[118:121], v[186:189], v[70:73]
	v_mfma_f32_16x16x32_bf16 v[66:69], v[134:137], v[186:189], v[66:69]
	v_mfma_f32_16x16x32_bf16 v[150:153], v[126:129], v[158:161], v[150:153]
	v_mfma_f32_16x16x32_bf16 v[146:149], v[142:145], v[158:161], v[146:149]
	v_mfma_f32_16x16x32_bf16 v[122:125], v[126:129], v[166:169], v[122:125]
	v_mfma_f32_16x16x32_bf16 v[114:117], v[142:145], v[166:169], v[114:117]
	v_mfma_f32_16x16x32_bf16 v[98:101], v[126:129], v[182:185], v[98:101]
	v_mfma_f32_16x16x32_bf16 v[90:93], v[142:145], v[182:185], v[90:93]
	v_mfma_f32_16x16x32_bf16 v[70:73], v[126:129], v[190:193], v[70:73]
	v_mfma_f32_16x16x32_bf16 v[66:69], v[142:145], v[190:193], v[66:69]
	s_setprio 0
	s_barrier
	s_add_i32 s28, s57, s19
	s_mov_b32 m0, s28
	ds_read_b128 v[154:157], v244 offset:49152
	ds_read_b128 v[158:161], v244 offset:50176
	ds_read_b128 v[162:165], v244 offset:51200
	ds_read_b128 v[166:169], v244 offset:52224
	ds_read_b128 v[170:173], v244 offset:53248
	ds_read_b128 v[182:185], v244 offset:54272
	ds_read_b128 v[186:189], v244 offset:55296
	ds_read_b128 v[190:193], v244 offset:56320
	global_load_lds_dwordx4 v218, s[98:99]
	s_add_i32 m0, s28, 0x2000
	s_add_u32 s28, s34, 0x160080
	s_addc_u32 s29, s35, 0
	s_add_i32 s34, s58, s19
	global_load_lds_dwordx4 v214, s[98:99]
	s_mov_b32 m0, s34
	s_nop 0
	global_load_lds_dwordx4 v218, s[28:29]
	s_add_i32 m0, s34, 0x2000
	s_nop 0
	global_load_lds_dwordx4 v214, s[28:29]
	s_mov_b32 m0, s46
	s_nop 0
	global_load_lds_dwordx4 v220, s[100:101]
	s_waitcnt vmcnt(7)
	s_waitcnt lgkmcnt(0)
	s_barrier
	s_setprio 1
	v_mfma_f32_16x16x32_bf16 v[62:65], v[78:81], v[154:157], v[62:65]
	v_mfma_f32_16x16x32_bf16 v[58:61], v[94:97], v[154:157], v[58:61]
	v_mfma_f32_16x16x32_bf16 v[46:49], v[78:81], v[162:165], v[46:49]
	v_mfma_f32_16x16x32_bf16 v[42:45], v[94:97], v[162:165], v[42:45]
	v_mfma_f32_16x16x32_bf16 v[30:33], v[78:81], v[170:173], v[30:33]
	v_mfma_f32_16x16x32_bf16 v[26:29], v[94:97], v[170:173], v[26:29]
	v_mfma_f32_16x16x32_bf16 v[12:15], v[78:81], v[186:189], v[12:15]
	v_mfma_f32_16x16x32_bf16 v[8:11], v[94:97], v[186:189], v[8:11]
	v_mfma_f32_16x16x32_bf16 v[62:65], v[86:89], v[158:161], v[62:65]
	v_mfma_f32_16x16x32_bf16 v[58:61], v[102:105], v[158:161], v[58:61]
	v_mfma_f32_16x16x32_bf16 v[46:49], v[86:89], v[166:169], v[46:49]
	v_mfma_f32_16x16x32_bf16 v[42:45], v[102:105], v[166:169], v[42:45]
	v_mfma_f32_16x16x32_bf16 v[30:33], v[86:89], v[182:185], v[30:33]
	v_mfma_f32_16x16x32_bf16 v[26:29], v[102:105], v[182:185], v[26:29]
	v_mfma_f32_16x16x32_bf16 v[12:15], v[86:89], v[190:193], v[12:15]
	v_mfma_f32_16x16x32_bf16 v[8:11], v[102:105], v[190:193], v[8:11]
	s_setprio 0
	s_setprio 1
	v_mfma_f32_16x16x32_bf16 v[54:57], v[118:121], v[154:157], v[54:57]
	v_mfma_f32_16x16x32_bf16 v[50:53], v[134:137], v[154:157], v[50:53]
	v_mfma_f32_16x16x32_bf16 v[38:41], v[118:121], v[162:165], v[38:41]
	v_mfma_f32_16x16x32_bf16 v[34:37], v[134:137], v[162:165], v[34:37]
	v_mfma_f32_16x16x32_bf16 v[22:25], v[118:121], v[170:173], v[22:25]
	v_mfma_f32_16x16x32_bf16 v[16:19], v[134:137], v[170:173], v[16:19]
	v_mfma_f32_16x16x32_bf16 v[4:7], v[118:121], v[186:189], v[4:7]
	v_mfma_f32_16x16x32_bf16 v[0:3], v[134:137], v[186:189], v[0:3]
	v_mfma_f32_16x16x32_bf16 v[54:57], v[126:129], v[158:161], v[54:57]
	v_mfma_f32_16x16x32_bf16 v[50:53], v[142:145], v[158:161], v[50:53]
	v_mfma_f32_16x16x32_bf16 v[38:41], v[126:129], v[166:169], v[38:41]
	v_mfma_f32_16x16x32_bf16 v[34:37], v[142:145], v[166:169], v[34:37]
	v_mfma_f32_16x16x32_bf16 v[22:25], v[126:129], v[182:185], v[22:25]
	v_mfma_f32_16x16x32_bf16 v[16:19], v[142:145], v[182:185], v[16:19]
	v_mfma_f32_16x16x32_bf16 v[4:7], v[126:129], v[190:193], v[4:7]
	v_mfma_f32_16x16x32_bf16 v[0:3], v[142:145], v[190:193], v[0:3]
	s_setprio 0
	s_barrier
	s_add_i32 s56, s56, 2
	s_add_u32 s54, s54, 0x100
	s_addc_u32 s55, s55, 0
	s_cmpk_gt_u32 s56, 0x55
	s_mov_b64 s[28:29], s[30:31]
